# speedup vs baseline: 1.0097x; 1.0049x over previous
.LBB0_71:
	s_add_u32 s43, s26, 0x3c00000
	v_readlane_b32 s14, v255, 20
	s_addc_u32 s46, s27, 0
	s_add_i32 s9, s14, -2
	v_readlane_b32 s15, v255, 21
	s_and_b64 s[6:7], s[6:7], exec
	s_cselect_b32 s6, s9, s14
	s_cselect_b32 s7, 0, s15
	s_mov_b32 s9, 0x1600000
	s_mul_i32 s7, s7, 0x580000
	s_mul_hi_u32 s11, s6, 0x580000
	s_cselect_b32 s9, s9, 0x2e00000
	s_add_i32 s11, s11, s7
	s_mul_i32 s6, s6, 0x580000
	s_add_u32 s6, s26, s6
	s_addc_u32 s7, s27, s11
	s_add_u32 s47, s6, s9
	s_addc_u32 s68, s7, 0
	s_add_i32 s6, s10, s8
	s_ashr_i32 s7, s6, 31
	s_lshr_b32 s7, s7, 27
	s_add_i32 s7, s6, s7
	s_and_b32 s8, s7, 0xffe0
	s_sub_i32 s6, s6, s8
	s_bfe_i32 s8, s6, 0x80000
	s_bfe_u32 s8, s8, 0x3000c
	s_add_i32 s8, s6, s8
	s_bfe_i32 s9, s8, 0x80000
	s_and_b32 s8, s8, 0xf8
	s_sub_i32 s6, s6, s8
	s_sext_i32_i8 s6, s6
	s_lshl_b32 s7, s7, 6
	s_sext_i32_i16 s9, s9
	s_and_b32 s7, s7, 0xfffff800
	s_lshl_b32 s6, s6, 8
	v_ashrrev_i32_e32 v1, 6, v0
	v_lshrrev_b32_e32 v4, 31, v0
	s_add_i32 s18, s6, s7
	s_ashr_i32 s6, s9, 3
	v_lshlrev_b32_e32 v2, 4, v0
	v_and_b32_e32 v3, 32, v0
	v_add_u32_e32 v4, v1, v4
	s_lshl_b32 s19, s6, 8
	s_mul_i32 s6, s6, 0xb0000
	v_lshlrev_b32_e32 v134, 10, v1
	v_ashrrev_i32_e32 v8, 1, v4
	v_bfe_u32 v9, v0, 2, 4
	v_and_b32_e32 v4, 0x3fffffe, v4
	v_bitop3_b32 v2, v2, v3, 48 bitop3:0x6c
	s_ashr_i32 s7, s6, 31
	v_lshl_or_b32 v5, v8, 4, v9
	v_sub_u32_e32 v4, v1, v4
	v_lshrrev_b32_e32 v10, 1, v2
	s_movk_i32 s37, 0xb00
	s_lshl_b64 s[6:7], s[6:7], 1
	v_add_u32_e32 v135, 0x10000, v134
	v_lshl_or_b32 v2, v4, 5, v10
	v_mul_lo_u32 v3, v5, s37
	s_add_u32 s14, s47, s6
	v_readfirstlane_b32 s6, v135
	v_add_u32_e32 v136, 0x12000, v134
	v_add_lshl_u32 v128, v2, v3, 1
	s_addc_u32 s15, s68, s7
	s_mov_b32 m0, s6
	v_readfirstlane_b32 s6, v136
	s_mul_i32 s7, s18, 0x1600
	v_lshl_add_u64 v[2:3], s[14:15], 0, v[128:129]
	global_load_lds_dwordx4 v128, s[14:15]
	s_mov_b64 s[8:9], 0x58000
	s_mov_b32 m0, s6
	s_mul_hi_i32 s6, s18, 0x1600
	s_add_u32 s22, s43, s7
	v_lshl_add_u64 v[4:5], v[2:3], 0, s[8:9]
	s_addc_u32 s23, s46, s6
	v_readfirstlane_b32 s6, v134
	v_add_u32_e32 v137, 0x2000, v134
	global_load_lds_dwordx4 v[4:5], off
	v_lshl_add_u64 v[4:5], s[22:23], 0, v[128:129]
	s_mov_b32 m0, s6
	v_readfirstlane_b32 s6, v137
	v_add_u32_e32 v138, 0x14000, v134
	global_load_lds_dwordx4 v128, s[22:23]
	v_lshl_add_u64 v[6:7], v[4:5], 0, s[8:9]
	s_mov_b32 m0, s6
	s_mov_b64 s[8:9], 0xb0000
	v_readfirstlane_b32 s6, v138
	v_add_u32_e32 v139, 0x16000, v134
	global_load_lds_dwordx4 v[6:7], off
	v_lshl_add_u64 v[6:7], v[2:3], 0, s[8:9]
	s_mov_b32 m0, s6
	s_mov_b64 s[10:11], 0x108000
	v_readfirstlane_b32 s6, v139
	v_add_u32_e32 v140, 0x4000, v134
	global_load_lds_dwordx4 v[6:7], off
	v_lshl_add_u64 v[6:7], v[2:3], 0, s[10:11]
	s_mov_b32 m0, s6
	v_readfirstlane_b32 s6, v140
	v_add_u32_e32 v141, 0x6000, v134
	global_load_lds_dwordx4 v[6:7], off
	v_lshl_add_u64 v[6:7], v[4:5], 0, s[8:9]
	s_mov_b32 m0, s6
	v_readfirstlane_b32 s6, v141
	v_add_u32_e32 v142, 0x18000, v134
	global_load_lds_dwordx4 v[6:7], off
	v_lshl_add_u64 v[6:7], v[4:5], 0, s[10:11]
	s_mov_b32 m0, s6
	v_readfirstlane_b32 s6, v142
	v_add_u32_e32 v143, 0x1a000, v134
	global_load_lds_dwordx4 v[6:7], off
	v_lshl_add_u64 v[6:7], v[2:3], 0, s[44:45]
	s_mov_b32 m0, s6
	s_mov_b64 s[8:9], 0x58080
	v_readfirstlane_b32 s6, v143
	v_add_u32_e32 v144, 0x8000, v134
	global_load_lds_dwordx4 v[6:7], off
	v_lshl_add_u64 v[6:7], v[2:3], 0, s[8:9]
	s_mov_b32 m0, s6
	v_readfirstlane_b32 s6, v144
	v_add_u32_e32 v145, 0xa000, v134
	global_load_lds_dwordx4 v[6:7], off
	v_lshl_add_u64 v[6:7], v[4:5], 0, s[44:45]
	s_mov_b32 m0, s6
	v_readfirstlane_b32 s6, v145
	global_load_lds_dwordx4 v[6:7], off
	v_lshl_add_u64 v[4:5], v[4:5], 0, s[8:9]
	s_mov_b32 m0, s6
	s_mov_b64 s[6:7], 0xb0080
	v_add_u32_e32 v146, 0x1c000, v134
	global_load_lds_dwordx4 v[4:5], off
	v_lshl_add_u64 v[4:5], v[2:3], 0, s[6:7]
	v_readfirstlane_b32 s6, v146
	s_mov_b32 m0, s6
	s_mov_b64 s[6:7], 0x108080
	v_add_u32_e32 v147, 0x1e000, v134
	v_lshl_add_u64 v[2:3], v[2:3], 0, s[6:7]
	v_readfirstlane_b32 s6, v147
	global_load_lds_dwordx4 v[4:5], off
	s_mov_b32 m0, s6
	v_and_b32_e32 v4, 15, v0
	global_load_lds_dwordx4 v[2:3], off
	v_and_b32_e32 v7, 48, v0
	v_lshlrev_b32_e32 v4, 6, v4
	v_lshlrev_b32_e32 v12, 2, v0
	v_or_b32_e32 v11, v4, v7
	v_and_b32_e32 v12, 32, v12
	s_mov_b32 s8, 0x10000
	v_bitop3_b32 v13, v11, s8, v12 bitop3:0xde
	s_mov_b32 s8, 0x14000
	v_bitop3_b32 v15, v11, s8, v12 bitop3:0xde
	s_mov_b32 s8, 0x18000
	v_ashrrev_i32_e32 v2, 8, v0
	v_lshrrev_b32_e32 v5, 2, v0
	v_bitop3_b32 v16, v11, s8, v12 bitop3:0xde
	s_mov_b32 s8, 0x1c000
	v_lshlrev_b32_e32 v14, 6, v2
	v_bitop3_b32 v11, v11, s8, v12 bitop3:0xde
	s_movk_i32 s8, 0x100
	v_and_b32_e32 v17, 1, v0
	v_and_b32_e32 v5, 12, v5
	s_mov_b32 s36, 0xafc0
	v_cmp_gt_u32_e64 s[8:9], s8, v0
	v_or3_b32 v148, v14, v5, v17
	v_and_b32_e32 v5, 14, v0
	v_lshlrev_b32_e32 v0, 6, v0
	v_mul_lo_u32 v8, v8, s36
	v_and_b32_e32 v3, 3, v1
	v_cmp_eq_u32_e64 s[6:7], 1, v2
	v_lshlrev_b32_e32 v2, 13, v2
	v_and_b32_e32 v0, 0x3c0, v0
	v_or_b32_e32 v8, v10, v8
	v_lshlrev_b32_e32 v6, 12, v3
	v_bitop3_b32 v4, v4, v12, v7 bitop3:0x36
	v_lshl_or_b32 v149, v3, 5, v5
	v_bitop3_b32 v0, v0, v12, v7 bitop3:0x36
	v_or_b32_e32 v3, 0x800, v2
	v_or_b32_e32 v5, 0x1000, v2
	v_or_b32_e32 v7, 0x1800, v2
	v_mad_u32_u24 v8, v9, s37, v8
	v_lshlrev_b32_e32 v1, 5, v1
	v_cmp_eq_u32_e64 s[10:11], 0, v17
	v_add_lshl_u32 v132, v8, v1, 1
	v_mov_b32_e32 v133, v129
	v_add_u32_e32 v150, v13, v6
	v_add_u32_e32 v151, v4, v2
	v_add_u32_e32 v152, v0, v3
	v_add_u32_e32 v153, v0, v5
	v_add_u32_e32 v154, v0, v7
	v_add_u32_e32 v155, v15, v6
	v_add_u32_e32 v156, v16, v6
	v_add_u32_e32 v157, v11, v6
	s_waitcnt vmcnt(0)
	v_mov_b32_e32 v250, 0x3020706
	v_mov_b32_e32 v251, 0x5040100
	v_cndmask_b32_e64 v250, v250, v251, s[10:11]
	s_branch .LBB0_74

.LBB0_73:
	v_or_b32_e32 v158, s19, v149
	v_add_lshl_u32 v159, v148, s18, 11
	v_lshl_add_u32 v158, v158, 1, v159
	v_cvt_pk_bf16_f32 v159, v124, v125
	s_nop 1
	v_mov_b32_dpp v160, v159 quad_perm:[1,0,3,2] row_mask:0xf bank_mask:0xf
	v_perm_b32 v124, v160, v159, v250
	global_store_dword v158, v124, s[12:13]
	v_cvt_pk_bf16_f32 v124, v126, v127
	s_nop 1
	v_mov_b32_dpp v125, v124 quad_perm:[1,0,3,2] row_mask:0xf bank_mask:0xf
	v_perm_b32 v124, v125, v124, v250
	v_add_u32_e32 v125, 0x1000, v158
	global_store_dword v125, v124, s[12:13]
	v_cndmask_b32_e64 v125, v116, v117, s[10:11]
	v_mov_b32_e32 v126, v129
	v_or_b32_e32 v124, 32, v158
	s_nop 0
	v_mov_b32_dpp v126, v125 quad_perm:[1,0,3,2] row_mask:0xf bank_mask:0xf
	v_cndmask_b32_e64 v116, v126, v116, s[10:11]
	v_cndmask_b32_e64 v117, v117, v126, s[10:11]
	v_cvt_pk_bf16_f32 v116, v116, v117
	global_store_dword v124, v116, s[12:13]
	v_cvt_pk_bf16_f32 v116, v118, v119
	s_nop 1
	v_mov_b32_dpp v117, v116 quad_perm:[1,0,3,2] row_mask:0xf bank_mask:0xf
	v_perm_b32 v116, v117, v116, v250
	v_add_u32_e32 v117, 0x1020, v158
	global_store_dword v117, v116, s[12:13]
	v_cndmask_b32_e64 v117, v120, v121, s[10:11]
	v_mov_b32_e32 v118, v129
	v_or_b32_e32 v116, 0x100, v158
	s_nop 0
	v_mov_b32_dpp v118, v117 quad_perm:[1,0,3,2] row_mask:0xf bank_mask:0xf
	v_cndmask_b32_e64 v117, v118, v120, s[10:11]
	v_cndmask_b32_e64 v118, v121, v118, s[10:11]
	v_cvt_pk_bf16_f32 v117, v117, v118
	global_store_dword v116, v117, s[12:13]
	v_cndmask_b32_e64 v116, v122, v123, s[10:11]
	v_mov_b32_e32 v117, v129
	v_mov_b32_e32 v118, v129
	s_nop 0
	v_mov_b32_dpp v117, v116 quad_perm:[1,0,3,2] row_mask:0xf bank_mask:0xf
	v_cndmask_b32_e64 v116, v117, v122, s[10:11]
	v_cndmask_b32_e64 v117, v123, v117, s[10:11]
	v_cvt_pk_bf16_f32 v116, v116, v117
	v_add_u32_e32 v117, 0x1100, v158
	global_store_dword v117, v116, s[12:13]
	v_cndmask_b32_e64 v117, v112, v113, s[10:11]
	v_or_b32_e32 v116, 0x120, v158
	s_nop 0
	v_mov_b32_dpp v118, v117 quad_perm:[1,0,3,2] row_mask:0xf bank_mask:0xf
	v_cndmask_b32_e64 v112, v118, v112, s[10:11]
	v_cndmask_b32_e64 v113, v113, v118, s[10:11]
	v_cvt_pk_bf16_f32 v112, v112, v113
	global_store_dword v116, v112, s[12:13]
	v_cvt_pk_bf16_f32 v112, v114, v115
	s_nop 1
	v_mov_b32_dpp v113, v112 quad_perm:[1,0,3,2] row_mask:0xf bank_mask:0xf
	v_perm_b32 v112, v113, v112, v250
	v_add_u32_e32 v113, 0x1120, v158
	global_store_dword v113, v112, s[12:13]
	v_cvt_pk_bf16_f32 v112, v108, v109
	s_nop 1
	v_mov_b32_dpp v113, v112 quad_perm:[1,0,3,2] row_mask:0xf bank_mask:0xf
	v_perm_b32 v108, v113, v112, v250
	v_add_u32_e32 v109, 0x8000, v158
	global_store_dword v109, v108, s[12:13]
	v_cvt_pk_bf16_f32 v108, v110, v111
	s_nop 1
	v_mov_b32_dpp v109, v108 quad_perm:[1,0,3,2] row_mask:0xf bank_mask:0xf
	v_perm_b32 v108, v109, v108, v250
	v_add_u32_e32 v109, 0x9000, v158
	global_store_dword v109, v108, s[12:13]
	v_cvt_pk_bf16_f32 v108, v100, v101
	s_nop 1
	v_mov_b32_dpp v109, v108 quad_perm:[1,0,3,2] row_mask:0xf bank_mask:0xf
	v_perm_b32 v100, v109, v108, v250
	v_add_u32_e32 v101, 0x8020, v158
	global_store_dword v101, v100, s[12:13]
	v_cvt_pk_bf16_f32 v100, v102, v103
	s_nop 1
	v_mov_b32_dpp v101, v100 quad_perm:[1,0,3,2] row_mask:0xf bank_mask:0xf
	v_perm_b32 v100, v101, v100, v250
	v_add_u32_e32 v101, 0x9020, v158
	global_store_dword v101, v100, s[12:13]
	v_cvt_pk_bf16_f32 v100, v104, v105
	s_nop 1
	v_mov_b32_dpp v101, v100 quad_perm:[1,0,3,2] row_mask:0xf bank_mask:0xf
	v_perm_b32 v100, v101, v100, v250
	v_add_u32_e32 v101, 0x8100, v158
	global_store_dword v101, v100, s[12:13]
	v_cvt_pk_bf16_f32 v100, v106, v107
	s_nop 1
	v_mov_b32_dpp v101, v100 quad_perm:[1,0,3,2] row_mask:0xf bank_mask:0xf
	v_perm_b32 v100, v101, v100, v250
	v_add_u32_e32 v101, 0x9100, v158
	global_store_dword v101, v100, s[12:13]
	v_cvt_pk_bf16_f32 v100, v96, v97
	s_nop 1
	v_mov_b32_dpp v101, v100 quad_perm:[1,0,3,2] row_mask:0xf bank_mask:0xf
	v_perm_b32 v96, v101, v100, v250
	v_add_u32_e32 v97, 0x8120, v158
	global_store_dword v97, v96, s[12:13]
	v_cvt_pk_bf16_f32 v96, v98, v99
	s_nop 1
	v_mov_b32_dpp v97, v96 quad_perm:[1,0,3,2] row_mask:0xf bank_mask:0xf
	v_perm_b32 v96, v97, v96, v250
	v_add_u32_e32 v97, 0x9120, v158
	global_store_dword v97, v96, s[12:13]
	v_cvt_pk_bf16_f32 v96, v92, v93
	s_nop 1
	v_mov_b32_dpp v97, v96 quad_perm:[1,0,3,2] row_mask:0xf bank_mask:0xf
	v_perm_b32 v92, v97, v96, v250
	v_add_u32_e32 v93, 0x10000, v158
	global_store_dword v93, v92, s[12:13]
	v_cvt_pk_bf16_f32 v92, v94, v95
	s_nop 1
	v_mov_b32_dpp v93, v92 quad_perm:[1,0,3,2] row_mask:0xf bank_mask:0xf
	v_perm_b32 v92, v93, v92, v250
	v_add_u32_e32 v93, 0x11000, v158
	global_store_dword v93, v92, s[12:13]
	v_cvt_pk_bf16_f32 v92, v84, v85
	s_nop 1
	v_mov_b32_dpp v93, v92 quad_perm:[1,0,3,2] row_mask:0xf bank_mask:0xf
	v_perm_b32 v84, v93, v92, v250
	v_add_u32_e32 v85, 0x10020, v158
	global_store_dword v85, v84, s[12:13]
	v_cvt_pk_bf16_f32 v84, v86, v87
	s_nop 1
	v_mov_b32_dpp v85, v84 quad_perm:[1,0,3,2] row_mask:0xf bank_mask:0xf
	v_perm_b32 v84, v85, v84, v250
	v_add_u32_e32 v85, 0x11020, v158
	global_store_dword v85, v84, s[12:13]
	v_cvt_pk_bf16_f32 v84, v88, v89
	s_nop 1
	v_mov_b32_dpp v85, v84 quad_perm:[1,0,3,2] row_mask:0xf bank_mask:0xf
	v_perm_b32 v84, v85, v84, v250
	v_add_u32_e32 v85, 0x10100, v158
	global_store_dword v85, v84, s[12:13]
	v_cvt_pk_bf16_f32 v84, v90, v91
	s_nop 1
	v_mov_b32_dpp v85, v84 quad_perm:[1,0,3,2] row_mask:0xf bank_mask:0xf
	v_perm_b32 v84, v85, v84, v250
	v_add_u32_e32 v85, 0x11100, v158
	global_store_dword v85, v84, s[12:13]
	v_cvt_pk_bf16_f32 v84, v80, v81
	s_nop 1
	v_mov_b32_dpp v85, v84 quad_perm:[1,0,3,2] row_mask:0xf bank_mask:0xf
	v_perm_b32 v80, v85, v84, v250
	v_add_u32_e32 v81, 0x10120, v158
	global_store_dword v81, v80, s[12:13]
	v_cvt_pk_bf16_f32 v80, v82, v83
	s_nop 1
	v_mov_b32_dpp v81, v80 quad_perm:[1,0,3,2] row_mask:0xf bank_mask:0xf
	v_perm_b32 v80, v81, v80, v250
	v_add_u32_e32 v81, 0x11120, v158
	global_store_dword v81, v80, s[12:13]
	v_cvt_pk_bf16_f32 v80, v76, v77
	s_nop 1
	v_mov_b32_dpp v81, v80 quad_perm:[1,0,3,2] row_mask:0xf bank_mask:0xf
	v_perm_b32 v76, v81, v80, v250
	v_add_u32_e32 v77, 0x18000, v158
	global_store_dword v77, v76, s[12:13]
	v_cvt_pk_bf16_f32 v76, v78, v79
	s_nop 1
	v_mov_b32_dpp v77, v76 quad_perm:[1,0,3,2] row_mask:0xf bank_mask:0xf
	v_perm_b32 v76, v77, v76, v250
	v_add_u32_e32 v77, 0x19000, v158
	global_store_dword v77, v76, s[12:13]
	v_cvt_pk_bf16_f32 v76, v68, v69
	s_nop 1
	v_mov_b32_dpp v77, v76 quad_perm:[1,0,3,2] row_mask:0xf bank_mask:0xf
	v_perm_b32 v68, v77, v76, v250
	v_add_u32_e32 v69, 0x18020, v158
	global_store_dword v69, v68, s[12:13]
	v_cvt_pk_bf16_f32 v68, v70, v71
	s_nop 1
	v_mov_b32_dpp v69, v68 quad_perm:[1,0,3,2] row_mask:0xf bank_mask:0xf
	v_perm_b32 v68, v69, v68, v250
	v_add_u32_e32 v69, 0x19020, v158
	global_store_dword v69, v68, s[12:13]
	v_cvt_pk_bf16_f32 v68, v72, v73
	s_nop 1
	v_mov_b32_dpp v69, v68 quad_perm:[1,0,3,2] row_mask:0xf bank_mask:0xf
	v_perm_b32 v68, v69, v68, v250
	v_add_u32_e32 v69, 0x18100, v158
	global_store_dword v69, v68, s[12:13]
	v_cvt_pk_bf16_f32 v68, v74, v75
	s_nop 1
	v_mov_b32_dpp v69, v68 quad_perm:[1,0,3,2] row_mask:0xf bank_mask:0xf
	v_perm_b32 v68, v69, v68, v250
	v_add_u32_e32 v69, 0x19100, v158
	global_store_dword v69, v68, s[12:13]
	v_cvt_pk_bf16_f32 v68, v64, v65
	s_nop 1
	v_mov_b32_dpp v69, v68 quad_perm:[1,0,3,2] row_mask:0xf bank_mask:0xf
	v_perm_b32 v64, v69, v68, v250
	v_add_u32_e32 v65, 0x18120, v158
	global_store_dword v65, v64, s[12:13]
	v_cvt_pk_bf16_f32 v64, v66, v67
	s_nop 1
	v_mov_b32_dpp v65, v64 quad_perm:[1,0,3,2] row_mask:0xf bank_mask:0xf
	v_perm_b32 v64, v65, v64, v250
	v_add_u32_e32 v65, 0x19120, v158
	global_store_dword v65, v64, s[12:13]
	v_cvt_pk_bf16_f32 v64, v60, v61
	s_nop 1
	v_mov_b32_dpp v65, v64 quad_perm:[1,0,3,2] row_mask:0xf bank_mask:0xf
	v_perm_b32 v60, v65, v64, v250
	v_add_u32_e32 v61, 0x40000, v158
	global_store_dword v61, v60, s[12:13]
	v_cvt_pk_bf16_f32 v60, v62, v63
	s_nop 1
	v_mov_b32_dpp v61, v60 quad_perm:[1,0,3,2] row_mask:0xf bank_mask:0xf
	v_perm_b32 v60, v61, v60, v250
	v_add_u32_e32 v61, 0x41000, v158
	global_store_dword v61, v60, s[12:13]
	v_cvt_pk_bf16_f32 v60, v52, v53
	s_nop 1
	v_mov_b32_dpp v61, v60 quad_perm:[1,0,3,2] row_mask:0xf bank_mask:0xf
	v_perm_b32 v52, v61, v60, v250
	v_add_u32_e32 v53, 0x40020, v158
	global_store_dword v53, v52, s[12:13]
	v_cvt_pk_bf16_f32 v52, v54, v55
	s_nop 1
	v_mov_b32_dpp v53, v52 quad_perm:[1,0,3,2] row_mask:0xf bank_mask:0xf
	v_perm_b32 v52, v53, v52, v250
	v_add_u32_e32 v53, 0x41020, v158
	global_store_dword v53, v52, s[12:13]
	v_cvt_pk_bf16_f32 v52, v56, v57
	s_nop 1
	v_mov_b32_dpp v53, v52 quad_perm:[1,0,3,2] row_mask:0xf bank_mask:0xf
	v_perm_b32 v52, v53, v52, v250
	v_add_u32_e32 v53, 0x40100, v158
	global_store_dword v53, v52, s[12:13]
	v_cvt_pk_bf16_f32 v52, v58, v59
	s_nop 1
	v_mov_b32_dpp v53, v52 quad_perm:[1,0,3,2] row_mask:0xf bank_mask:0xf
	v_perm_b32 v52, v53, v52, v250
	v_add_u32_e32 v53, 0x41100, v158
	global_store_dword v53, v52, s[12:13]
	v_cvt_pk_bf16_f32 v52, v48, v49
	s_nop 1
	v_mov_b32_dpp v53, v52 quad_perm:[1,0,3,2] row_mask:0xf bank_mask:0xf
	v_perm_b32 v48, v53, v52, v250
	v_add_u32_e32 v49, 0x40120, v158
	global_store_dword v49, v48, s[12:13]
	v_cvt_pk_bf16_f32 v48, v50, v51
	s_nop 1
	v_mov_b32_dpp v49, v48 quad_perm:[1,0,3,2] row_mask:0xf bank_mask:0xf
	v_perm_b32 v48, v49, v48, v250
	v_add_u32_e32 v49, 0x41120, v158
	global_store_dword v49, v48, s[12:13]
	v_cvt_pk_bf16_f32 v48, v44, v45
	s_nop 1
	v_mov_b32_dpp v49, v48 quad_perm:[1,0,3,2] row_mask:0xf bank_mask:0xf
	v_perm_b32 v44, v49, v48, v250
	v_add_u32_e32 v45, 0x48000, v158
	global_store_dword v45, v44, s[12:13]
	v_cvt_pk_bf16_f32 v44, v46, v47
	s_nop 1
	v_mov_b32_dpp v45, v44 quad_perm:[1,0,3,2] row_mask:0xf bank_mask:0xf
	v_perm_b32 v44, v45, v44, v250
	v_add_u32_e32 v45, 0x49000, v158
	global_store_dword v45, v44, s[12:13]
	v_cvt_pk_bf16_f32 v44, v36, v37
	s_nop 1
	v_mov_b32_dpp v45, v44 quad_perm:[1,0,3,2] row_mask:0xf bank_mask:0xf
	v_perm_b32 v36, v45, v44, v250
	v_add_u32_e32 v37, 0x48020, v158
	global_store_dword v37, v36, s[12:13]
	v_cvt_pk_bf16_f32 v36, v38, v39
	s_nop 1
	v_mov_b32_dpp v37, v36 quad_perm:[1,0,3,2] row_mask:0xf bank_mask:0xf
	v_perm_b32 v36, v37, v36, v250
	v_add_u32_e32 v37, 0x49020, v158
	global_store_dword v37, v36, s[12:13]
	v_cvt_pk_bf16_f32 v36, v40, v41
	s_nop 1
	v_mov_b32_dpp v37, v36 quad_perm:[1,0,3,2] row_mask:0xf bank_mask:0xf
	v_perm_b32 v36, v37, v36, v250
	v_add_u32_e32 v37, 0x48100, v158
	global_store_dword v37, v36, s[12:13]
	v_cvt_pk_bf16_f32 v36, v42, v43
	s_nop 1
	v_mov_b32_dpp v37, v36 quad_perm:[1,0,3,2] row_mask:0xf bank_mask:0xf
	v_perm_b32 v36, v37, v36, v250
	v_add_u32_e32 v37, 0x49100, v158
	global_store_dword v37, v36, s[12:13]
	v_cvt_pk_bf16_f32 v36, v32, v33
	s_nop 1
	v_mov_b32_dpp v37, v36 quad_perm:[1,0,3,2] row_mask:0xf bank_mask:0xf
	v_perm_b32 v32, v37, v36, v250
	v_add_u32_e32 v33, 0x48120, v158
	global_store_dword v33, v32, s[12:13]
	v_cvt_pk_bf16_f32 v32, v34, v35
	s_nop 1
	v_mov_b32_dpp v33, v32 quad_perm:[1,0,3,2] row_mask:0xf bank_mask:0xf
	v_perm_b32 v32, v33, v32, v250
	v_add_u32_e32 v33, 0x49120, v158
	global_store_dword v33, v32, s[12:13]
	v_cvt_pk_bf16_f32 v32, v28, v29
	s_nop 1
	v_mov_b32_dpp v33, v32 quad_perm:[1,0,3,2] row_mask:0xf bank_mask:0xf
	v_perm_b32 v28, v33, v32, v250
	v_add_u32_e32 v29, 0x50000, v158
	global_store_dword v29, v28, s[12:13]
	v_cvt_pk_bf16_f32 v28, v30, v31
	s_nop 1
	v_mov_b32_dpp v29, v28 quad_perm:[1,0,3,2] row_mask:0xf bank_mask:0xf
	v_perm_b32 v28, v29, v28, v250
	v_add_u32_e32 v29, 0x51000, v158
	global_store_dword v29, v28, s[12:13]
	v_cvt_pk_bf16_f32 v28, v20, v21
	s_nop 1
	v_mov_b32_dpp v29, v28 quad_perm:[1,0,3,2] row_mask:0xf bank_mask:0xf
	v_perm_b32 v20, v29, v28, v250
	v_add_u32_e32 v21, 0x50020, v158
	global_store_dword v21, v20, s[12:13]
	v_cvt_pk_bf16_f32 v20, v22, v23
	s_nop 1
	v_mov_b32_dpp v21, v20 quad_perm:[1,0,3,2] row_mask:0xf bank_mask:0xf
	v_perm_b32 v20, v21, v20, v250
	v_add_u32_e32 v21, 0x51020, v158
	global_store_dword v21, v20, s[12:13]
	v_cvt_pk_bf16_f32 v20, v24, v25
	s_nop 1
	v_mov_b32_dpp v21, v20 quad_perm:[1,0,3,2] row_mask:0xf bank_mask:0xf
	v_perm_b32 v20, v21, v20, v250
	v_add_u32_e32 v21, 0x50100, v158
	global_store_dword v21, v20, s[12:13]
	v_cvt_pk_bf16_f32 v20, v26, v27
	s_nop 1
	v_mov_b32_dpp v21, v20 quad_perm:[1,0,3,2] row_mask:0xf bank_mask:0xf
	v_perm_b32 v20, v21, v20, v250
	v_add_u32_e32 v21, 0x51100, v158
	global_store_dword v21, v20, s[12:13]
	v_cvt_pk_bf16_f32 v20, v16, v17
	s_nop 1
	v_mov_b32_dpp v21, v20 quad_perm:[1,0,3,2] row_mask:0xf bank_mask:0xf
	v_perm_b32 v16, v21, v20, v250
	v_add_u32_e32 v17, 0x50120, v158
	global_store_dword v17, v16, s[12:13]
	v_cvt_pk_bf16_f32 v16, v18, v19
	s_nop 1
	v_mov_b32_dpp v17, v16 quad_perm:[1,0,3,2] row_mask:0xf bank_mask:0xf
	v_perm_b32 v16, v17, v16, v250
	v_add_u32_e32 v17, 0x51120, v158
	global_store_dword v17, v16, s[12:13]
	v_cvt_pk_bf16_f32 v16, v12, v13
	s_nop 1
	v_mov_b32_dpp v17, v16 quad_perm:[1,0,3,2] row_mask:0xf bank_mask:0xf
	v_perm_b32 v12, v17, v16, v250
	v_add_u32_e32 v13, 0x58000, v158
	global_store_dword v13, v12, s[12:13]
	v_cvt_pk_bf16_f32 v12, v14, v15
	s_nop 1
	v_mov_b32_dpp v13, v12 quad_perm:[1,0,3,2] row_mask:0xf bank_mask:0xf
	v_perm_b32 v12, v13, v12, v250
	v_add_u32_e32 v13, 0x59000, v158
	global_store_dword v13, v12, s[12:13]
	v_cvt_pk_bf16_f32 v12, v4, v5
	s_nop 1
	v_mov_b32_dpp v13, v12 quad_perm:[1,0,3,2] row_mask:0xf bank_mask:0xf
	v_perm_b32 v4, v13, v12, v250
	v_add_u32_e32 v5, 0x58020, v158
	global_store_dword v5, v4, s[12:13]
	v_cvt_pk_bf16_f32 v4, v6, v7
	s_nop 1
	v_mov_b32_dpp v5, v4 quad_perm:[1,0,3,2] row_mask:0xf bank_mask:0xf
	v_perm_b32 v4, v5, v4, v250
	v_add_u32_e32 v5, 0x59020, v158
	global_store_dword v5, v4, s[12:13]
	v_cvt_pk_bf16_f32 v4, v8, v9
	s_nop 1
	v_mov_b32_dpp v5, v4 quad_perm:[1,0,3,2] row_mask:0xf bank_mask:0xf
	v_perm_b32 v4, v5, v4, v250
	v_add_u32_e32 v5, 0x58100, v158
	global_store_dword v5, v4, s[12:13]
	v_cvt_pk_bf16_f32 v4, v10, v11
	s_nop 1
	v_mov_b32_dpp v5, v4 quad_perm:[1,0,3,2] row_mask:0xf bank_mask:0xf
	v_perm_b32 v4, v5, v4, v250
	v_add_u32_e32 v5, 0x59100, v158
	global_store_dword v5, v4, s[12:13]
	v_cvt_pk_bf16_f32 v4, v0, v1
	s_nop 1
	v_mov_b32_dpp v5, v4 quad_perm:[1,0,3,2] row_mask:0xf bank_mask:0xf
	v_perm_b32 v0, v5, v4, v250
	v_add_u32_e32 v1, 0x58120, v158
	global_store_dword v1, v0, s[12:13]
	v_cvt_pk_bf16_f32 v0, v2, v3
	s_nop 1
	v_mov_b32_dpp v1, v0 quad_perm:[1,0,3,2] row_mask:0xf bank_mask:0xf
	v_perm_b32 v0, v1, v0, v250
	v_add_u32_e32 v1, 0x59120, v158
	global_store_dword v1, v0, s[12:13]
	s_and_b64 vcc, exec, s[38:39]
	s_mov_b32 s18, s36
	s_mov_b32 s19, s37
	s_cbranch_vccnz .LBB0_87

.LBB0_93:
	s_waitcnt vmcnt(0)
	v_mov_b32_e32 v0, v131
	s_mov_b32 s34, s83
	s_mov_b32 s36, s73
	s_cmpk_gt_i32 s36, 0xaff
	s_cbranch_scc1 .LBB0_104
	s_add_u32 s37, s26, s6
	s_addc_u32 s46, s27, s7
	s_add_u32 s14, s26, 0x3c00000
	s_addc_u32 s15, s27, 0
	s_ashr_i32 s6, s36, 31
	s_lshr_b32 s6, s6, 29
	s_add_i32 s6, s36, s6
	s_ashr_i32 s7, s6, 3
	s_and_b32 s6, s6, -8
	s_sub_i32 s6, s36, s6
	s_cmp_lt_i32 s6, 0
	s_movk_i32 s8, 0x161
	s_cselect_b32 s8, s8, 0x160
	s_mul_i32 s6, s8, s6
	s_add_i32 s6, s6, s7
	s_mul_hi_i32 s7, s6, 0x2e8ba2e9
	s_lshr_b32 s8, s7, 31
	s_ashr_i32 s7, s7, 5
	s_add_i32 s7, s7, s8
	s_mul_i32 s8, s7, 0xb0
	s_sub_i32 s6, s6, s8
	s_bfe_u32 s8, s6, 0x3001c
	s_add_i32 s8, s6, s8
	s_sext_i32_i16 s9, s8
	s_and_b32 s8, s8, 0xfff8
	s_sub_i32 s6, s6, s8
	s_sext_i32_i16 s6, s6
	v_ashrrev_i32_e32 v1, 6, v0
	v_lshrrev_b32_e32 v2, 31, v0
	s_lshl_b32 s7, s7, 11
	s_lshl_b32 s6, s6, 8
	v_add_u32_e32 v2, v1, v2
	v_lshlrev_b32_e32 v3, 9, v0
	s_add_i32 s76, s6, s7
	s_lshl_b32 s6, s9, 5
	v_ashrrev_i32_e32 v8, 1, v2
	v_and_b32_e32 v9, 0x7800, v3
	v_and_b32_e32 v2, 0x3fffffe, v2
	s_and_b32 s78, s6, 0xffffff00
	v_lshl_or_b32 v3, v8, 15, v9
	v_sub_u32_e32 v2, v1, v2
	s_ashr_i32 s77, s76, 31
	s_ashr_i32 s79, s78, 31
	v_lshl_add_u32 v2, v2, 6, v3
	v_lshlrev_b32_e32 v3, 4, v0
	v_lshlrev_b32_e32 v134, 10, v1
	s_lshl_b64 s[6:7], s[76:77], 11
	s_lshl_b64 s[8:9], s[78:79], 11
	v_and_b32_e32 v10, 48, v3
	v_and_b32_e32 v11, 32, v0
	s_add_u32 s68, s37, s8
	v_add_u32_e32 v135, 0x10000, v134
	v_bitop3_b32 v128, v2, v10, v11 bitop3:0xf6
	s_addc_u32 s69, s46, s9
	v_readfirstlane_b32 s8, v135
	v_add_u32_e32 v136, 0x12000, v134
	v_lshl_add_u64 v[2:3], s[68:69], 0, v[128:129]
	s_mov_b32 m0, s8
	s_mov_b64 s[10:11], 0x20000
	v_readfirstlane_b32 s8, v136
	s_add_u32 s70, s16, s6
	global_load_lds_dwordx4 v128, s[68:69]
	v_lshl_add_u64 v[4:5], v[2:3], 0, s[10:11]
	s_mov_b32 m0, s8
	s_addc_u32 s71, s17, s7
	v_readfirstlane_b32 s6, v134
	v_add_u32_e32 v137, 0x2000, v134
	global_load_lds_dwordx4 v[4:5], off
	v_lshl_add_u64 v[4:5], s[70:71], 0, v[128:129]
	s_mov_b32 m0, s6
	v_readfirstlane_b32 s6, v137
	v_add_u32_e32 v138, 0x14000, v134
	global_load_lds_dwordx4 v128, s[70:71]
	v_lshl_add_u64 v[6:7], v[4:5], 0, s[10:11]
	s_mov_b32 m0, s6
	s_mov_b64 s[8:9], 0x40000
	v_readfirstlane_b32 s6, v138
	v_add_u32_e32 v139, 0x16000, v134
	global_load_lds_dwordx4 v[6:7], off
	v_lshl_add_u64 v[6:7], v[2:3], 0, s[8:9]
	s_mov_b32 m0, s6
	s_mov_b64 s[10:11], 0x60000
	v_readfirstlane_b32 s6, v139
	v_add_u32_e32 v140, 0x4000, v134
	global_load_lds_dwordx4 v[6:7], off
	v_lshl_add_u64 v[6:7], v[2:3], 0, s[10:11]
	s_mov_b32 m0, s6
	v_readfirstlane_b32 s6, v140
	v_add_u32_e32 v141, 0x6000, v134
	global_load_lds_dwordx4 v[6:7], off
	v_lshl_add_u64 v[6:7], v[4:5], 0, s[8:9]
	s_mov_b32 m0, s6
	v_readfirstlane_b32 s6, v141
	v_add_u32_e32 v142, 0x18000, v134
	global_load_lds_dwordx4 v[6:7], off
	v_lshl_add_u64 v[6:7], v[4:5], 0, s[10:11]
	s_mov_b32 m0, s6
	v_readfirstlane_b32 s6, v142
	v_add_u32_e32 v143, 0x1a000, v134
	global_load_lds_dwordx4 v[6:7], off
	v_lshl_add_u64 v[6:7], v[2:3], 0, s[44:45]
	s_mov_b32 m0, s6
	s_mov_b64 s[8:9], 0x20080
	v_readfirstlane_b32 s6, v143
	v_add_u32_e32 v144, 0x8000, v134
	global_load_lds_dwordx4 v[6:7], off
	v_lshl_add_u64 v[6:7], v[2:3], 0, s[8:9]
	s_mov_b32 m0, s6
	v_readfirstlane_b32 s6, v144
	v_add_u32_e32 v145, 0xa000, v134
	global_load_lds_dwordx4 v[6:7], off
	v_lshl_add_u64 v[6:7], v[4:5], 0, s[44:45]
	s_mov_b32 m0, s6
	v_readfirstlane_b32 s6, v145
	v_add_u32_e32 v146, 0x1c000, v134
	global_load_lds_dwordx4 v[6:7], off
	v_lshl_add_u64 v[4:5], v[4:5], 0, s[8:9]
	s_mov_b32 m0, s6
	v_readfirstlane_b32 s6, v146
	v_add_u32_e32 v147, 0x1e000, v134
	global_load_lds_dwordx4 v[4:5], off
	v_lshl_add_u64 v[4:5], v[2:3], 0, s[48:49]
	s_mov_b32 m0, s6
	v_readfirstlane_b32 s6, v147
	global_load_lds_dwordx4 v[4:5], off
	v_lshl_add_u64 v[2:3], v[2:3], 0, s[50:51]
	s_mov_b32 m0, s6
	v_and_b32_e32 v5, 48, v0
	global_load_lds_dwordx4 v[2:3], off
	v_and_b32_e32 v2, 15, v0
	v_lshlrev_b32_e32 v2, 6, v2
	v_lshlrev_b32_e32 v7, 2, v0
	v_ashrrev_i32_e32 v3, 8, v0
	v_or_b32_e32 v6, v2, v5
	v_and_b32_e32 v7, 32, v7
	s_mov_b32 s8, 0x10000
	v_lshrrev_b32_e32 v17, 2, v0
	v_bitop3_b32 v12, v6, s8, v7 bitop3:0xde
	v_lshlrev_b32_e32 v13, 6, v3
	s_mov_b32 s8, 0x14000
	v_and_b32_e32 v16, 1, v0
	v_and_b32_e32 v17, 12, v17
	v_and_b32_e32 v1, 3, v1
	v_bitop3_b32 v14, v6, s8, v7 bitop3:0xde
	s_mov_b32 s8, 0x18000
	v_or3_b32 v148, v13, v17, v16
	v_and_b32_e32 v13, 14, v0
	v_cmp_eq_u32_e64 s[6:7], 1, v3
	v_lshlrev_b32_e32 v4, 12, v1
	v_bitop3_b32 v15, v6, s8, v7 bitop3:0xde
	s_mov_b32 s8, 0x1c000
	v_lshl_or_b32 v149, v1, 5, v13
	v_lshlrev_b32_e32 v1, 13, v3
	v_lshlrev_b32_e32 v3, 6, v0
	s_movk_i32 s18, 0x7f80
	v_bitop3_b32 v6, v6, s8, v7 bitop3:0xde
	s_movk_i32 s8, 0x100
	v_and_b32_e32 v3, 0x3c0, v3
	v_mul_lo_u32 v8, v8, s18
	v_bitop3_b32 v2, v2, v7, v5 bitop3:0x36
	v_cmp_gt_u32_e64 s[8:9], s8, v0
	v_bitop3_b32 v3, v3, v7, v5 bitop3:0x36
	v_or_b32_e32 v5, 0x800, v1
	v_or_b32_e32 v7, 0x1000, v1
	v_or_b32_e32 v13, 0x1800, v1
	v_bitop3_b32 v8, v10, v8, v11 bitop3:0xde
	v_and_b32_e32 v0, 0xffffffc0, v0
	v_cmp_eq_u32_e64 s[10:11], 0, v16
	v_add3_u32 v132, v8, v9, v0
	v_mov_b32_e32 v133, v129
	v_add_u32_e32 v150, v12, v4
	v_add_u32_e32 v151, v2, v1
	v_add_u32_e32 v152, v3, v5
	v_add_u32_e32 v153, v3, v7
	v_add_u32_e32 v154, v3, v13
	v_add_u32_e32 v155, v14, v4
	v_add_u32_e32 v156, v15, v4
	v_add_u32_e32 v157, v6, v4
	s_waitcnt vmcnt(0)
	v_mov_b32_e32 v250, 0x3020706
	v_mov_b32_e32 v251, 0x5040100
	v_cndmask_b32_e64 v250, v250, v251, s[10:11]
	s_branch .LBB0_96
.LBB0_95:
	v_pk_mul_f32 v[160:161], v[120:121], s[72:73] op_sel_hi:[1,0]
	v_add_u32_e32 v158, s76, v148
	v_exp_f32_e32 v160, v160
	v_exp_f32_e32 v161, v161
	s_movk_i32 s18, 0xb00
	v_mul_lo_u32 v158, v158, s18
	s_lshr_b32 s18, s78, 1
	v_pk_add_f32 v[160:161], v[160:161], 1.0 op_sel_hi:[1,0]
	v_or_b32_e32 v159, s18, v149
	v_rcp_f32_e32 v160, v160
	v_rcp_f32_e32 v161, v161
	v_add_lshl_u32 v158, v159, v158, 1
	v_pk_mul_f32 v[120:121], v[120:121], v[160:161]
	s_nop 0
	v_pk_mul_f32 v[120:121], v[120:121], v[124:125]
	v_cvt_pk_bf16_f32 v124, v120, v121
	s_nop 1
	v_mov_b32_dpp v125, v124 quad_perm:[1,0,3,2] row_mask:0xf bank_mask:0xf
	v_perm_b32 v120, v125, v124, v250
	global_store_dword v158, v120, s[14:15]
	v_pk_mul_f32 v[120:121], v[122:123], s[72:73] op_sel_hi:[1,0]
	s_nop 0
	v_exp_f32_e32 v120, v120
	v_exp_f32_e32 v121, v121
	s_nop 0
	v_pk_add_f32 v[120:121], v[120:121], 1.0 op_sel_hi:[1,0]
	s_nop 0
	v_rcp_f32_e32 v120, v120
	v_rcp_f32_e32 v121, v121
	s_nop 0
	v_pk_mul_f32 v[120:121], v[122:123], v[120:121]
	s_nop 0
	v_pk_mul_f32 v[120:121], v[120:121], v[126:127]
	v_cvt_pk_bf16_f32 v122, v120, v121
	s_nop 1
	v_mov_b32_dpp v123, v122 quad_perm:[1,0,3,2] row_mask:0xf bank_mask:0xf
	v_perm_b32 v120, v123, v122, v250
	v_add_u32_e32 v121, 0x2c00, v158
	global_store_dword v121, v120, s[14:15]
	v_pk_mul_f32 v[120:121], v[112:113], s[72:73] op_sel_hi:[1,0]
	v_or_b32_e32 v122, 32, v158
	v_exp_f32_e32 v120, v120
	v_exp_f32_e32 v121, v121
	s_nop 0
	v_pk_add_f32 v[120:121], v[120:121], 1.0 op_sel_hi:[1,0]
	s_nop 0
	v_rcp_f32_e32 v120, v120
	v_rcp_f32_e32 v121, v121
	s_nop 0
	v_pk_mul_f32 v[112:113], v[112:113], v[120:121]
	s_nop 0
	v_pk_mul_f32 v[112:113], v[112:113], v[116:117]
	v_cvt_pk_bf16_f32 v116, v112, v113
	s_nop 1
	v_mov_b32_dpp v117, v116 quad_perm:[1,0,3,2] row_mask:0xf bank_mask:0xf
	v_perm_b32 v112, v117, v116, v250
	global_store_dword v122, v112, s[14:15]
	v_pk_mul_f32 v[112:113], v[114:115], s[72:73] op_sel_hi:[1,0]
	s_nop 0
	v_exp_f32_e32 v112, v112
	v_exp_f32_e32 v113, v113
	s_nop 0
	v_pk_add_f32 v[112:113], v[112:113], 1.0 op_sel_hi:[1,0]
	s_nop 0
	v_rcp_f32_e32 v112, v112
	v_rcp_f32_e32 v113, v113
	s_nop 0
	v_pk_mul_f32 v[112:113], v[114:115], v[112:113]
	s_nop 0
	v_pk_mul_f32 v[112:113], v[112:113], v[118:119]
	v_cvt_pk_bf16_f32 v114, v112, v113
	s_nop 1
	v_mov_b32_dpp v115, v114 quad_perm:[1,0,3,2] row_mask:0xf bank_mask:0xf
	v_perm_b32 v112, v115, v114, v250
	v_add_u32_e32 v113, 0x2c20, v158
	global_store_dword v113, v112, s[14:15]
	v_pk_mul_f32 v[112:113], v[104:105], s[72:73] op_sel_hi:[1,0]
	s_nop 0
	v_exp_f32_e32 v112, v112
	v_exp_f32_e32 v113, v113
	s_nop 0
	v_pk_add_f32 v[112:113], v[112:113], 1.0 op_sel_hi:[1,0]
	s_nop 0
	v_rcp_f32_e32 v112, v112
	v_rcp_f32_e32 v113, v113
	s_nop 0
	v_pk_mul_f32 v[104:105], v[104:105], v[112:113]
	s_nop 0
	v_pk_mul_f32 v[104:105], v[104:105], v[108:109]
	v_cvt_pk_bf16_f32 v108, v104, v105
	s_nop 1
	v_mov_b32_dpp v109, v108 quad_perm:[1,0,3,2] row_mask:0xf bank_mask:0xf
	v_perm_b32 v104, v109, v108, v250
	v_add_u32_e32 v105, 0x16000, v158
	global_store_dword v105, v104, s[14:15]
	v_pk_mul_f32 v[104:105], v[106:107], s[72:73] op_sel_hi:[1,0]
	s_nop 0
	v_exp_f32_e32 v104, v104
	v_exp_f32_e32 v105, v105
	s_nop 0
	v_pk_add_f32 v[104:105], v[104:105], 1.0 op_sel_hi:[1,0]
	s_nop 0
	v_rcp_f32_e32 v104, v104
	v_rcp_f32_e32 v105, v105
	s_nop 0
	v_pk_mul_f32 v[104:105], v[106:107], v[104:105]
	s_nop 0
	v_pk_mul_f32 v[104:105], v[104:105], v[110:111]
	v_cvt_pk_bf16_f32 v106, v104, v105
	s_nop 1
	v_mov_b32_dpp v107, v106 quad_perm:[1,0,3,2] row_mask:0xf bank_mask:0xf
	v_perm_b32 v104, v107, v106, v250
	v_add_u32_e32 v105, 0x18c00, v158
	global_store_dword v105, v104, s[14:15]
	v_pk_mul_f32 v[104:105], v[96:97], s[72:73] op_sel_hi:[1,0]
	s_nop 0
	v_exp_f32_e32 v104, v104
	v_exp_f32_e32 v105, v105
	s_nop 0
	v_pk_add_f32 v[104:105], v[104:105], 1.0 op_sel_hi:[1,0]
	s_nop 0
	v_rcp_f32_e32 v104, v104
	v_rcp_f32_e32 v105, v105
	s_nop 0
	v_pk_mul_f32 v[96:97], v[96:97], v[104:105]
	s_nop 0
	v_pk_mul_f32 v[96:97], v[96:97], v[100:101]
	v_cvt_pk_bf16_f32 v100, v96, v97
	s_nop 1
	v_mov_b32_dpp v101, v100 quad_perm:[1,0,3,2] row_mask:0xf bank_mask:0xf
	v_perm_b32 v96, v101, v100, v250
	v_add_u32_e32 v97, 0x16020, v158
	global_store_dword v97, v96, s[14:15]
	v_pk_mul_f32 v[96:97], v[98:99], s[72:73] op_sel_hi:[1,0]
	s_nop 0
	v_exp_f32_e32 v96, v96
	v_exp_f32_e32 v97, v97
	s_nop 0
	v_pk_add_f32 v[96:97], v[96:97], 1.0 op_sel_hi:[1,0]
	s_nop 0
	v_rcp_f32_e32 v96, v96
	v_rcp_f32_e32 v97, v97
	s_nop 0
	v_pk_mul_f32 v[96:97], v[98:99], v[96:97]
	s_nop 0
	v_pk_mul_f32 v[96:97], v[96:97], v[102:103]
	v_cvt_pk_bf16_f32 v98, v96, v97
	s_nop 1
	v_mov_b32_dpp v99, v98 quad_perm:[1,0,3,2] row_mask:0xf bank_mask:0xf
	v_perm_b32 v96, v99, v98, v250
	v_add_u32_e32 v97, 0x18c20, v158
	global_store_dword v97, v96, s[14:15]
	v_pk_mul_f32 v[96:97], v[88:89], s[72:73] op_sel_hi:[1,0]
	s_nop 0
	v_exp_f32_e32 v96, v96
	v_exp_f32_e32 v97, v97
	s_nop 0
	v_pk_add_f32 v[96:97], v[96:97], 1.0 op_sel_hi:[1,0]
	s_nop 0
	v_rcp_f32_e32 v96, v96
	v_rcp_f32_e32 v97, v97
	s_nop 0
	v_pk_mul_f32 v[88:89], v[88:89], v[96:97]
	s_nop 0
	v_pk_mul_f32 v[88:89], v[88:89], v[92:93]
	v_cvt_pk_bf16_f32 v92, v88, v89
	s_nop 1
	v_mov_b32_dpp v93, v92 quad_perm:[1,0,3,2] row_mask:0xf bank_mask:0xf
	v_perm_b32 v88, v93, v92, v250
	v_add_u32_e32 v89, 0x2c000, v158
	global_store_dword v89, v88, s[14:15]
	v_pk_mul_f32 v[88:89], v[90:91], s[72:73] op_sel_hi:[1,0]
	s_nop 0
	v_exp_f32_e32 v88, v88
	v_exp_f32_e32 v89, v89
	s_nop 0
	v_pk_add_f32 v[88:89], v[88:89], 1.0 op_sel_hi:[1,0]
	s_nop 0
	v_rcp_f32_e32 v88, v88
	v_rcp_f32_e32 v89, v89
	s_nop 0
	v_pk_mul_f32 v[88:89], v[90:91], v[88:89]
	s_nop 0
	v_pk_mul_f32 v[88:89], v[88:89], v[94:95]
	v_cvt_pk_bf16_f32 v90, v88, v89
	s_nop 1
	v_mov_b32_dpp v91, v90 quad_perm:[1,0,3,2] row_mask:0xf bank_mask:0xf
	v_perm_b32 v88, v91, v90, v250
	v_add_u32_e32 v89, 0x2ec00, v158
	global_store_dword v89, v88, s[14:15]
	v_pk_mul_f32 v[88:89], v[80:81], s[72:73] op_sel_hi:[1,0]
	s_nop 0
	v_exp_f32_e32 v88, v88
	v_exp_f32_e32 v89, v89
	s_nop 0
	v_pk_add_f32 v[88:89], v[88:89], 1.0 op_sel_hi:[1,0]
	s_nop 0
	v_rcp_f32_e32 v88, v88
	v_rcp_f32_e32 v89, v89
	s_nop 0
	v_pk_mul_f32 v[80:81], v[80:81], v[88:89]
	s_nop 0
	v_pk_mul_f32 v[80:81], v[80:81], v[84:85]
	v_cvt_pk_bf16_f32 v84, v80, v81
	s_nop 1
	v_mov_b32_dpp v85, v84 quad_perm:[1,0,3,2] row_mask:0xf bank_mask:0xf
	v_perm_b32 v80, v85, v84, v250
	v_add_u32_e32 v81, 0x2c020, v158
	global_store_dword v81, v80, s[14:15]
	v_pk_mul_f32 v[80:81], v[82:83], s[72:73] op_sel_hi:[1,0]
	s_nop 0
	v_exp_f32_e32 v80, v80
	v_exp_f32_e32 v81, v81
	s_nop 0
	v_pk_add_f32 v[80:81], v[80:81], 1.0 op_sel_hi:[1,0]
	s_nop 0
	v_rcp_f32_e32 v80, v80
	v_rcp_f32_e32 v81, v81
	s_nop 0
	v_pk_mul_f32 v[80:81], v[82:83], v[80:81]
	s_nop 0
	v_pk_mul_f32 v[80:81], v[80:81], v[86:87]
	v_cvt_pk_bf16_f32 v82, v80, v81
	s_nop 1
	v_mov_b32_dpp v83, v82 quad_perm:[1,0,3,2] row_mask:0xf bank_mask:0xf
	v_perm_b32 v80, v83, v82, v250
	v_add_u32_e32 v81, 0x2ec20, v158
	global_store_dword v81, v80, s[14:15]
	v_pk_mul_f32 v[80:81], v[72:73], s[72:73] op_sel_hi:[1,0]
	s_nop 0
	v_exp_f32_e32 v80, v80
	v_exp_f32_e32 v81, v81
	s_nop 0
	v_pk_add_f32 v[80:81], v[80:81], 1.0 op_sel_hi:[1,0]
	s_nop 0
	v_rcp_f32_e32 v80, v80
	v_rcp_f32_e32 v81, v81
	s_nop 0
	v_pk_mul_f32 v[72:73], v[72:73], v[80:81]
	s_nop 0
	v_pk_mul_f32 v[72:73], v[72:73], v[76:77]
	v_cvt_pk_bf16_f32 v76, v72, v73
	s_nop 1
	v_mov_b32_dpp v77, v76 quad_perm:[1,0,3,2] row_mask:0xf bank_mask:0xf
	v_perm_b32 v72, v77, v76, v250
	v_add_u32_e32 v73, 0x42000, v158
	global_store_dword v73, v72, s[14:15]
	v_pk_mul_f32 v[72:73], v[74:75], s[72:73] op_sel_hi:[1,0]
	s_nop 0
	v_exp_f32_e32 v72, v72
	v_exp_f32_e32 v73, v73
	s_nop 0
	v_pk_add_f32 v[72:73], v[72:73], 1.0 op_sel_hi:[1,0]
	s_nop 0
	v_rcp_f32_e32 v72, v72
	v_rcp_f32_e32 v73, v73
	s_nop 0
	v_pk_mul_f32 v[72:73], v[74:75], v[72:73]
	s_nop 0
	v_pk_mul_f32 v[72:73], v[72:73], v[78:79]
	v_cvt_pk_bf16_f32 v74, v72, v73
	s_nop 1
	v_mov_b32_dpp v75, v74 quad_perm:[1,0,3,2] row_mask:0xf bank_mask:0xf
	v_perm_b32 v72, v75, v74, v250
	v_add_u32_e32 v73, 0x44c00, v158
	global_store_dword v73, v72, s[14:15]
	v_pk_mul_f32 v[72:73], v[64:65], s[72:73] op_sel_hi:[1,0]
	s_nop 0
	v_exp_f32_e32 v72, v72
	v_exp_f32_e32 v73, v73
	s_nop 0
	v_pk_add_f32 v[72:73], v[72:73], 1.0 op_sel_hi:[1,0]
	s_nop 0
	v_rcp_f32_e32 v72, v72
	v_rcp_f32_e32 v73, v73
	s_nop 0
	v_pk_mul_f32 v[64:65], v[64:65], v[72:73]
	s_nop 0
	v_pk_mul_f32 v[64:65], v[64:65], v[68:69]
	v_cvt_pk_bf16_f32 v68, v64, v65
	s_nop 1
	v_mov_b32_dpp v69, v68 quad_perm:[1,0,3,2] row_mask:0xf bank_mask:0xf
	v_perm_b32 v64, v69, v68, v250
	v_add_u32_e32 v65, 0x42020, v158
	global_store_dword v65, v64, s[14:15]
	v_pk_mul_f32 v[64:65], v[66:67], s[72:73] op_sel_hi:[1,0]
	s_nop 0
	v_exp_f32_e32 v64, v64
	v_exp_f32_e32 v65, v65
	s_nop 0
	v_pk_add_f32 v[64:65], v[64:65], 1.0 op_sel_hi:[1,0]
	s_nop 0
	v_rcp_f32_e32 v64, v64
	v_rcp_f32_e32 v65, v65
	s_nop 0
	v_pk_mul_f32 v[64:65], v[66:67], v[64:65]
	s_nop 0
	v_pk_mul_f32 v[64:65], v[64:65], v[70:71]
	v_cvt_pk_bf16_f32 v66, v64, v65
	s_nop 1
	v_mov_b32_dpp v67, v66 quad_perm:[1,0,3,2] row_mask:0xf bank_mask:0xf
	v_perm_b32 v64, v67, v66, v250
	v_add_u32_e32 v65, 0x44c20, v158
	global_store_dword v65, v64, s[14:15]
	v_pk_mul_f32 v[64:65], v[56:57], s[72:73] op_sel_hi:[1,0]
	s_nop 0
	v_exp_f32_e32 v64, v64
	v_exp_f32_e32 v65, v65
	s_nop 0
	v_pk_add_f32 v[64:65], v[64:65], 1.0 op_sel_hi:[1,0]
	s_nop 0
	v_rcp_f32_e32 v64, v64
	v_rcp_f32_e32 v65, v65
	s_nop 0
	v_pk_mul_f32 v[56:57], v[56:57], v[64:65]
	s_nop 0
	v_pk_mul_f32 v[56:57], v[56:57], v[60:61]
	v_cvt_pk_bf16_f32 v60, v56, v57
	s_nop 1
	v_mov_b32_dpp v61, v60 quad_perm:[1,0,3,2] row_mask:0xf bank_mask:0xf
	v_perm_b32 v56, v61, v60, v250
	v_add_u32_e32 v57, 0xb0000, v158
	global_store_dword v57, v56, s[14:15]
	v_pk_mul_f32 v[56:57], v[58:59], s[72:73] op_sel_hi:[1,0]
	s_nop 0
	v_exp_f32_e32 v56, v56
	v_exp_f32_e32 v57, v57
	s_nop 0
	v_pk_add_f32 v[56:57], v[56:57], 1.0 op_sel_hi:[1,0]
	s_nop 0
	v_rcp_f32_e32 v56, v56
	v_rcp_f32_e32 v57, v57
	s_nop 0
	v_pk_mul_f32 v[56:57], v[58:59], v[56:57]
	s_nop 0
	v_pk_mul_f32 v[56:57], v[56:57], v[62:63]
	v_cvt_pk_bf16_f32 v58, v56, v57
	s_nop 1
	v_mov_b32_dpp v59, v58 quad_perm:[1,0,3,2] row_mask:0xf bank_mask:0xf
	v_perm_b32 v56, v59, v58, v250
	v_add_u32_e32 v57, 0xb2c00, v158
	global_store_dword v57, v56, s[14:15]
	v_pk_mul_f32 v[56:57], v[48:49], s[72:73] op_sel_hi:[1,0]
	s_nop 0
	v_exp_f32_e32 v56, v56
	v_exp_f32_e32 v57, v57
	s_nop 0
	v_pk_add_f32 v[56:57], v[56:57], 1.0 op_sel_hi:[1,0]
	s_nop 0
	v_rcp_f32_e32 v56, v56
	v_rcp_f32_e32 v57, v57
	s_nop 0
	v_pk_mul_f32 v[48:49], v[48:49], v[56:57]
	s_nop 0
	v_pk_mul_f32 v[48:49], v[48:49], v[52:53]
	v_cvt_pk_bf16_f32 v52, v48, v49
	s_nop 1
	v_mov_b32_dpp v53, v52 quad_perm:[1,0,3,2] row_mask:0xf bank_mask:0xf
	v_perm_b32 v48, v53, v52, v250
	v_add_u32_e32 v49, 0xb0020, v158
	global_store_dword v49, v48, s[14:15]
	v_pk_mul_f32 v[48:49], v[50:51], s[72:73] op_sel_hi:[1,0]
	s_nop 0
	v_exp_f32_e32 v48, v48
	v_exp_f32_e32 v49, v49
	s_nop 0
	v_pk_add_f32 v[48:49], v[48:49], 1.0 op_sel_hi:[1,0]
	s_nop 0
	v_rcp_f32_e32 v48, v48
	v_rcp_f32_e32 v49, v49
	s_nop 0
	v_pk_mul_f32 v[48:49], v[50:51], v[48:49]
	s_nop 0
	v_pk_mul_f32 v[48:49], v[48:49], v[54:55]
	v_cvt_pk_bf16_f32 v50, v48, v49
	s_nop 1
	v_mov_b32_dpp v51, v50 quad_perm:[1,0,3,2] row_mask:0xf bank_mask:0xf
	v_perm_b32 v48, v51, v50, v250
	v_add_u32_e32 v49, 0xb2c20, v158
	global_store_dword v49, v48, s[14:15]
	v_pk_mul_f32 v[48:49], v[40:41], s[72:73] op_sel_hi:[1,0]
	s_nop 0
	v_exp_f32_e32 v48, v48
	v_exp_f32_e32 v49, v49
	s_nop 0
	v_pk_add_f32 v[48:49], v[48:49], 1.0 op_sel_hi:[1,0]
	s_nop 0
	v_rcp_f32_e32 v48, v48
	v_rcp_f32_e32 v49, v49
	s_nop 0
	v_pk_mul_f32 v[40:41], v[40:41], v[48:49]
	s_nop 0
	v_pk_mul_f32 v[40:41], v[40:41], v[44:45]
	v_cvt_pk_bf16_f32 v44, v40, v41
	s_nop 1
	v_mov_b32_dpp v45, v44 quad_perm:[1,0,3,2] row_mask:0xf bank_mask:0xf
	v_perm_b32 v40, v45, v44, v250
	v_add_u32_e32 v41, 0xc6000, v158
	global_store_dword v41, v40, s[14:15]
	v_pk_mul_f32 v[40:41], v[42:43], s[72:73] op_sel_hi:[1,0]
	s_nop 0
	v_exp_f32_e32 v40, v40
	v_exp_f32_e32 v41, v41
	s_nop 0
	v_pk_add_f32 v[40:41], v[40:41], 1.0 op_sel_hi:[1,0]
	s_nop 0
	v_rcp_f32_e32 v40, v40
	v_rcp_f32_e32 v41, v41
	s_nop 0
	v_pk_mul_f32 v[40:41], v[42:43], v[40:41]
	s_nop 0
	v_pk_mul_f32 v[40:41], v[40:41], v[46:47]
	v_cvt_pk_bf16_f32 v42, v40, v41
	s_nop 1
	v_mov_b32_dpp v43, v42 quad_perm:[1,0,3,2] row_mask:0xf bank_mask:0xf
	v_perm_b32 v40, v43, v42, v250
	v_add_u32_e32 v41, 0xc8c00, v158
	global_store_dword v41, v40, s[14:15]
	v_pk_mul_f32 v[40:41], v[32:33], s[72:73] op_sel_hi:[1,0]
	s_nop 0
	v_exp_f32_e32 v40, v40
	v_exp_f32_e32 v41, v41
	s_nop 0
	v_pk_add_f32 v[40:41], v[40:41], 1.0 op_sel_hi:[1,0]
	s_nop 0
	v_rcp_f32_e32 v40, v40
	v_rcp_f32_e32 v41, v41
	s_nop 0
	v_pk_mul_f32 v[32:33], v[32:33], v[40:41]
	s_nop 0
	v_pk_mul_f32 v[32:33], v[32:33], v[36:37]
	v_cvt_pk_bf16_f32 v36, v32, v33
	s_nop 1
	v_mov_b32_dpp v37, v36 quad_perm:[1,0,3,2] row_mask:0xf bank_mask:0xf
	v_perm_b32 v32, v37, v36, v250
	v_add_u32_e32 v33, 0xc6020, v158
	global_store_dword v33, v32, s[14:15]
	v_pk_mul_f32 v[32:33], v[34:35], s[72:73] op_sel_hi:[1,0]
	s_nop 0
	v_exp_f32_e32 v32, v32
	v_exp_f32_e32 v33, v33
	s_nop 0
	v_pk_add_f32 v[32:33], v[32:33], 1.0 op_sel_hi:[1,0]
	s_nop 0
	v_rcp_f32_e32 v32, v32
	v_rcp_f32_e32 v33, v33
	s_nop 0
	v_pk_mul_f32 v[32:33], v[34:35], v[32:33]
	s_nop 0
	v_pk_mul_f32 v[32:33], v[32:33], v[38:39]
	v_cvt_pk_bf16_f32 v34, v32, v33
	s_nop 1
	v_mov_b32_dpp v35, v34 quad_perm:[1,0,3,2] row_mask:0xf bank_mask:0xf
	v_perm_b32 v32, v35, v34, v250
	v_add_u32_e32 v33, 0xc8c20, v158
	global_store_dword v33, v32, s[14:15]
	v_pk_mul_f32 v[32:33], v[24:25], s[72:73] op_sel_hi:[1,0]
	s_nop 0
	v_exp_f32_e32 v32, v32
	v_exp_f32_e32 v33, v33
	s_nop 0
	v_pk_add_f32 v[32:33], v[32:33], 1.0 op_sel_hi:[1,0]
	s_nop 0
	v_rcp_f32_e32 v32, v32
	v_rcp_f32_e32 v33, v33
	s_nop 0
	v_pk_mul_f32 v[24:25], v[24:25], v[32:33]
	s_nop 0
	v_pk_mul_f32 v[24:25], v[24:25], v[28:29]
	v_cvt_pk_bf16_f32 v28, v24, v25
	s_nop 1
	v_mov_b32_dpp v29, v28 quad_perm:[1,0,3,2] row_mask:0xf bank_mask:0xf
	v_perm_b32 v24, v29, v28, v250
	v_add_u32_e32 v25, 0xdc000, v158
	global_store_dword v25, v24, s[14:15]
	v_pk_mul_f32 v[24:25], v[26:27], s[72:73] op_sel_hi:[1,0]
	s_nop 0
	v_exp_f32_e32 v24, v24
	v_exp_f32_e32 v25, v25
	s_nop 0
	v_pk_add_f32 v[24:25], v[24:25], 1.0 op_sel_hi:[1,0]
	s_nop 0
	v_rcp_f32_e32 v24, v24
	v_rcp_f32_e32 v25, v25
	s_nop 0
	v_pk_mul_f32 v[24:25], v[26:27], v[24:25]
	s_nop 0
	v_pk_mul_f32 v[24:25], v[24:25], v[30:31]
	v_cvt_pk_bf16_f32 v26, v24, v25
	s_nop 1
	v_mov_b32_dpp v27, v26 quad_perm:[1,0,3,2] row_mask:0xf bank_mask:0xf
	v_perm_b32 v24, v27, v26, v250
	v_add_u32_e32 v25, 0xdec00, v158
	global_store_dword v25, v24, s[14:15]
	v_pk_mul_f32 v[24:25], v[16:17], s[72:73] op_sel_hi:[1,0]
	s_nop 0
	v_exp_f32_e32 v24, v24
	v_exp_f32_e32 v25, v25
	s_nop 0
	v_pk_add_f32 v[24:25], v[24:25], 1.0 op_sel_hi:[1,0]
	s_nop 0
	v_rcp_f32_e32 v24, v24
	v_rcp_f32_e32 v25, v25
	s_nop 0
	v_pk_mul_f32 v[16:17], v[16:17], v[24:25]
	s_nop 0
	v_pk_mul_f32 v[16:17], v[16:17], v[20:21]
	v_cvt_pk_bf16_f32 v20, v16, v17
	s_nop 1
	v_mov_b32_dpp v21, v20 quad_perm:[1,0,3,2] row_mask:0xf bank_mask:0xf
	v_perm_b32 v16, v21, v20, v250
	v_add_u32_e32 v17, 0xdc020, v158
	global_store_dword v17, v16, s[14:15]
	v_pk_mul_f32 v[16:17], v[18:19], s[72:73] op_sel_hi:[1,0]
	s_nop 0
	v_exp_f32_e32 v16, v16
	v_exp_f32_e32 v17, v17
	s_nop 0
	v_pk_add_f32 v[16:17], v[16:17], 1.0 op_sel_hi:[1,0]
	s_nop 0
	v_rcp_f32_e32 v16, v16
	v_rcp_f32_e32 v17, v17
	s_nop 0
	v_pk_mul_f32 v[16:17], v[18:19], v[16:17]
	s_nop 0
	v_pk_mul_f32 v[16:17], v[16:17], v[22:23]
	v_cvt_pk_bf16_f32 v18, v16, v17
	s_nop 1
	v_mov_b32_dpp v19, v18 quad_perm:[1,0,3,2] row_mask:0xf bank_mask:0xf
	v_perm_b32 v16, v19, v18, v250
	v_add_u32_e32 v17, 0xdec20, v158
	global_store_dword v17, v16, s[14:15]
	v_pk_mul_f32 v[16:17], v[8:9], s[72:73] op_sel_hi:[1,0]
	s_nop 0
	v_exp_f32_e32 v16, v16
	v_exp_f32_e32 v17, v17
	s_nop 0
	v_pk_add_f32 v[16:17], v[16:17], 1.0 op_sel_hi:[1,0]
	s_nop 0
	v_rcp_f32_e32 v16, v16
	v_rcp_f32_e32 v17, v17
	s_nop 0
	v_pk_mul_f32 v[8:9], v[8:9], v[16:17]
	s_nop 0
	v_pk_mul_f32 v[8:9], v[8:9], v[12:13]
	v_cvt_pk_bf16_f32 v12, v8, v9
	s_nop 1
	v_mov_b32_dpp v13, v12 quad_perm:[1,0,3,2] row_mask:0xf bank_mask:0xf
	v_perm_b32 v8, v13, v12, v250
	v_add_u32_e32 v9, 0xf2000, v158
	global_store_dword v9, v8, s[14:15]
	v_pk_mul_f32 v[8:9], v[10:11], s[72:73] op_sel_hi:[1,0]
	s_nop 0
	v_exp_f32_e32 v8, v8
	v_exp_f32_e32 v9, v9
	s_nop 0
	v_pk_add_f32 v[8:9], v[8:9], 1.0 op_sel_hi:[1,0]
	s_nop 0
	v_rcp_f32_e32 v8, v8
	v_rcp_f32_e32 v9, v9
	s_nop 0
	v_pk_mul_f32 v[8:9], v[10:11], v[8:9]
	s_nop 0
	v_pk_mul_f32 v[8:9], v[8:9], v[14:15]
	v_cvt_pk_bf16_f32 v10, v8, v9
	s_nop 1
	v_mov_b32_dpp v11, v10 quad_perm:[1,0,3,2] row_mask:0xf bank_mask:0xf
	v_perm_b32 v8, v11, v10, v250
	v_add_u32_e32 v9, 0xf4c00, v158
	global_store_dword v9, v8, s[14:15]
	v_pk_mul_f32 v[8:9], v[0:1], s[72:73] op_sel_hi:[1,0]
	s_nop 0
	v_exp_f32_e32 v8, v8
	v_exp_f32_e32 v9, v9
	s_nop 0
	v_pk_add_f32 v[8:9], v[8:9], 1.0 op_sel_hi:[1,0]
	s_nop 0
	v_rcp_f32_e32 v8, v8
	v_rcp_f32_e32 v9, v9
	s_nop 0
	v_pk_mul_f32 v[0:1], v[0:1], v[8:9]
	s_nop 0
	v_pk_mul_f32 v[0:1], v[0:1], v[4:5]
	v_cvt_pk_bf16_f32 v4, v0, v1
	s_nop 1
	v_mov_b32_dpp v5, v4 quad_perm:[1,0,3,2] row_mask:0xf bank_mask:0xf
	v_perm_b32 v0, v5, v4, v250
	v_add_u32_e32 v1, 0xf2020, v158
	global_store_dword v1, v0, s[14:15]
	v_pk_mul_f32 v[0:1], v[2:3], s[72:73] op_sel_hi:[1,0]
	s_nop 0
	v_exp_f32_e32 v0, v0
	v_exp_f32_e32 v1, v1
	s_nop 0
	v_pk_add_f32 v[0:1], v[0:1], 1.0 op_sel_hi:[1,0]
	s_nop 0
	v_rcp_f32_e32 v0, v0
	v_rcp_f32_e32 v1, v1
	s_nop 0
	v_pk_mul_f32 v[0:1], v[2:3], v[0:1]
	s_nop 0
	v_pk_mul_f32 v[0:1], v[0:1], v[6:7]
	v_cvt_pk_bf16_f32 v2, v0, v1
	s_nop 1
	v_mov_b32_dpp v3, v2 quad_perm:[1,0,3,2] row_mask:0xf bank_mask:0xf
	v_perm_b32 v0, v3, v2, v250
	v_add_u32_e32 v1, 0xf4c20, v158
	global_store_dword v1, v0, s[14:15]
	s_and_b64 vcc, exec, s[38:39]
	s_mov_b32 s76, s40
	s_mov_b32 s78, s42
	s_cbranch_vccnz .LBB0_104

.LBB0_129:
	s_ashr_i32 s6, s9, 3
	s_add_i32 s6, s8, s6
	s_ashr_i32 s7, s6, 31
	s_lshr_b32 s7, s7, 27
	s_add_i32 s7, s6, s7
	s_and_b32 s8, s7, 0xffe0
	s_sub_i32 s6, s6, s8
	s_bfe_i32 s8, s6, 0x80000
	s_bfe_u32 s8, s8, 0x3000c
	s_add_i32 s8, s6, s8
	s_bfe_i32 s9, s8, 0x80000
	s_and_b32 s8, s8, 0xf8
	s_sub_i32 s6, s6, s8
	s_sext_i32_i8 s6, s6
	s_lshl_b32 s7, s7, 6
	s_sext_i32_i16 s9, s9
	s_and_b32 s7, s7, 0xfffff800
	s_lshl_b32 s6, s6, 8
	v_ashrrev_i32_e32 v1, 6, v0
	v_lshrrev_b32_e32 v4, 31, v0
	s_add_i32 s19, s6, s7
	s_lshl_b32 s6, s9, 5
	v_lshlrev_b32_e32 v2, 4, v0
	v_and_b32_e32 v3, 32, v0
	v_add_u32_e32 v4, v1, v4
	s_and_b32 s80, s6, 0xffffff00
	v_ashrrev_i32_e32 v16, 1, v4
	v_bfe_u32 v5, v0, 2, 4
	v_and_b32_e32 v4, 0x3fffffe, v4
	v_bitop3_b32 v2, v2, v3, 48 bitop3:0x6c
	s_mul_hi_i32 s9, s80, s36
	s_mul_i32 s8, s80, s36
	v_lshlrev_b32_e32 v134, 10, v1
	v_lshl_or_b32 v5, v16, 4, v5
	v_sub_u32_e32 v4, v1, v4
	v_lshrrev_b32_e32 v17, 1, v2
	s_lshr_b32 s10, s36, 6
	s_lshl_b64 s[8:9], s[8:9], 1
	v_lshl_or_b32 v2, v4, 5, v17
	v_mul_lo_u32 v18, v5, s36
	s_mul_hi_i32 s7, s19, s36
	s_mul_i32 s6, s19, s36
	s_waitcnt lgkmcnt(0)
	s_add_u32 s14, s2, s8
	v_add_u32_e32 v135, 0x10000, v134
	v_add_lshl_u32 v128, v2, v18, 1
	s_addc_u32 s15, s3, s9
	s_lshl_b32 s34, s36, 7
	v_readfirstlane_b32 s8, v135
	v_add_u32_e32 v136, 0x12000, v134
	s_lshl_b64 s[6:7], s[6:7], 1
	v_lshl_add_u64 v[2:3], s[14:15], 0, v[128:129]
	s_mov_b32 m0, s8
	v_readfirstlane_b32 s8, v136
	s_add_u32 s38, s16, s6
	global_load_lds_dwordx4 v128, s[14:15]
	v_lshl_add_u64 v[4:5], v[2:3], 0, s[34:35]
	s_mov_b32 m0, s8
	s_addc_u32 s39, s17, s7
	v_readfirstlane_b32 s6, v134
	v_add_u32_e32 v137, 0x2000, v134
	global_load_lds_dwordx4 v[4:5], off
	v_lshl_add_u64 v[6:7], s[38:39], 0, v[128:129]
	s_mov_b32 m0, s6
	v_readfirstlane_b32 s6, v137
	s_lshl_b32 s86, s36, 8
	v_add_u32_e32 v138, 0x14000, v134
	global_load_lds_dwordx4 v128, s[38:39]
	v_lshl_add_u64 v[8:9], v[6:7], 0, s[34:35]
	s_mov_b32 m0, s6
	s_add_u32 s6, s14, s86
	v_readfirstlane_b32 s8, v138
	global_load_lds_dwordx4 v[8:9], off
	s_addc_u32 s7, s15, 0
	s_mov_b32 m0, s8
	v_add_u32_e32 v139, 0x16000, v134
	v_lshl_add_u64 v[10:11], s[6:7], 0, v[128:129]
	global_load_lds_dwordx4 v128, s[6:7]
	v_readfirstlane_b32 s6, v139
	v_add_u32_e32 v140, 0x4000, v134
	v_lshl_add_u64 v[12:13], v[10:11], 0, s[34:35]
	s_mov_b32 m0, s6
	s_add_u32 s6, s38, s86
	v_readfirstlane_b32 s8, v140
	global_load_lds_dwordx4 v[12:13], off
	s_addc_u32 s7, s39, 0
	s_mov_b32 m0, s8
	v_add_u32_e32 v141, 0x6000, v134
	v_lshl_add_u64 v[14:15], s[6:7], 0, v[128:129]
	global_load_lds_dwordx4 v128, s[6:7]
	v_readfirstlane_b32 s6, v141
	v_add_u32_e32 v142, 0x18000, v134
	v_lshl_add_u64 v[14:15], v[14:15], 0, s[34:35]
	s_mov_b32 m0, s6
	v_readfirstlane_b32 s6, v142
	v_add_u32_e32 v143, 0x1a000, v134
	global_load_lds_dwordx4 v[14:15], off
	v_lshl_add_u64 v[2:3], v[2:3], 0, s[44:45]
	s_mov_b32 m0, s6
	v_readfirstlane_b32 s6, v143
	v_add_u32_e32 v144, 0x8000, v134
	global_load_lds_dwordx4 v[2:3], off
	v_lshl_add_u64 v[2:3], v[4:5], 0, s[44:45]
	s_mov_b32 m0, s6
	v_readfirstlane_b32 s6, v144
	v_add_u32_e32 v145, 0xa000, v134
	global_load_lds_dwordx4 v[2:3], off
	v_lshl_add_u64 v[2:3], v[6:7], 0, s[44:45]
	s_mov_b32 m0, s6
	v_readfirstlane_b32 s6, v145
	v_add_u32_e32 v146, 0x1c000, v134
	global_load_lds_dwordx4 v[2:3], off
	v_lshl_add_u64 v[2:3], v[8:9], 0, s[44:45]
	s_mov_b32 m0, s6
	v_readfirstlane_b32 s6, v146
	v_add_u32_e32 v147, 0x1e000, v134
	global_load_lds_dwordx4 v[2:3], off
	v_lshl_add_u64 v[2:3], v[10:11], 0, s[44:45]
	s_mov_b32 m0, s6
	v_readfirstlane_b32 s6, v147
	global_load_lds_dwordx4 v[2:3], off
	v_lshl_add_u64 v[2:3], v[12:13], 0, s[44:45]
	s_mov_b32 m0, s6
	v_and_b32_e32 v4, 15, v0
	global_load_lds_dwordx4 v[2:3], off
	v_and_b32_e32 v7, 48, v0
	v_lshlrev_b32_e32 v4, 6, v4
	v_lshlrev_b32_e32 v9, 2, v0
	v_or_b32_e32 v8, v4, v7
	v_and_b32_e32 v9, 32, v9
	s_mov_b32 s8, 0x10000
	v_bitop3_b32 v10, v8, s8, v9 bitop3:0xde
	s_mov_b32 s8, 0x14000
	v_bitop3_b32 v12, v8, s8, v9 bitop3:0xde
	s_mov_b32 s8, 0x18000
	v_bitop3_b32 v13, v8, s8, v9 bitop3:0xde
	s_mov_b32 s8, 0x1c000
	v_ashrrev_i32_e32 v2, 8, v0
	v_lshrrev_b32_e32 v5, 2, v0
	v_bitop3_b32 v8, v8, s8, v9 bitop3:0xde
	s_add_i32 s8, s10, -1
	s_mov_b32 s9, s35
	v_lshlrev_b32_e32 v11, 6, v2
	s_lshl_b64 s[40:41], s[8:9], 7
	s_movk_i32 s8, 0x100
	v_and_b32_e32 v14, 1, v0
	v_and_b32_e32 v5, 12, v5
	v_cmp_gt_u32_e64 s[8:9], s8, v0
	v_or3_b32 v148, v11, v5, v14
	v_and_b32_e32 v5, 14, v0
	v_lshlrev_b32_e32 v0, 6, v0
	v_and_b32_e32 v3, 3, v1
	v_and_b32_e32 v0, 0x3c0, v0
	v_lshlrev_b32_e32 v1, 5, v1
	v_cmp_eq_u32_e64 s[6:7], 1, v2
	v_bitop3_b32 v4, v4, v9, v7 bitop3:0x36
	v_lshlrev_b32_e32 v2, 13, v2
	v_bitop3_b32 v0, v0, v9, v7 bitop3:0x36
	v_add3_u32 v1, v17, v18, v1
	v_lshlrev_b32_e32 v9, 6, v16
	v_lshlrev_b32_e32 v6, 12, v3
	v_lshl_or_b32 v149, v3, 5, v5
	v_or_b32_e32 v3, 0x800, v2
	v_or_b32_e32 v5, 0x1000, v2
	v_or_b32_e32 v7, 0x1800, v2
	v_sub_u32_e32 v1, v1, v9
	s_add_i32 s87, s10, -2
	v_cmp_eq_u32_e64 s[10:11], 0, v14
	v_lshlrev_b32_e32 v132, 1, v1
	v_mov_b32_e32 v133, v129
	s_mul_i32 s18, s36, 0x180
	v_add_u32_e32 v150, v10, v6
	v_add_u32_e32 v151, v4, v2
	v_add_u32_e32 v152, v0, v3
	v_add_u32_e32 v153, v0, v5
	v_add_u32_e32 v154, v0, v7
	v_add_u32_e32 v155, v12, v6
	v_add_u32_e32 v156, v13, v6
	v_add_u32_e32 v157, v8, v6
	s_waitcnt vmcnt(0)
	v_mov_b32_e32 v250, 0x3020706
	v_mov_b32_e32 v251, 0x5040100
	v_cndmask_b32_e64 v250, v250, v251, s[10:11]
	s_branch .LBB0_132

.LBB0_131:
	v_or_b32_e32 v158, s80, v149
	v_add_lshl_u32 v159, v148, s19, 11
	v_lshl_add_u32 v158, v158, 1, v159
	v_cvt_pk_bf16_f32 v159, v124, v125
	s_nop 1
	v_mov_b32_dpp v160, v159 quad_perm:[1,0,3,2] row_mask:0xf bank_mask:0xf
	v_perm_b32 v124, v160, v159, v250
	global_store_dword v158, v124, s[12:13]
	v_cvt_pk_bf16_f32 v124, v126, v127
	s_nop 1
	v_mov_b32_dpp v125, v124 quad_perm:[1,0,3,2] row_mask:0xf bank_mask:0xf
	v_perm_b32 v124, v125, v124, v250
	v_add_u32_e32 v125, 0x1000, v158
	global_store_dword v125, v124, s[12:13]
	v_cndmask_b32_e64 v125, v116, v117, s[10:11]
	v_mov_b32_e32 v126, v129
	v_or_b32_e32 v124, 32, v158
	s_nop 0
	v_mov_b32_dpp v126, v125 quad_perm:[1,0,3,2] row_mask:0xf bank_mask:0xf
	v_cndmask_b32_e64 v116, v126, v116, s[10:11]
	v_cndmask_b32_e64 v117, v117, v126, s[10:11]
	v_cvt_pk_bf16_f32 v116, v116, v117
	global_store_dword v124, v116, s[12:13]
	v_cvt_pk_bf16_f32 v116, v118, v119
	s_nop 1
	v_mov_b32_dpp v117, v116 quad_perm:[1,0,3,2] row_mask:0xf bank_mask:0xf
	v_perm_b32 v116, v117, v116, v250
	v_add_u32_e32 v117, 0x1020, v158
	global_store_dword v117, v116, s[12:13]
	v_cndmask_b32_e64 v117, v120, v121, s[10:11]
	v_mov_b32_e32 v118, v129
	v_or_b32_e32 v116, 0x100, v158
	s_nop 0
	v_mov_b32_dpp v118, v117 quad_perm:[1,0,3,2] row_mask:0xf bank_mask:0xf
	v_cndmask_b32_e64 v117, v118, v120, s[10:11]
	v_cndmask_b32_e64 v118, v121, v118, s[10:11]
	v_cvt_pk_bf16_f32 v117, v117, v118
	global_store_dword v116, v117, s[12:13]
	v_cndmask_b32_e64 v116, v122, v123, s[10:11]
	v_mov_b32_e32 v117, v129
	v_mov_b32_e32 v118, v129
	s_nop 0
	v_mov_b32_dpp v117, v116 quad_perm:[1,0,3,2] row_mask:0xf bank_mask:0xf
	v_cndmask_b32_e64 v116, v117, v122, s[10:11]
	v_cndmask_b32_e64 v117, v123, v117, s[10:11]
	v_cvt_pk_bf16_f32 v116, v116, v117
	v_add_u32_e32 v117, 0x1100, v158
	global_store_dword v117, v116, s[12:13]
	v_cndmask_b32_e64 v117, v112, v113, s[10:11]
	v_or_b32_e32 v116, 0x120, v158
	s_nop 0
	v_mov_b32_dpp v118, v117 quad_perm:[1,0,3,2] row_mask:0xf bank_mask:0xf
	v_cndmask_b32_e64 v112, v118, v112, s[10:11]
	v_cndmask_b32_e64 v113, v113, v118, s[10:11]
	v_cvt_pk_bf16_f32 v112, v112, v113
	global_store_dword v116, v112, s[12:13]
	v_cvt_pk_bf16_f32 v112, v114, v115
	s_nop 1
	v_mov_b32_dpp v113, v112 quad_perm:[1,0,3,2] row_mask:0xf bank_mask:0xf
	v_perm_b32 v112, v113, v112, v250
	v_add_u32_e32 v113, 0x1120, v158
	global_store_dword v113, v112, s[12:13]
	v_cvt_pk_bf16_f32 v112, v108, v109
	s_nop 1
	v_mov_b32_dpp v113, v112 quad_perm:[1,0,3,2] row_mask:0xf bank_mask:0xf
	v_perm_b32 v108, v113, v112, v250
	v_add_u32_e32 v109, 0x8000, v158
	global_store_dword v109, v108, s[12:13]
	v_cvt_pk_bf16_f32 v108, v110, v111
	s_nop 1
	v_mov_b32_dpp v109, v108 quad_perm:[1,0,3,2] row_mask:0xf bank_mask:0xf
	v_perm_b32 v108, v109, v108, v250
	v_add_u32_e32 v109, 0x9000, v158
	global_store_dword v109, v108, s[12:13]
	v_cvt_pk_bf16_f32 v108, v100, v101
	s_nop 1
	v_mov_b32_dpp v109, v108 quad_perm:[1,0,3,2] row_mask:0xf bank_mask:0xf
	v_perm_b32 v100, v109, v108, v250
	v_add_u32_e32 v101, 0x8020, v158
	global_store_dword v101, v100, s[12:13]
	v_cvt_pk_bf16_f32 v100, v102, v103
	s_nop 1
	v_mov_b32_dpp v101, v100 quad_perm:[1,0,3,2] row_mask:0xf bank_mask:0xf
	v_perm_b32 v100, v101, v100, v250
	v_add_u32_e32 v101, 0x9020, v158
	global_store_dword v101, v100, s[12:13]
	v_cvt_pk_bf16_f32 v100, v104, v105
	s_nop 1
	v_mov_b32_dpp v101, v100 quad_perm:[1,0,3,2] row_mask:0xf bank_mask:0xf
	v_perm_b32 v100, v101, v100, v250
	v_add_u32_e32 v101, 0x8100, v158
	global_store_dword v101, v100, s[12:13]
	v_cvt_pk_bf16_f32 v100, v106, v107
	s_nop 1
	v_mov_b32_dpp v101, v100 quad_perm:[1,0,3,2] row_mask:0xf bank_mask:0xf
	v_perm_b32 v100, v101, v100, v250
	v_add_u32_e32 v101, 0x9100, v158
	global_store_dword v101, v100, s[12:13]
	v_cvt_pk_bf16_f32 v100, v96, v97
	s_nop 1
	v_mov_b32_dpp v101, v100 quad_perm:[1,0,3,2] row_mask:0xf bank_mask:0xf
	v_perm_b32 v96, v101, v100, v250
	v_add_u32_e32 v97, 0x8120, v158
	global_store_dword v97, v96, s[12:13]
	v_cvt_pk_bf16_f32 v96, v98, v99
	s_nop 1
	v_mov_b32_dpp v97, v96 quad_perm:[1,0,3,2] row_mask:0xf bank_mask:0xf
	v_perm_b32 v96, v97, v96, v250
	v_add_u32_e32 v97, 0x9120, v158
	global_store_dword v97, v96, s[12:13]
	v_cvt_pk_bf16_f32 v96, v92, v93
	s_nop 1
	v_mov_b32_dpp v97, v96 quad_perm:[1,0,3,2] row_mask:0xf bank_mask:0xf
	v_perm_b32 v92, v97, v96, v250
	v_add_u32_e32 v93, 0x10000, v158
	global_store_dword v93, v92, s[12:13]
	v_cvt_pk_bf16_f32 v92, v94, v95
	s_nop 1
	v_mov_b32_dpp v93, v92 quad_perm:[1,0,3,2] row_mask:0xf bank_mask:0xf
	v_perm_b32 v92, v93, v92, v250
	v_add_u32_e32 v93, 0x11000, v158
	global_store_dword v93, v92, s[12:13]
	v_cvt_pk_bf16_f32 v92, v84, v85
	s_nop 1
	v_mov_b32_dpp v93, v92 quad_perm:[1,0,3,2] row_mask:0xf bank_mask:0xf
	v_perm_b32 v84, v93, v92, v250
	v_add_u32_e32 v85, 0x10020, v158
	global_store_dword v85, v84, s[12:13]
	v_cvt_pk_bf16_f32 v84, v86, v87
	s_nop 1
	v_mov_b32_dpp v85, v84 quad_perm:[1,0,3,2] row_mask:0xf bank_mask:0xf
	v_perm_b32 v84, v85, v84, v250
	v_add_u32_e32 v85, 0x11020, v158
	global_store_dword v85, v84, s[12:13]
	v_cvt_pk_bf16_f32 v84, v88, v89
	s_nop 1
	v_mov_b32_dpp v85, v84 quad_perm:[1,0,3,2] row_mask:0xf bank_mask:0xf
	v_perm_b32 v84, v85, v84, v250
	v_add_u32_e32 v85, 0x10100, v158
	global_store_dword v85, v84, s[12:13]
	v_cvt_pk_bf16_f32 v84, v90, v91
	s_nop 1
	v_mov_b32_dpp v85, v84 quad_perm:[1,0,3,2] row_mask:0xf bank_mask:0xf
	v_perm_b32 v84, v85, v84, v250
	v_add_u32_e32 v85, 0x11100, v158
	global_store_dword v85, v84, s[12:13]
	v_cvt_pk_bf16_f32 v84, v80, v81
	s_nop 1
	v_mov_b32_dpp v85, v84 quad_perm:[1,0,3,2] row_mask:0xf bank_mask:0xf
	v_perm_b32 v80, v85, v84, v250
	v_add_u32_e32 v81, 0x10120, v158
	global_store_dword v81, v80, s[12:13]
	v_cvt_pk_bf16_f32 v80, v82, v83
	s_nop 1
	v_mov_b32_dpp v81, v80 quad_perm:[1,0,3,2] row_mask:0xf bank_mask:0xf
	v_perm_b32 v80, v81, v80, v250
	v_add_u32_e32 v81, 0x11120, v158
	global_store_dword v81, v80, s[12:13]
	v_cvt_pk_bf16_f32 v80, v76, v77
	s_nop 1
	v_mov_b32_dpp v81, v80 quad_perm:[1,0,3,2] row_mask:0xf bank_mask:0xf
	v_perm_b32 v76, v81, v80, v250
	v_add_u32_e32 v77, 0x18000, v158
	global_store_dword v77, v76, s[12:13]
	v_cvt_pk_bf16_f32 v76, v78, v79
	s_nop 1
	v_mov_b32_dpp v77, v76 quad_perm:[1,0,3,2] row_mask:0xf bank_mask:0xf
	v_perm_b32 v76, v77, v76, v250
	v_add_u32_e32 v77, 0x19000, v158
	global_store_dword v77, v76, s[12:13]
	v_cvt_pk_bf16_f32 v76, v68, v69
	s_nop 1
	v_mov_b32_dpp v77, v76 quad_perm:[1,0,3,2] row_mask:0xf bank_mask:0xf
	v_perm_b32 v68, v77, v76, v250
	v_add_u32_e32 v69, 0x18020, v158
	global_store_dword v69, v68, s[12:13]
	v_cvt_pk_bf16_f32 v68, v70, v71
	s_nop 1
	v_mov_b32_dpp v69, v68 quad_perm:[1,0,3,2] row_mask:0xf bank_mask:0xf
	v_perm_b32 v68, v69, v68, v250
	v_add_u32_e32 v69, 0x19020, v158
	global_store_dword v69, v68, s[12:13]
	v_cvt_pk_bf16_f32 v68, v72, v73
	s_nop 1
	v_mov_b32_dpp v69, v68 quad_perm:[1,0,3,2] row_mask:0xf bank_mask:0xf
	v_perm_b32 v68, v69, v68, v250
	v_add_u32_e32 v69, 0x18100, v158
	global_store_dword v69, v68, s[12:13]
	v_cvt_pk_bf16_f32 v68, v74, v75
	s_nop 1
	v_mov_b32_dpp v69, v68 quad_perm:[1,0,3,2] row_mask:0xf bank_mask:0xf
	v_perm_b32 v68, v69, v68, v250
	v_add_u32_e32 v69, 0x19100, v158
	global_store_dword v69, v68, s[12:13]
	v_cvt_pk_bf16_f32 v68, v64, v65
	s_nop 1
	v_mov_b32_dpp v69, v68 quad_perm:[1,0,3,2] row_mask:0xf bank_mask:0xf
	v_perm_b32 v64, v69, v68, v250
	v_add_u32_e32 v65, 0x18120, v158
	global_store_dword v65, v64, s[12:13]
	v_cvt_pk_bf16_f32 v64, v66, v67
	s_nop 1
	v_mov_b32_dpp v65, v64 quad_perm:[1,0,3,2] row_mask:0xf bank_mask:0xf
	v_perm_b32 v64, v65, v64, v250
	v_add_u32_e32 v65, 0x19120, v158
	global_store_dword v65, v64, s[12:13]
	v_cvt_pk_bf16_f32 v64, v60, v61
	s_nop 1
	v_mov_b32_dpp v65, v64 quad_perm:[1,0,3,2] row_mask:0xf bank_mask:0xf
	v_perm_b32 v60, v65, v64, v250
	v_add_u32_e32 v61, 0x40000, v158
	global_store_dword v61, v60, s[12:13]
	v_cvt_pk_bf16_f32 v60, v62, v63
	s_nop 1
	v_mov_b32_dpp v61, v60 quad_perm:[1,0,3,2] row_mask:0xf bank_mask:0xf
	v_perm_b32 v60, v61, v60, v250
	v_add_u32_e32 v61, 0x41000, v158
	global_store_dword v61, v60, s[12:13]
	v_cvt_pk_bf16_f32 v60, v52, v53
	s_nop 1
	v_mov_b32_dpp v61, v60 quad_perm:[1,0,3,2] row_mask:0xf bank_mask:0xf
	v_perm_b32 v52, v61, v60, v250
	v_add_u32_e32 v53, 0x40020, v158
	global_store_dword v53, v52, s[12:13]
	v_cvt_pk_bf16_f32 v52, v54, v55
	s_nop 1
	v_mov_b32_dpp v53, v52 quad_perm:[1,0,3,2] row_mask:0xf bank_mask:0xf
	v_perm_b32 v52, v53, v52, v250
	v_add_u32_e32 v53, 0x41020, v158
	global_store_dword v53, v52, s[12:13]
	v_cvt_pk_bf16_f32 v52, v56, v57
	s_nop 1
	v_mov_b32_dpp v53, v52 quad_perm:[1,0,3,2] row_mask:0xf bank_mask:0xf
	v_perm_b32 v52, v53, v52, v250
	v_add_u32_e32 v53, 0x40100, v158
	global_store_dword v53, v52, s[12:13]
	v_cvt_pk_bf16_f32 v52, v58, v59
	s_nop 1
	v_mov_b32_dpp v53, v52 quad_perm:[1,0,3,2] row_mask:0xf bank_mask:0xf
	v_perm_b32 v52, v53, v52, v250
	v_add_u32_e32 v53, 0x41100, v158
	global_store_dword v53, v52, s[12:13]
	v_cvt_pk_bf16_f32 v52, v48, v49
	s_nop 1
	v_mov_b32_dpp v53, v52 quad_perm:[1,0,3,2] row_mask:0xf bank_mask:0xf
	v_perm_b32 v48, v53, v52, v250
	v_add_u32_e32 v49, 0x40120, v158
	global_store_dword v49, v48, s[12:13]
	v_cvt_pk_bf16_f32 v48, v50, v51
	s_nop 1
	v_mov_b32_dpp v49, v48 quad_perm:[1,0,3,2] row_mask:0xf bank_mask:0xf
	v_perm_b32 v48, v49, v48, v250
	v_add_u32_e32 v49, 0x41120, v158
	global_store_dword v49, v48, s[12:13]
	v_cvt_pk_bf16_f32 v48, v44, v45
	s_nop 1
	v_mov_b32_dpp v49, v48 quad_perm:[1,0,3,2] row_mask:0xf bank_mask:0xf
	v_perm_b32 v44, v49, v48, v250
	v_add_u32_e32 v45, 0x48000, v158
	global_store_dword v45, v44, s[12:13]
	v_cvt_pk_bf16_f32 v44, v46, v47
	s_nop 1
	v_mov_b32_dpp v45, v44 quad_perm:[1,0,3,2] row_mask:0xf bank_mask:0xf
	v_perm_b32 v44, v45, v44, v250
	v_add_u32_e32 v45, 0x49000, v158
	global_store_dword v45, v44, s[12:13]
	v_cvt_pk_bf16_f32 v44, v36, v37
	s_nop 1
	v_mov_b32_dpp v45, v44 quad_perm:[1,0,3,2] row_mask:0xf bank_mask:0xf
	v_perm_b32 v36, v45, v44, v250
	v_add_u32_e32 v37, 0x48020, v158
	global_store_dword v37, v36, s[12:13]
	v_cvt_pk_bf16_f32 v36, v38, v39
	s_nop 1
	v_mov_b32_dpp v37, v36 quad_perm:[1,0,3,2] row_mask:0xf bank_mask:0xf
	v_perm_b32 v36, v37, v36, v250
	v_add_u32_e32 v37, 0x49020, v158
	global_store_dword v37, v36, s[12:13]
	v_cvt_pk_bf16_f32 v36, v40, v41
	s_nop 1
	v_mov_b32_dpp v37, v36 quad_perm:[1,0,3,2] row_mask:0xf bank_mask:0xf
	v_perm_b32 v36, v37, v36, v250
	v_add_u32_e32 v37, 0x48100, v158
	global_store_dword v37, v36, s[12:13]
	v_cvt_pk_bf16_f32 v36, v42, v43
	s_nop 1
	v_mov_b32_dpp v37, v36 quad_perm:[1,0,3,2] row_mask:0xf bank_mask:0xf
	v_perm_b32 v36, v37, v36, v250
	v_add_u32_e32 v37, 0x49100, v158
	global_store_dword v37, v36, s[12:13]
	v_cvt_pk_bf16_f32 v36, v32, v33
	s_nop 1
	v_mov_b32_dpp v37, v36 quad_perm:[1,0,3,2] row_mask:0xf bank_mask:0xf
	v_perm_b32 v32, v37, v36, v250
	v_add_u32_e32 v33, 0x48120, v158
	global_store_dword v33, v32, s[12:13]
	v_cvt_pk_bf16_f32 v32, v34, v35
	s_nop 1
	v_mov_b32_dpp v33, v32 quad_perm:[1,0,3,2] row_mask:0xf bank_mask:0xf
	v_perm_b32 v32, v33, v32, v250
	v_add_u32_e32 v33, 0x49120, v158
	global_store_dword v33, v32, s[12:13]
	v_cvt_pk_bf16_f32 v32, v28, v29
	s_nop 1
	v_mov_b32_dpp v33, v32 quad_perm:[1,0,3,2] row_mask:0xf bank_mask:0xf
	v_perm_b32 v28, v33, v32, v250
	v_add_u32_e32 v29, 0x50000, v158
	global_store_dword v29, v28, s[12:13]
	v_cvt_pk_bf16_f32 v28, v30, v31
	s_nop 1
	v_mov_b32_dpp v29, v28 quad_perm:[1,0,3,2] row_mask:0xf bank_mask:0xf
	v_perm_b32 v28, v29, v28, v250
	v_add_u32_e32 v29, 0x51000, v158
	global_store_dword v29, v28, s[12:13]
	v_cvt_pk_bf16_f32 v28, v20, v21
	s_nop 1
	v_mov_b32_dpp v29, v28 quad_perm:[1,0,3,2] row_mask:0xf bank_mask:0xf
	v_perm_b32 v20, v29, v28, v250
	v_add_u32_e32 v21, 0x50020, v158
	global_store_dword v21, v20, s[12:13]
	v_cvt_pk_bf16_f32 v20, v22, v23
	s_nop 1
	v_mov_b32_dpp v21, v20 quad_perm:[1,0,3,2] row_mask:0xf bank_mask:0xf
	v_perm_b32 v20, v21, v20, v250
	v_add_u32_e32 v21, 0x51020, v158
	global_store_dword v21, v20, s[12:13]
	v_cvt_pk_bf16_f32 v20, v24, v25
	s_nop 1
	v_mov_b32_dpp v21, v20 quad_perm:[1,0,3,2] row_mask:0xf bank_mask:0xf
	v_perm_b32 v20, v21, v20, v250
	v_add_u32_e32 v21, 0x50100, v158
	global_store_dword v21, v20, s[12:13]
	v_cvt_pk_bf16_f32 v20, v26, v27
	s_nop 1
	v_mov_b32_dpp v21, v20 quad_perm:[1,0,3,2] row_mask:0xf bank_mask:0xf
	v_perm_b32 v20, v21, v20, v250
	v_add_u32_e32 v21, 0x51100, v158
	global_store_dword v21, v20, s[12:13]
	v_cvt_pk_bf16_f32 v20, v16, v17
	s_nop 1
	v_mov_b32_dpp v21, v20 quad_perm:[1,0,3,2] row_mask:0xf bank_mask:0xf
	v_perm_b32 v16, v21, v20, v250
	v_add_u32_e32 v17, 0x50120, v158
	global_store_dword v17, v16, s[12:13]
	v_cvt_pk_bf16_f32 v16, v18, v19
	s_nop 1
	v_mov_b32_dpp v17, v16 quad_perm:[1,0,3,2] row_mask:0xf bank_mask:0xf
	v_perm_b32 v16, v17, v16, v250
	v_add_u32_e32 v17, 0x51120, v158
	global_store_dword v17, v16, s[12:13]
	v_cvt_pk_bf16_f32 v16, v12, v13
	s_nop 1
	v_mov_b32_dpp v17, v16 quad_perm:[1,0,3,2] row_mask:0xf bank_mask:0xf
	v_perm_b32 v12, v17, v16, v250
	v_add_u32_e32 v13, 0x58000, v158
	global_store_dword v13, v12, s[12:13]
	v_cvt_pk_bf16_f32 v12, v14, v15
	s_nop 1
	v_mov_b32_dpp v13, v12 quad_perm:[1,0,3,2] row_mask:0xf bank_mask:0xf
	v_perm_b32 v12, v13, v12, v250
	v_add_u32_e32 v13, 0x59000, v158
	global_store_dword v13, v12, s[12:13]
	v_cvt_pk_bf16_f32 v12, v4, v5
	s_nop 1
	v_mov_b32_dpp v13, v12 quad_perm:[1,0,3,2] row_mask:0xf bank_mask:0xf
	v_perm_b32 v4, v13, v12, v250
	v_add_u32_e32 v5, 0x58020, v158
	global_store_dword v5, v4, s[12:13]
	v_cvt_pk_bf16_f32 v4, v6, v7
	s_nop 1
	v_mov_b32_dpp v5, v4 quad_perm:[1,0,3,2] row_mask:0xf bank_mask:0xf
	v_perm_b32 v4, v5, v4, v250
	v_add_u32_e32 v5, 0x59020, v158
	global_store_dword v5, v4, s[12:13]
	v_cvt_pk_bf16_f32 v4, v8, v9
	s_nop 1
	v_mov_b32_dpp v5, v4 quad_perm:[1,0,3,2] row_mask:0xf bank_mask:0xf
	v_perm_b32 v4, v5, v4, v250
	v_add_u32_e32 v5, 0x58100, v158
	global_store_dword v5, v4, s[12:13]
	v_cvt_pk_bf16_f32 v4, v10, v11
	s_nop 1
	v_mov_b32_dpp v5, v4 quad_perm:[1,0,3,2] row_mask:0xf bank_mask:0xf
	v_perm_b32 v4, v5, v4, v250
	v_add_u32_e32 v5, 0x59100, v158
	global_store_dword v5, v4, s[12:13]
	v_cvt_pk_bf16_f32 v4, v0, v1
	s_nop 1
	v_mov_b32_dpp v5, v4 quad_perm:[1,0,3,2] row_mask:0xf bank_mask:0xf
	v_perm_b32 v0, v5, v4, v250
	v_add_u32_e32 v1, 0x58120, v158
	global_store_dword v1, v0, s[12:13]
	v_cvt_pk_bf16_f32 v0, v2, v3
	s_nop 1
	v_mov_b32_dpp v1, v0 quad_perm:[1,0,3,2] row_mask:0xf bank_mask:0xf
	v_perm_b32 v0, v1, v0, v250
	v_add_u32_e32 v1, 0x59120, v158
	global_store_dword v1, v0, s[12:13]
	s_and_b64 vcc, exec, s[22:23]
	s_mov_b32 s19, s42
	s_mov_b32 s80, s43
	s_cbranch_vccnz .LBB0_143

.LBB0_1534:
	v_readlane_b32 s10, v255, 20
	v_readlane_b32 s11, v255, 21
	s_lshl_b64 s[2:3], s[10:11], 23
	s_add_u32 s19, s26, s2
	s_addc_u32 s37, s27, s3
	s_add_u32 s2, s26, 0x3c00000
	s_addc_u32 s3, s27, 0
	s_lshl_b32 s10, s10, 12
	s_ashr_i32 s11, s10, 31
	s_lshl_b64 s[10:11], s[10:11], 2
	s_waitcnt lgkmcnt(0)
	s_add_u32 s12, s6, s10
	s_addc_u32 s13, s7, s11
	s_add_i32 s6, s8, s9
	s_ashr_i32 s7, s6, 31
	s_lshr_b32 s7, s7, 25
	s_add_i32 s7, s6, s7
	s_and_b32 s8, s7, 0xff80
	s_sub_i32 s6, s6, s8
	s_bfe_i32 s8, s6, 0x80000
	s_bfe_u32 s8, s8, 0x3000c
	s_add_i32 s8, s6, s8
	s_bfe_i32 s9, s8, 0x80000
	s_and_b32 s8, s8, 0xf8
	s_sub_i32 s6, s6, s8
	s_sext_i32_i8 s6, s6
	s_lshl_b32 s7, s7, 4
	s_sext_i32_i16 s9, s9
	s_and_b32 s7, s7, 0xfffff800
	s_lshl_b32 s6, s6, 8
	v_ashrrev_i32_e32 v1, 6, v0
	v_lshlrev_b32_e32 v2, 4, v0
	v_lshrrev_b32_e32 v3, 31, v0
	s_add_i32 s38, s6, s7
	s_lshl_b32 s6, s9, 5
	v_add_u32_e32 v3, v1, v3
	v_and_b32_e32 v10, 48, v2
	v_lshlrev_b32_e32 v2, 9, v0
	s_and_b32 s40, s6, 0xffffff00
	v_ashrrev_i32_e32 v9, 1, v3
	v_and_b32_e32 v3, 0x3fffffe, v3
	v_and_b32_e32 v11, 0x7800, v2
	s_ashr_i32 s39, s38, 31
	s_ashr_i32 s41, s40, 31
	v_lshlrev_b32_e32 v135, 10, v1
	v_sub_u32_e32 v3, v1, v3
	v_lshl_or_b32 v2, v9, 15, v11
	s_lshl_b64 s[6:7], s[38:39], 11
	s_lshl_b64 s[8:9], s[40:41], 11
	v_and_b32_e32 v8, 32, v0
	v_lshl_add_u32 v2, v3, 6, v2
	s_add_u32 s14, s19, s8
	v_add_u32_e32 v137, 0x10000, v135
	v_bitop3_b32 v128, v2, v10, v8 bitop3:0xf6
	s_addc_u32 s15, s37, s9
	v_readfirstlane_b32 s8, v137
	v_add_u32_e32 v139, 0x12000, v135
	v_lshl_add_u64 v[2:3], s[14:15], 0, v[128:129]
	s_mov_b32 m0, s8
	s_mov_b64 s[10:11], 0x20000
	v_readfirstlane_b32 s8, v139
	s_add_u32 s22, s16, s6
	global_load_lds_dwordx4 v128, s[14:15]
	v_lshl_add_u64 v[4:5], v[2:3], 0, s[10:11]
	s_mov_b32 m0, s8
	s_addc_u32 s23, s17, s7
	v_readfirstlane_b32 s6, v135
	v_add_u32_e32 v141, 0x2000, v135
	global_load_lds_dwordx4 v[4:5], off
	v_lshl_add_u64 v[4:5], s[22:23], 0, v[128:129]
	s_mov_b32 m0, s6
	v_readfirstlane_b32 s6, v141
	v_add_u32_e32 v142, 0x14000, v135
	global_load_lds_dwordx4 v128, s[22:23]
	v_lshl_add_u64 v[6:7], v[4:5], 0, s[10:11]
	s_mov_b32 m0, s6
	s_mov_b64 s[8:9], 0x40000
	v_readfirstlane_b32 s6, v142
	v_add_u32_e32 v143, 0x16000, v135
	global_load_lds_dwordx4 v[6:7], off
	v_lshl_add_u64 v[6:7], v[2:3], 0, s[8:9]
	s_mov_b32 m0, s6
	s_mov_b64 s[10:11], 0x60000
	v_readfirstlane_b32 s6, v143
	v_add_u32_e32 v144, 0x4000, v135
	global_load_lds_dwordx4 v[6:7], off
	v_lshl_add_u64 v[6:7], v[2:3], 0, s[10:11]
	s_mov_b32 m0, s6
	v_readfirstlane_b32 s6, v144
	v_add_u32_e32 v145, 0x6000, v135
	global_load_lds_dwordx4 v[6:7], off
	v_lshl_add_u64 v[6:7], v[4:5], 0, s[8:9]
	s_mov_b32 m0, s6
	v_readfirstlane_b32 s6, v145
	v_add_u32_e32 v146, 0x18000, v135
	global_load_lds_dwordx4 v[6:7], off
	v_lshl_add_u64 v[6:7], v[4:5], 0, s[10:11]
	s_mov_b32 m0, s6
	v_readfirstlane_b32 s6, v146
	v_add_u32_e32 v147, 0x1a000, v135
	global_load_lds_dwordx4 v[6:7], off
	v_lshl_add_u64 v[6:7], v[2:3], 0, s[44:45]
	s_mov_b32 m0, s6
	s_mov_b64 s[8:9], 0x20080
	v_readfirstlane_b32 s6, v147
	v_add_u32_e32 v148, 0x8000, v135
	global_load_lds_dwordx4 v[6:7], off
	v_lshl_add_u64 v[6:7], v[2:3], 0, s[8:9]
	s_mov_b32 m0, s6
	v_readfirstlane_b32 s6, v148
	v_add_u32_e32 v149, 0xa000, v135
	global_load_lds_dwordx4 v[6:7], off
	v_lshl_add_u64 v[6:7], v[4:5], 0, s[44:45]
	s_mov_b32 m0, s6
	v_readfirstlane_b32 s6, v149
	v_add_u32_e32 v150, 0x1c000, v135
	global_load_lds_dwordx4 v[6:7], off
	v_lshl_add_u64 v[4:5], v[4:5], 0, s[8:9]
	s_mov_b32 m0, s6
	v_readfirstlane_b32 s6, v150
	v_add_u32_e32 v151, 0x1e000, v135
	global_load_lds_dwordx4 v[4:5], off
	v_lshl_add_u64 v[4:5], v[2:3], 0, s[48:49]
	s_mov_b32 m0, s6
	v_readfirstlane_b32 s6, v151
	global_load_lds_dwordx4 v[4:5], off
	v_lshl_add_u64 v[2:3], v[2:3], 0, s[50:51]
	s_mov_b32 m0, s6
	v_and_b32_e32 v5, 48, v0
	global_load_lds_dwordx4 v[2:3], off
	v_and_b32_e32 v3, 15, v0
	v_lshlrev_b32_e32 v6, 6, v3
	v_lshlrev_b32_e32 v12, 2, v0
	v_or_b32_e32 v7, v6, v5
	v_and_b32_e32 v12, 32, v12
	s_mov_b32 s8, 0x10000
	v_and_b32_e32 v1, 3, v1
	v_bitop3_b32 v13, v7, s8, v12 bitop3:0xde
	s_mov_b32 s8, 0x14000
	v_ashrrev_i32_e32 v2, 8, v0
	v_lshlrev_b32_e32 v4, 12, v1
	v_bitop3_b32 v15, v7, s8, v12 bitop3:0xde
	s_mov_b32 s8, 0x18000
	v_lshlrev_b32_e32 v1, 5, v1
	v_cmp_eq_u32_e64 s[6:7], 1, v2
	v_lshlrev_b32_e32 v14, 6, v2
	v_bitop3_b32 v16, v7, s8, v12 bitop3:0xde
	s_mov_b32 s8, 0x1c000
	v_or_b32_e32 v152, v1, v3
	v_and_or_b32 v154, v0, 14, v1
	v_lshlrev_b32_e32 v1, 13, v2
	v_lshlrev_b32_e32 v2, 6, v0
	s_movk_i32 s18, 0x7f80
	v_bitop3_b32 v7, v7, s8, v12 bitop3:0xde
	s_movk_i32 s8, 0x100
	v_lshrrev_b32_e32 v18, 2, v0
	v_and_b32_e32 v2, 0x3c0, v2
	v_mul_lo_u32 v9, v9, s18
	v_bitop3_b32 v6, v6, v12, v5 bitop3:0x36
	v_cmp_gt_u32_e64 s[8:9], s8, v0
	v_and_b32_e32 v17, 1, v0
	v_and_b32_e32 v18, 12, v18
	v_bitop3_b32 v2, v2, v12, v5 bitop3:0x36
	v_or_b32_e32 v3, 0x800, v1
	v_or_b32_e32 v5, 0x1000, v1
	v_or_b32_e32 v12, 0x1800, v1
	v_bitop3_b32 v8, v10, v9, v8 bitop3:0xde
	v_and_b32_e32 v0, 0xffffffc0, v0
	v_or3_b32 v153, v14, v18, v17
	v_cmp_eq_u32_e64 s[10:11], 0, v17
	v_add3_u32 v132, v8, v11, v0
	v_mov_b32_e32 v133, v129
	v_add_u32_e32 v155, v13, v4
	v_add_u32_e32 v156, v6, v1
	v_add_u32_e32 v157, v2, v3
	v_add_u32_e32 v158, v2, v5
	v_add_u32_e32 v159, v2, v12
	v_add_u32_e32 v160, v15, v4
	v_add_u32_e32 v161, v16, v4
	v_add_u32_e32 v162, v7, v4
	s_waitcnt vmcnt(0)
	v_mov_b32_e32 v250, 0x3020706
	v_mov_b32_e32 v251, 0x5040100
	v_cndmask_b32_e64 v250, v250, v251, s[10:11]
	s_branch .LBB0_1537

.LBB0_1536:
	v_or_b32_e32 v164, s40, v152
	v_ashrrev_i32_e32 v165, 31, v164
	v_lshl_add_u64 v[164:165], v[164:165], 2, s[12:13]
	global_load_dword v140, v[164:165], off
	global_load_dword v138, v[164:165], off offset:64
	global_load_dword v136, v[164:165], off offset:512
	global_load_dword v134, v[164:165], off offset:576
	v_or_b32_e32 v163, s40, v154
	v_add_lshl_u32 v164, v153, s38, 13
	v_lshl_add_u32 v163, v163, 1, v164
	s_mov_b32 s18, 0xc0135761
	s_waitcnt vmcnt(0)
	v_pk_add_f32 v[164:165], v[124:125], v[140:141] op_sel_hi:[1,0]
	s_nop 0
	v_pk_mul_f32 v[166:167], v[164:165], v[164:165]
	v_mov_b64_e32 v[124:125], s[18:19]
	v_pk_fma_f32 v[166:167], v[166:167], s[88:89], v[124:125] op_sel_hi:[1,0,0] neg_lo:[1,0,0] neg_hi:[1,0,0]
	v_pk_add_f32 v[126:127], v[126:127], v[140:141] op_sel_hi:[1,0]
	v_pk_mul_f32 v[166:167], v[164:165], v[166:167]
	v_pk_add_f32 v[120:121], v[120:121], v[138:139] op_sel_hi:[1,0]
	v_exp_f32_e32 v166, v166
	v_exp_f32_e32 v167, v167
	v_pk_add_f32 v[116:117], v[116:117], v[136:137] op_sel_hi:[1,0]
	v_pk_add_f32 v[112:113], v[112:113], v[134:135] op_sel_hi:[1,0]
	v_pk_add_f32 v[166:167], v[166:167], 1.0 op_sel_hi:[1,0]
	s_nop 0
	v_rcp_f32_e32 v166, v166
	v_rcp_f32_e32 v167, v167
	s_nop 0
	v_pk_mul_f32 v[164:165], v[164:165], v[166:167]
	s_nop 0
	v_cvt_pk_bf16_f32 v166, v164, v165
	s_nop 1
	v_mov_b32_dpp v167, v166 quad_perm:[1,0,3,2] row_mask:0xf bank_mask:0xf
	v_perm_b32 v164, v167, v166, v250
	global_store_dword v163, v164, s[2:3]
	v_pk_mul_f32 v[164:165], v[126:127], v[126:127]
	s_nop 0
	v_pk_fma_f32 v[164:165], v[164:165], s[88:89], v[124:125] op_sel_hi:[1,0,0] neg_lo:[1,0,0] neg_hi:[1,0,0]
	s_nop 0
	v_pk_mul_f32 v[164:165], v[126:127], v[164:165]
	s_nop 0
	v_exp_f32_e32 v164, v164
	v_exp_f32_e32 v165, v165
	s_nop 0
	v_pk_add_f32 v[164:165], v[164:165], 1.0 op_sel_hi:[1,0]
	s_nop 0
	v_rcp_f32_e32 v164, v164
	v_rcp_f32_e32 v165, v165
	s_nop 0
	v_pk_mul_f32 v[126:127], v[126:127], v[164:165]
	s_nop 0
	v_cvt_pk_bf16_f32 v164, v126, v127
	s_nop 1
	v_mov_b32_dpp v165, v164 quad_perm:[1,0,3,2] row_mask:0xf bank_mask:0xf
	v_perm_b32 v126, v165, v164, v250
	v_add_u32_e32 v127, 0x4000, v163
	global_store_dword v127, v126, s[2:3]
	v_pk_mul_f32 v[126:127], v[120:121], v[120:121]
	v_or_b32_e32 v164, 32, v163
	v_pk_fma_f32 v[126:127], v[126:127], s[88:89], v[124:125] op_sel_hi:[1,0,0] neg_lo:[1,0,0] neg_hi:[1,0,0]
	s_nop 0
	v_pk_mul_f32 v[126:127], v[120:121], v[126:127]
	s_nop 0
	v_exp_f32_e32 v126, v126
	v_exp_f32_e32 v127, v127
	s_nop 0
	v_pk_add_f32 v[126:127], v[126:127], 1.0 op_sel_hi:[1,0]
	s_nop 0
	v_rcp_f32_e32 v126, v126
	v_rcp_f32_e32 v127, v127
	s_nop 0
	v_pk_mul_f32 v[120:121], v[120:121], v[126:127]
	s_nop 0
	v_cvt_pk_bf16_f32 v126, v120, v121
	s_nop 1
	v_mov_b32_dpp v127, v126 quad_perm:[1,0,3,2] row_mask:0xf bank_mask:0xf
	v_perm_b32 v120, v127, v126, v250
	global_store_dword v164, v120, s[2:3]
	v_pk_add_f32 v[120:121], v[122:123], v[138:139] op_sel_hi:[1,0]
	s_nop 0
	v_pk_mul_f32 v[122:123], v[120:121], v[120:121]
	s_nop 0
	v_pk_fma_f32 v[122:123], v[122:123], s[88:89], v[124:125] op_sel_hi:[1,0,0] neg_lo:[1,0,0] neg_hi:[1,0,0]
	s_nop 0
	v_pk_mul_f32 v[122:123], v[120:121], v[122:123]
	s_nop 0
	v_exp_f32_e32 v122, v122
	v_exp_f32_e32 v123, v123
	s_nop 0
	v_pk_add_f32 v[122:123], v[122:123], 1.0 op_sel_hi:[1,0]
	s_nop 0
	v_rcp_f32_e32 v122, v122
	v_rcp_f32_e32 v123, v123
	s_nop 0
	v_pk_mul_f32 v[120:121], v[120:121], v[122:123]
	s_nop 0
	v_cvt_pk_bf16_f32 v122, v120, v121
	s_nop 1
	v_mov_b32_dpp v123, v122 quad_perm:[1,0,3,2] row_mask:0xf bank_mask:0xf
	v_perm_b32 v120, v123, v122, v250
	v_add_u32_e32 v121, 0x4020, v163
	global_store_dword v121, v120, s[2:3]
	v_pk_mul_f32 v[120:121], v[116:117], v[116:117]
	v_or_b32_e32 v122, 0x100, v163
	v_pk_fma_f32 v[120:121], v[120:121], s[88:89], v[124:125] op_sel_hi:[1,0,0] neg_lo:[1,0,0] neg_hi:[1,0,0]
	s_nop 0
	v_pk_mul_f32 v[120:121], v[116:117], v[120:121]
	s_nop 0
	v_exp_f32_e32 v120, v120
	v_exp_f32_e32 v121, v121
	s_nop 0
	v_pk_add_f32 v[120:121], v[120:121], 1.0 op_sel_hi:[1,0]
	s_nop 0
	v_rcp_f32_e32 v120, v120
	v_rcp_f32_e32 v121, v121
	s_nop 0
	v_pk_mul_f32 v[116:117], v[116:117], v[120:121]
	s_nop 0
	v_cvt_pk_bf16_f32 v120, v116, v117
	s_nop 1
	v_mov_b32_dpp v121, v120 quad_perm:[1,0,3,2] row_mask:0xf bank_mask:0xf
	v_perm_b32 v116, v121, v120, v250
	global_store_dword v122, v116, s[2:3]
	v_pk_add_f32 v[116:117], v[118:119], v[136:137] op_sel_hi:[1,0]
	s_nop 0
	v_pk_mul_f32 v[118:119], v[116:117], v[116:117]
	s_nop 0
	v_pk_fma_f32 v[118:119], v[118:119], s[88:89], v[124:125] op_sel_hi:[1,0,0] neg_lo:[1,0,0] neg_hi:[1,0,0]
	s_nop 0
	v_pk_mul_f32 v[118:119], v[116:117], v[118:119]
	s_nop 0
	v_exp_f32_e32 v118, v118
	v_exp_f32_e32 v119, v119
	s_nop 0
	v_pk_add_f32 v[118:119], v[118:119], 1.0 op_sel_hi:[1,0]
	s_nop 0
	v_rcp_f32_e32 v118, v118
	v_rcp_f32_e32 v119, v119
	s_nop 0
	v_pk_mul_f32 v[116:117], v[116:117], v[118:119]
	s_nop 0
	v_cvt_pk_bf16_f32 v118, v116, v117
	s_nop 1
	v_mov_b32_dpp v119, v118 quad_perm:[1,0,3,2] row_mask:0xf bank_mask:0xf
	v_perm_b32 v116, v119, v118, v250
	v_add_u32_e32 v117, 0x4100, v163
	global_store_dword v117, v116, s[2:3]
	v_pk_mul_f32 v[116:117], v[112:113], v[112:113]
	v_or_b32_e32 v118, 0x120, v163
	v_pk_fma_f32 v[116:117], v[116:117], s[88:89], v[124:125] op_sel_hi:[1,0,0] neg_lo:[1,0,0] neg_hi:[1,0,0]
	s_nop 0
	v_pk_mul_f32 v[116:117], v[112:113], v[116:117]
	s_nop 0
	v_exp_f32_e32 v116, v116
	v_exp_f32_e32 v117, v117
	s_nop 0
	v_pk_add_f32 v[116:117], v[116:117], 1.0 op_sel_hi:[1,0]
	s_nop 0
	v_rcp_f32_e32 v116, v116
	v_rcp_f32_e32 v117, v117
	s_nop 0
	v_pk_mul_f32 v[112:113], v[112:113], v[116:117]
	s_nop 0
	v_cvt_pk_bf16_f32 v116, v112, v113
	s_nop 1
	v_mov_b32_dpp v117, v116 quad_perm:[1,0,3,2] row_mask:0xf bank_mask:0xf
	v_perm_b32 v112, v117, v116, v250
	global_store_dword v118, v112, s[2:3]
	v_pk_add_f32 v[112:113], v[114:115], v[134:135] op_sel_hi:[1,0]
	s_nop 0
	v_pk_mul_f32 v[114:115], v[112:113], v[112:113]
	s_nop 0
	v_pk_fma_f32 v[114:115], v[114:115], s[88:89], v[124:125] op_sel_hi:[1,0,0] neg_lo:[1,0,0] neg_hi:[1,0,0]
	s_nop 0
	v_pk_mul_f32 v[114:115], v[112:113], v[114:115]
	s_nop 0
	v_exp_f32_e32 v114, v114
	v_exp_f32_e32 v115, v115
	s_nop 0
	v_pk_add_f32 v[114:115], v[114:115], 1.0 op_sel_hi:[1,0]
	s_nop 0
	v_rcp_f32_e32 v114, v114
	v_rcp_f32_e32 v115, v115
	s_nop 0
	v_pk_mul_f32 v[112:113], v[112:113], v[114:115]
	s_nop 0
	v_cvt_pk_bf16_f32 v114, v112, v113
	s_nop 1
	v_mov_b32_dpp v115, v114 quad_perm:[1,0,3,2] row_mask:0xf bank_mask:0xf
	v_perm_b32 v112, v115, v114, v250
	v_add_u32_e32 v113, 0x4120, v163
	global_store_dword v113, v112, s[2:3]
	v_pk_add_f32 v[108:109], v[108:109], v[140:141] op_sel_hi:[1,0]
	v_pk_add_f32 v[104:105], v[104:105], v[138:139] op_sel_hi:[1,0]
	v_pk_mul_f32 v[112:113], v[108:109], v[108:109]
	v_pk_add_f32 v[100:101], v[100:101], v[136:137] op_sel_hi:[1,0]
	v_pk_fma_f32 v[112:113], v[112:113], s[88:89], v[124:125] op_sel_hi:[1,0,0] neg_lo:[1,0,0] neg_hi:[1,0,0]
	v_pk_add_f32 v[96:97], v[96:97], v[134:135] op_sel_hi:[1,0]
	v_pk_mul_f32 v[112:113], v[108:109], v[112:113]
	s_nop 0
	v_exp_f32_e32 v112, v112
	v_exp_f32_e32 v113, v113
	s_nop 0
	v_pk_add_f32 v[112:113], v[112:113], 1.0 op_sel_hi:[1,0]
	s_nop 0
	v_rcp_f32_e32 v112, v112
	v_rcp_f32_e32 v113, v113
	s_nop 0
	v_pk_mul_f32 v[108:109], v[108:109], v[112:113]
	s_nop 0
	v_cvt_pk_bf16_f32 v112, v108, v109
	s_nop 1
	v_mov_b32_dpp v113, v112 quad_perm:[1,0,3,2] row_mask:0xf bank_mask:0xf
	v_perm_b32 v108, v113, v112, v250
	v_add_u32_e32 v109, 0x20000, v163
	global_store_dword v109, v108, s[2:3]
	v_pk_add_f32 v[108:109], v[110:111], v[140:141] op_sel_hi:[1,0]
	s_nop 0
	v_pk_mul_f32 v[110:111], v[108:109], v[108:109]
	s_nop 0
	v_pk_fma_f32 v[110:111], v[110:111], s[88:89], v[124:125] op_sel_hi:[1,0,0] neg_lo:[1,0,0] neg_hi:[1,0,0]
	s_nop 0
	v_pk_mul_f32 v[110:111], v[108:109], v[110:111]
	s_nop 0
	v_exp_f32_e32 v110, v110
	v_exp_f32_e32 v111, v111
	s_nop 0
	v_pk_add_f32 v[110:111], v[110:111], 1.0 op_sel_hi:[1,0]
	s_nop 0
	v_rcp_f32_e32 v110, v110
	v_rcp_f32_e32 v111, v111
	s_nop 0
	v_pk_mul_f32 v[108:109], v[108:109], v[110:111]
	s_nop 0
	v_cvt_pk_bf16_f32 v110, v108, v109
	s_nop 1
	v_mov_b32_dpp v111, v110 quad_perm:[1,0,3,2] row_mask:0xf bank_mask:0xf
	v_perm_b32 v108, v111, v110, v250
	v_add_u32_e32 v109, 0x24000, v163
	global_store_dword v109, v108, s[2:3]
	v_pk_mul_f32 v[108:109], v[104:105], v[104:105]
	s_nop 0
	v_pk_fma_f32 v[108:109], v[108:109], s[88:89], v[124:125] op_sel_hi:[1,0,0] neg_lo:[1,0,0] neg_hi:[1,0,0]
	s_nop 0
	v_pk_mul_f32 v[108:109], v[104:105], v[108:109]
	s_nop 0
	v_exp_f32_e32 v108, v108
	v_exp_f32_e32 v109, v109
	s_nop 0
	v_pk_add_f32 v[108:109], v[108:109], 1.0 op_sel_hi:[1,0]
	s_nop 0
	v_rcp_f32_e32 v108, v108
	v_rcp_f32_e32 v109, v109
	s_nop 0
	v_pk_mul_f32 v[104:105], v[104:105], v[108:109]
	s_nop 0
	v_cvt_pk_bf16_f32 v108, v104, v105
	s_nop 1
	v_mov_b32_dpp v109, v108 quad_perm:[1,0,3,2] row_mask:0xf bank_mask:0xf
	v_perm_b32 v104, v109, v108, v250
	v_add_u32_e32 v105, 0x20020, v163
	global_store_dword v105, v104, s[2:3]
	v_pk_add_f32 v[104:105], v[106:107], v[138:139] op_sel_hi:[1,0]
	s_nop 0
	v_pk_mul_f32 v[106:107], v[104:105], v[104:105]
	s_nop 0
	v_pk_fma_f32 v[106:107], v[106:107], s[88:89], v[124:125] op_sel_hi:[1,0,0] neg_lo:[1,0,0] neg_hi:[1,0,0]
	s_nop 0
	v_pk_mul_f32 v[106:107], v[104:105], v[106:107]
	s_nop 0
	v_exp_f32_e32 v106, v106
	v_exp_f32_e32 v107, v107
	s_nop 0
	v_pk_add_f32 v[106:107], v[106:107], 1.0 op_sel_hi:[1,0]
	s_nop 0
	v_rcp_f32_e32 v106, v106
	v_rcp_f32_e32 v107, v107
	s_nop 0
	v_pk_mul_f32 v[104:105], v[104:105], v[106:107]
	s_nop 0
	v_cvt_pk_bf16_f32 v106, v104, v105
	s_nop 1
	v_mov_b32_dpp v107, v106 quad_perm:[1,0,3,2] row_mask:0xf bank_mask:0xf
	v_perm_b32 v104, v107, v106, v250
	v_add_u32_e32 v105, 0x24020, v163
	global_store_dword v105, v104, s[2:3]
	v_pk_mul_f32 v[104:105], v[100:101], v[100:101]
	s_nop 0
	v_pk_fma_f32 v[104:105], v[104:105], s[88:89], v[124:125] op_sel_hi:[1,0,0] neg_lo:[1,0,0] neg_hi:[1,0,0]
	s_nop 0
	v_pk_mul_f32 v[104:105], v[100:101], v[104:105]
	s_nop 0
	v_exp_f32_e32 v104, v104
	v_exp_f32_e32 v105, v105
	s_nop 0
	v_pk_add_f32 v[104:105], v[104:105], 1.0 op_sel_hi:[1,0]
	s_nop 0
	v_rcp_f32_e32 v104, v104
	v_rcp_f32_e32 v105, v105
	s_nop 0
	v_pk_mul_f32 v[100:101], v[100:101], v[104:105]
	s_nop 0
	v_cvt_pk_bf16_f32 v104, v100, v101
	s_nop 1
	v_mov_b32_dpp v105, v104 quad_perm:[1,0,3,2] row_mask:0xf bank_mask:0xf
	v_perm_b32 v100, v105, v104, v250
	v_add_u32_e32 v101, 0x20100, v163
	global_store_dword v101, v100, s[2:3]
	v_pk_add_f32 v[100:101], v[102:103], v[136:137] op_sel_hi:[1,0]
	s_nop 0
	v_pk_mul_f32 v[102:103], v[100:101], v[100:101]
	s_nop 0
	v_pk_fma_f32 v[102:103], v[102:103], s[88:89], v[124:125] op_sel_hi:[1,0,0] neg_lo:[1,0,0] neg_hi:[1,0,0]
	s_nop 0
	v_pk_mul_f32 v[102:103], v[100:101], v[102:103]
	s_nop 0
	v_exp_f32_e32 v102, v102
	v_exp_f32_e32 v103, v103
	s_nop 0
	v_pk_add_f32 v[102:103], v[102:103], 1.0 op_sel_hi:[1,0]
	s_nop 0
	v_rcp_f32_e32 v102, v102
	v_rcp_f32_e32 v103, v103
	s_nop 0
	v_pk_mul_f32 v[100:101], v[100:101], v[102:103]
	s_nop 0
	v_cvt_pk_bf16_f32 v102, v100, v101
	s_nop 1
	v_mov_b32_dpp v103, v102 quad_perm:[1,0,3,2] row_mask:0xf bank_mask:0xf
	v_perm_b32 v100, v103, v102, v250
	v_add_u32_e32 v101, 0x24100, v163
	global_store_dword v101, v100, s[2:3]
	v_pk_mul_f32 v[100:101], v[96:97], v[96:97]
	s_nop 0
	v_pk_fma_f32 v[100:101], v[100:101], s[88:89], v[124:125] op_sel_hi:[1,0,0] neg_lo:[1,0,0] neg_hi:[1,0,0]
	s_nop 0
	v_pk_mul_f32 v[100:101], v[96:97], v[100:101]
	s_nop 0
	v_exp_f32_e32 v100, v100
	v_exp_f32_e32 v101, v101
	s_nop 0
	v_pk_add_f32 v[100:101], v[100:101], 1.0 op_sel_hi:[1,0]
	s_nop 0
	v_rcp_f32_e32 v100, v100
	v_rcp_f32_e32 v101, v101
	s_nop 0
	v_pk_mul_f32 v[96:97], v[96:97], v[100:101]
	s_nop 0
	v_cvt_pk_bf16_f32 v100, v96, v97
	s_nop 1
	v_mov_b32_dpp v101, v100 quad_perm:[1,0,3,2] row_mask:0xf bank_mask:0xf
	v_perm_b32 v96, v101, v100, v250
	v_add_u32_e32 v97, 0x20120, v163
	global_store_dword v97, v96, s[2:3]
	v_pk_add_f32 v[96:97], v[98:99], v[134:135] op_sel_hi:[1,0]
	s_nop 0
	v_pk_mul_f32 v[98:99], v[96:97], v[96:97]
	s_nop 0
	v_pk_fma_f32 v[98:99], v[98:99], s[88:89], v[124:125] op_sel_hi:[1,0,0] neg_lo:[1,0,0] neg_hi:[1,0,0]
	s_nop 0
	v_pk_mul_f32 v[98:99], v[96:97], v[98:99]
	s_nop 0
	v_exp_f32_e32 v98, v98
	v_exp_f32_e32 v99, v99
	s_nop 0
	v_pk_add_f32 v[98:99], v[98:99], 1.0 op_sel_hi:[1,0]
	s_nop 0
	v_rcp_f32_e32 v98, v98
	v_rcp_f32_e32 v99, v99
	s_nop 0
	v_pk_mul_f32 v[96:97], v[96:97], v[98:99]
	s_nop 0
	v_cvt_pk_bf16_f32 v98, v96, v97
	s_nop 1
	v_mov_b32_dpp v99, v98 quad_perm:[1,0,3,2] row_mask:0xf bank_mask:0xf
	v_perm_b32 v96, v99, v98, v250
	v_add_u32_e32 v97, 0x24120, v163
	global_store_dword v97, v96, s[2:3]
	v_pk_add_f32 v[92:93], v[92:93], v[140:141] op_sel_hi:[1,0]
	v_pk_add_f32 v[88:89], v[88:89], v[138:139] op_sel_hi:[1,0]
	v_pk_mul_f32 v[96:97], v[92:93], v[92:93]
	v_pk_add_f32 v[84:85], v[84:85], v[136:137] op_sel_hi:[1,0]
	v_pk_fma_f32 v[96:97], v[96:97], s[88:89], v[124:125] op_sel_hi:[1,0,0] neg_lo:[1,0,0] neg_hi:[1,0,0]
	v_pk_add_f32 v[80:81], v[80:81], v[134:135] op_sel_hi:[1,0]
	v_pk_mul_f32 v[96:97], v[92:93], v[96:97]
	s_nop 0
	v_exp_f32_e32 v96, v96
	v_exp_f32_e32 v97, v97
	s_nop 0
	v_pk_add_f32 v[96:97], v[96:97], 1.0 op_sel_hi:[1,0]
	s_nop 0
	v_rcp_f32_e32 v96, v96
	v_rcp_f32_e32 v97, v97
	s_nop 0
	v_pk_mul_f32 v[92:93], v[92:93], v[96:97]
	s_nop 0
	v_cvt_pk_bf16_f32 v96, v92, v93
	s_nop 1
	v_mov_b32_dpp v97, v96 quad_perm:[1,0,3,2] row_mask:0xf bank_mask:0xf
	v_perm_b32 v92, v97, v96, v250
	v_add_u32_e32 v93, 0x40000, v163
	global_store_dword v93, v92, s[2:3]
	v_pk_add_f32 v[92:93], v[94:95], v[140:141] op_sel_hi:[1,0]
	s_nop 0
	v_pk_mul_f32 v[94:95], v[92:93], v[92:93]
	s_nop 0
	v_pk_fma_f32 v[94:95], v[94:95], s[88:89], v[124:125] op_sel_hi:[1,0,0] neg_lo:[1,0,0] neg_hi:[1,0,0]
	s_nop 0
	v_pk_mul_f32 v[94:95], v[92:93], v[94:95]
	s_nop 0
	v_exp_f32_e32 v94, v94
	v_exp_f32_e32 v95, v95
	s_nop 0
	v_pk_add_f32 v[94:95], v[94:95], 1.0 op_sel_hi:[1,0]
	s_nop 0
	v_rcp_f32_e32 v94, v94
	v_rcp_f32_e32 v95, v95
	s_nop 0
	v_pk_mul_f32 v[92:93], v[92:93], v[94:95]
	s_nop 0
	v_cvt_pk_bf16_f32 v94, v92, v93
	s_nop 1
	v_mov_b32_dpp v95, v94 quad_perm:[1,0,3,2] row_mask:0xf bank_mask:0xf
	v_perm_b32 v92, v95, v94, v250
	v_add_u32_e32 v93, 0x44000, v163
	global_store_dword v93, v92, s[2:3]
	v_pk_mul_f32 v[92:93], v[88:89], v[88:89]
	s_nop 0
	v_pk_fma_f32 v[92:93], v[92:93], s[88:89], v[124:125] op_sel_hi:[1,0,0] neg_lo:[1,0,0] neg_hi:[1,0,0]
	s_nop 0
	v_pk_mul_f32 v[92:93], v[88:89], v[92:93]
	s_nop 0
	v_exp_f32_e32 v92, v92
	v_exp_f32_e32 v93, v93
	s_nop 0
	v_pk_add_f32 v[92:93], v[92:93], 1.0 op_sel_hi:[1,0]
	s_nop 0
	v_rcp_f32_e32 v92, v92
	v_rcp_f32_e32 v93, v93
	s_nop 0
	v_pk_mul_f32 v[88:89], v[88:89], v[92:93]
	s_nop 0
	v_cvt_pk_bf16_f32 v92, v88, v89
	s_nop 1
	v_mov_b32_dpp v93, v92 quad_perm:[1,0,3,2] row_mask:0xf bank_mask:0xf
	v_perm_b32 v88, v93, v92, v250
	v_add_u32_e32 v89, 0x40020, v163
	global_store_dword v89, v88, s[2:3]
	v_pk_add_f32 v[88:89], v[90:91], v[138:139] op_sel_hi:[1,0]
	s_nop 0
	v_pk_mul_f32 v[90:91], v[88:89], v[88:89]
	s_nop 0
	v_pk_fma_f32 v[90:91], v[90:91], s[88:89], v[124:125] op_sel_hi:[1,0,0] neg_lo:[1,0,0] neg_hi:[1,0,0]
	s_nop 0
	v_pk_mul_f32 v[90:91], v[88:89], v[90:91]
	s_nop 0
	v_exp_f32_e32 v90, v90
	v_exp_f32_e32 v91, v91
	s_nop 0
	v_pk_add_f32 v[90:91], v[90:91], 1.0 op_sel_hi:[1,0]
	s_nop 0
	v_rcp_f32_e32 v90, v90
	v_rcp_f32_e32 v91, v91
	s_nop 0
	v_pk_mul_f32 v[88:89], v[88:89], v[90:91]
	s_nop 0
	v_cvt_pk_bf16_f32 v90, v88, v89
	s_nop 1
	v_mov_b32_dpp v91, v90 quad_perm:[1,0,3,2] row_mask:0xf bank_mask:0xf
	v_perm_b32 v88, v91, v90, v250
	v_add_u32_e32 v89, 0x44020, v163
	global_store_dword v89, v88, s[2:3]
	v_pk_mul_f32 v[88:89], v[84:85], v[84:85]
	s_nop 0
	v_pk_fma_f32 v[88:89], v[88:89], s[88:89], v[124:125] op_sel_hi:[1,0,0] neg_lo:[1,0,0] neg_hi:[1,0,0]
	s_nop 0
	v_pk_mul_f32 v[88:89], v[84:85], v[88:89]
	s_nop 0
	v_exp_f32_e32 v88, v88
	v_exp_f32_e32 v89, v89
	s_nop 0
	v_pk_add_f32 v[88:89], v[88:89], 1.0 op_sel_hi:[1,0]
	s_nop 0
	v_rcp_f32_e32 v88, v88
	v_rcp_f32_e32 v89, v89
	s_nop 0
	v_pk_mul_f32 v[84:85], v[84:85], v[88:89]
	s_nop 0
	v_cvt_pk_bf16_f32 v88, v84, v85
	s_nop 1
	v_mov_b32_dpp v89, v88 quad_perm:[1,0,3,2] row_mask:0xf bank_mask:0xf
	v_perm_b32 v84, v89, v88, v250
	v_add_u32_e32 v85, 0x40100, v163
	global_store_dword v85, v84, s[2:3]
	v_pk_add_f32 v[84:85], v[86:87], v[136:137] op_sel_hi:[1,0]
	s_nop 0
	v_pk_mul_f32 v[86:87], v[84:85], v[84:85]
	s_nop 0
	v_pk_fma_f32 v[86:87], v[86:87], s[88:89], v[124:125] op_sel_hi:[1,0,0] neg_lo:[1,0,0] neg_hi:[1,0,0]
	s_nop 0
	v_pk_mul_f32 v[86:87], v[84:85], v[86:87]
	s_nop 0
	v_exp_f32_e32 v86, v86
	v_exp_f32_e32 v87, v87
	s_nop 0
	v_pk_add_f32 v[86:87], v[86:87], 1.0 op_sel_hi:[1,0]
	s_nop 0
	v_rcp_f32_e32 v86, v86
	v_rcp_f32_e32 v87, v87
	s_nop 0
	v_pk_mul_f32 v[84:85], v[84:85], v[86:87]
	s_nop 0
	v_cvt_pk_bf16_f32 v86, v84, v85
	s_nop 1
	v_mov_b32_dpp v87, v86 quad_perm:[1,0,3,2] row_mask:0xf bank_mask:0xf
	v_perm_b32 v84, v87, v86, v250
	v_add_u32_e32 v85, 0x44100, v163
	global_store_dword v85, v84, s[2:3]
	v_pk_mul_f32 v[84:85], v[80:81], v[80:81]
	s_nop 0
	v_pk_fma_f32 v[84:85], v[84:85], s[88:89], v[124:125] op_sel_hi:[1,0,0] neg_lo:[1,0,0] neg_hi:[1,0,0]
	s_nop 0
	v_pk_mul_f32 v[84:85], v[80:81], v[84:85]
	s_nop 0
	v_exp_f32_e32 v84, v84
	v_exp_f32_e32 v85, v85
	s_nop 0
	v_pk_add_f32 v[84:85], v[84:85], 1.0 op_sel_hi:[1,0]
	s_nop 0
	v_rcp_f32_e32 v84, v84
	v_rcp_f32_e32 v85, v85
	s_nop 0
	v_pk_mul_f32 v[80:81], v[80:81], v[84:85]
	s_nop 0
	v_cvt_pk_bf16_f32 v84, v80, v81
	s_nop 1
	v_mov_b32_dpp v85, v84 quad_perm:[1,0,3,2] row_mask:0xf bank_mask:0xf
	v_perm_b32 v80, v85, v84, v250
	v_add_u32_e32 v81, 0x40120, v163
	global_store_dword v81, v80, s[2:3]
	v_pk_add_f32 v[80:81], v[82:83], v[134:135] op_sel_hi:[1,0]
	s_nop 0
	v_pk_mul_f32 v[82:83], v[80:81], v[80:81]
	s_nop 0
	v_pk_fma_f32 v[82:83], v[82:83], s[88:89], v[124:125] op_sel_hi:[1,0,0] neg_lo:[1,0,0] neg_hi:[1,0,0]
	s_nop 0
	v_pk_mul_f32 v[82:83], v[80:81], v[82:83]
	s_nop 0
	v_exp_f32_e32 v82, v82
	v_exp_f32_e32 v83, v83
	s_nop 0
	v_pk_add_f32 v[82:83], v[82:83], 1.0 op_sel_hi:[1,0]
	s_nop 0
	v_rcp_f32_e32 v82, v82
	v_rcp_f32_e32 v83, v83
	s_nop 0
	v_pk_mul_f32 v[80:81], v[80:81], v[82:83]
	s_nop 0
	v_cvt_pk_bf16_f32 v82, v80, v81
	s_nop 1
	v_mov_b32_dpp v83, v82 quad_perm:[1,0,3,2] row_mask:0xf bank_mask:0xf
	v_perm_b32 v80, v83, v82, v250
	v_add_u32_e32 v81, 0x44120, v163
	global_store_dword v81, v80, s[2:3]
	v_pk_add_f32 v[76:77], v[76:77], v[140:141] op_sel_hi:[1,0]
	v_pk_add_f32 v[72:73], v[72:73], v[138:139] op_sel_hi:[1,0]
	v_pk_mul_f32 v[80:81], v[76:77], v[76:77]
	v_pk_add_f32 v[68:69], v[68:69], v[136:137] op_sel_hi:[1,0]
	v_pk_fma_f32 v[80:81], v[80:81], s[88:89], v[124:125] op_sel_hi:[1,0,0] neg_lo:[1,0,0] neg_hi:[1,0,0]
	v_pk_add_f32 v[64:65], v[64:65], v[134:135] op_sel_hi:[1,0]
	v_pk_mul_f32 v[80:81], v[76:77], v[80:81]
	s_nop 0
	v_exp_f32_e32 v80, v80
	v_exp_f32_e32 v81, v81
	s_nop 0
	v_pk_add_f32 v[80:81], v[80:81], 1.0 op_sel_hi:[1,0]
	s_nop 0
	v_rcp_f32_e32 v80, v80
	v_rcp_f32_e32 v81, v81
	s_nop 0
	v_pk_mul_f32 v[76:77], v[76:77], v[80:81]
	s_nop 0
	v_cvt_pk_bf16_f32 v80, v76, v77
	s_nop 1
	v_mov_b32_dpp v81, v80 quad_perm:[1,0,3,2] row_mask:0xf bank_mask:0xf
	v_perm_b32 v76, v81, v80, v250
	v_add_u32_e32 v77, 0x60000, v163
	global_store_dword v77, v76, s[2:3]
	v_pk_add_f32 v[76:77], v[78:79], v[140:141] op_sel_hi:[1,0]
	s_nop 0
	v_pk_mul_f32 v[78:79], v[76:77], v[76:77]
	s_nop 0
	v_pk_fma_f32 v[78:79], v[78:79], s[88:89], v[124:125] op_sel_hi:[1,0,0] neg_lo:[1,0,0] neg_hi:[1,0,0]
	s_nop 0
	v_pk_mul_f32 v[78:79], v[76:77], v[78:79]
	s_nop 0
	v_exp_f32_e32 v78, v78
	v_exp_f32_e32 v79, v79
	s_nop 0
	v_pk_add_f32 v[78:79], v[78:79], 1.0 op_sel_hi:[1,0]
	s_nop 0
	v_rcp_f32_e32 v78, v78
	v_rcp_f32_e32 v79, v79
	s_nop 0
	v_pk_mul_f32 v[76:77], v[76:77], v[78:79]
	s_nop 0
	v_cvt_pk_bf16_f32 v78, v76, v77
	s_nop 1
	v_mov_b32_dpp v79, v78 quad_perm:[1,0,3,2] row_mask:0xf bank_mask:0xf
	v_perm_b32 v76, v79, v78, v250
	v_add_u32_e32 v77, 0x64000, v163
	global_store_dword v77, v76, s[2:3]
	v_pk_mul_f32 v[76:77], v[72:73], v[72:73]
	s_nop 0
	v_pk_fma_f32 v[76:77], v[76:77], s[88:89], v[124:125] op_sel_hi:[1,0,0] neg_lo:[1,0,0] neg_hi:[1,0,0]
	s_nop 0
	v_pk_mul_f32 v[76:77], v[72:73], v[76:77]
	s_nop 0
	v_exp_f32_e32 v76, v76
	v_exp_f32_e32 v77, v77
	s_nop 0
	v_pk_add_f32 v[76:77], v[76:77], 1.0 op_sel_hi:[1,0]
	s_nop 0
	v_rcp_f32_e32 v76, v76
	v_rcp_f32_e32 v77, v77
	s_nop 0
	v_pk_mul_f32 v[72:73], v[72:73], v[76:77]
	s_nop 0
	v_cvt_pk_bf16_f32 v76, v72, v73
	s_nop 1
	v_mov_b32_dpp v77, v76 quad_perm:[1,0,3,2] row_mask:0xf bank_mask:0xf
	v_perm_b32 v72, v77, v76, v250
	v_add_u32_e32 v73, 0x60020, v163
	global_store_dword v73, v72, s[2:3]
	v_pk_add_f32 v[72:73], v[74:75], v[138:139] op_sel_hi:[1,0]
	s_nop 0
	v_pk_mul_f32 v[74:75], v[72:73], v[72:73]
	s_nop 0
	v_pk_fma_f32 v[74:75], v[74:75], s[88:89], v[124:125] op_sel_hi:[1,0,0] neg_lo:[1,0,0] neg_hi:[1,0,0]
	s_nop 0
	v_pk_mul_f32 v[74:75], v[72:73], v[74:75]
	s_nop 0
	v_exp_f32_e32 v74, v74
	v_exp_f32_e32 v75, v75
	s_nop 0
	v_pk_add_f32 v[74:75], v[74:75], 1.0 op_sel_hi:[1,0]
	s_nop 0
	v_rcp_f32_e32 v74, v74
	v_rcp_f32_e32 v75, v75
	s_nop 0
	v_pk_mul_f32 v[72:73], v[72:73], v[74:75]
	s_nop 0
	v_cvt_pk_bf16_f32 v74, v72, v73
	s_nop 1
	v_mov_b32_dpp v75, v74 quad_perm:[1,0,3,2] row_mask:0xf bank_mask:0xf
	v_perm_b32 v72, v75, v74, v250
	v_add_u32_e32 v73, 0x64020, v163
	global_store_dword v73, v72, s[2:3]
	v_pk_mul_f32 v[72:73], v[68:69], v[68:69]
	s_nop 0
	v_pk_fma_f32 v[72:73], v[72:73], s[88:89], v[124:125] op_sel_hi:[1,0,0] neg_lo:[1,0,0] neg_hi:[1,0,0]
	s_nop 0
	v_pk_mul_f32 v[72:73], v[68:69], v[72:73]
	s_nop 0
	v_exp_f32_e32 v72, v72
	v_exp_f32_e32 v73, v73
	s_nop 0
	v_pk_add_f32 v[72:73], v[72:73], 1.0 op_sel_hi:[1,0]
	s_nop 0
	v_rcp_f32_e32 v72, v72
	v_rcp_f32_e32 v73, v73
	s_nop 0
	v_pk_mul_f32 v[68:69], v[68:69], v[72:73]
	s_nop 0
	v_cvt_pk_bf16_f32 v72, v68, v69
	s_nop 1
	v_mov_b32_dpp v73, v72 quad_perm:[1,0,3,2] row_mask:0xf bank_mask:0xf
	v_perm_b32 v68, v73, v72, v250
	v_add_u32_e32 v69, 0x60100, v163
	global_store_dword v69, v68, s[2:3]
	v_pk_add_f32 v[68:69], v[70:71], v[136:137] op_sel_hi:[1,0]
	s_nop 0
	v_pk_mul_f32 v[70:71], v[68:69], v[68:69]
	s_nop 0
	v_pk_fma_f32 v[70:71], v[70:71], s[88:89], v[124:125] op_sel_hi:[1,0,0] neg_lo:[1,0,0] neg_hi:[1,0,0]
	s_nop 0
	v_pk_mul_f32 v[70:71], v[68:69], v[70:71]
	s_nop 0
	v_exp_f32_e32 v70, v70
	v_exp_f32_e32 v71, v71
	s_nop 0
	v_pk_add_f32 v[70:71], v[70:71], 1.0 op_sel_hi:[1,0]
	s_nop 0
	v_rcp_f32_e32 v70, v70
	v_rcp_f32_e32 v71, v71
	s_nop 0
	v_pk_mul_f32 v[68:69], v[68:69], v[70:71]
	s_nop 0
	v_cvt_pk_bf16_f32 v70, v68, v69
	s_nop 1
	v_mov_b32_dpp v71, v70 quad_perm:[1,0,3,2] row_mask:0xf bank_mask:0xf
	v_perm_b32 v68, v71, v70, v250
	v_add_u32_e32 v69, 0x64100, v163
	global_store_dword v69, v68, s[2:3]
	v_pk_mul_f32 v[68:69], v[64:65], v[64:65]
	s_nop 0
	v_pk_fma_f32 v[68:69], v[68:69], s[88:89], v[124:125] op_sel_hi:[1,0,0] neg_lo:[1,0,0] neg_hi:[1,0,0]
	s_nop 0
	v_pk_mul_f32 v[68:69], v[64:65], v[68:69]
	s_nop 0
	v_exp_f32_e32 v68, v68
	v_exp_f32_e32 v69, v69
	s_nop 0
	v_pk_add_f32 v[68:69], v[68:69], 1.0 op_sel_hi:[1,0]
	s_nop 0
	v_rcp_f32_e32 v68, v68
	v_rcp_f32_e32 v69, v69
	s_nop 0
	v_pk_mul_f32 v[64:65], v[64:65], v[68:69]
	s_nop 0
	v_cvt_pk_bf16_f32 v68, v64, v65
	s_nop 1
	v_mov_b32_dpp v69, v68 quad_perm:[1,0,3,2] row_mask:0xf bank_mask:0xf
	v_perm_b32 v64, v69, v68, v250
	v_add_u32_e32 v65, 0x60120, v163
	global_store_dword v65, v64, s[2:3]
	v_pk_add_f32 v[64:65], v[66:67], v[134:135] op_sel_hi:[1,0]
	s_nop 0
	v_pk_mul_f32 v[66:67], v[64:65], v[64:65]
	s_nop 0
	v_pk_fma_f32 v[66:67], v[66:67], s[88:89], v[124:125] op_sel_hi:[1,0,0] neg_lo:[1,0,0] neg_hi:[1,0,0]
	s_nop 0
	v_pk_mul_f32 v[66:67], v[64:65], v[66:67]
	s_nop 0
	v_exp_f32_e32 v66, v66
	v_exp_f32_e32 v67, v67
	s_nop 0
	v_pk_add_f32 v[66:67], v[66:67], 1.0 op_sel_hi:[1,0]
	s_nop 0
	v_rcp_f32_e32 v66, v66
	v_rcp_f32_e32 v67, v67
	s_nop 0
	v_pk_mul_f32 v[64:65], v[64:65], v[66:67]
	s_nop 0
	v_cvt_pk_bf16_f32 v66, v64, v65
	s_nop 1
	v_mov_b32_dpp v67, v66 quad_perm:[1,0,3,2] row_mask:0xf bank_mask:0xf
	v_perm_b32 v64, v67, v66, v250
	v_add_u32_e32 v65, 0x64120, v163
	global_store_dword v65, v64, s[2:3]
	v_pk_add_f32 v[60:61], v[60:61], v[140:141] op_sel_hi:[1,0]
	v_pk_add_f32 v[56:57], v[56:57], v[138:139] op_sel_hi:[1,0]
	v_pk_mul_f32 v[64:65], v[60:61], v[60:61]
	v_pk_add_f32 v[52:53], v[52:53], v[136:137] op_sel_hi:[1,0]
	v_pk_fma_f32 v[64:65], v[64:65], s[88:89], v[124:125] op_sel_hi:[1,0,0] neg_lo:[1,0,0] neg_hi:[1,0,0]
	v_pk_add_f32 v[48:49], v[48:49], v[134:135] op_sel_hi:[1,0]
	v_pk_mul_f32 v[64:65], v[60:61], v[64:65]
	s_nop 0
	v_exp_f32_e32 v64, v64
	v_exp_f32_e32 v65, v65
	s_nop 0
	v_pk_add_f32 v[64:65], v[64:65], 1.0 op_sel_hi:[1,0]
	s_nop 0
	v_rcp_f32_e32 v64, v64
	v_rcp_f32_e32 v65, v65
	s_nop 0
	v_pk_mul_f32 v[60:61], v[60:61], v[64:65]
	s_nop 0
	v_cvt_pk_bf16_f32 v64, v60, v61
	s_nop 1
	v_mov_b32_dpp v65, v64 quad_perm:[1,0,3,2] row_mask:0xf bank_mask:0xf
	v_perm_b32 v60, v65, v64, v250
	v_add_u32_e32 v61, 0x100000, v163
	global_store_dword v61, v60, s[2:3]
	v_pk_add_f32 v[60:61], v[62:63], v[140:141] op_sel_hi:[1,0]
	s_nop 0
	v_pk_mul_f32 v[62:63], v[60:61], v[60:61]
	s_nop 0
	v_pk_fma_f32 v[62:63], v[62:63], s[88:89], v[124:125] op_sel_hi:[1,0,0] neg_lo:[1,0,0] neg_hi:[1,0,0]
	s_nop 0
	v_pk_mul_f32 v[62:63], v[60:61], v[62:63]
	s_nop 0
	v_exp_f32_e32 v62, v62
	v_exp_f32_e32 v63, v63
	s_nop 0
	v_pk_add_f32 v[62:63], v[62:63], 1.0 op_sel_hi:[1,0]
	s_nop 0
	v_rcp_f32_e32 v62, v62
	v_rcp_f32_e32 v63, v63
	s_nop 0
	v_pk_mul_f32 v[60:61], v[60:61], v[62:63]
	s_nop 0
	v_cvt_pk_bf16_f32 v62, v60, v61
	s_nop 1
	v_mov_b32_dpp v63, v62 quad_perm:[1,0,3,2] row_mask:0xf bank_mask:0xf
	v_perm_b32 v60, v63, v62, v250
	v_add_u32_e32 v61, 0x104000, v163
	global_store_dword v61, v60, s[2:3]
	v_pk_mul_f32 v[60:61], v[56:57], v[56:57]
	s_nop 0
	v_pk_fma_f32 v[60:61], v[60:61], s[88:89], v[124:125] op_sel_hi:[1,0,0] neg_lo:[1,0,0] neg_hi:[1,0,0]
	s_nop 0
	v_pk_mul_f32 v[60:61], v[56:57], v[60:61]
	s_nop 0
	v_exp_f32_e32 v60, v60
	v_exp_f32_e32 v61, v61
	s_nop 0
	v_pk_add_f32 v[60:61], v[60:61], 1.0 op_sel_hi:[1,0]
	s_nop 0
	v_rcp_f32_e32 v60, v60
	v_rcp_f32_e32 v61, v61
	s_nop 0
	v_pk_mul_f32 v[56:57], v[56:57], v[60:61]
	s_nop 0
	v_cvt_pk_bf16_f32 v60, v56, v57
	s_nop 1
	v_mov_b32_dpp v61, v60 quad_perm:[1,0,3,2] row_mask:0xf bank_mask:0xf
	v_perm_b32 v56, v61, v60, v250
	v_add_u32_e32 v57, 0x100020, v163
	global_store_dword v57, v56, s[2:3]
	v_pk_add_f32 v[56:57], v[58:59], v[138:139] op_sel_hi:[1,0]
	s_nop 0
	v_pk_mul_f32 v[58:59], v[56:57], v[56:57]
	s_nop 0
	v_pk_fma_f32 v[58:59], v[58:59], s[88:89], v[124:125] op_sel_hi:[1,0,0] neg_lo:[1,0,0] neg_hi:[1,0,0]
	s_nop 0
	v_pk_mul_f32 v[58:59], v[56:57], v[58:59]
	s_nop 0
	v_exp_f32_e32 v58, v58
	v_exp_f32_e32 v59, v59
	s_nop 0
	v_pk_add_f32 v[58:59], v[58:59], 1.0 op_sel_hi:[1,0]
	s_nop 0
	v_rcp_f32_e32 v58, v58
	v_rcp_f32_e32 v59, v59
	s_nop 0
	v_pk_mul_f32 v[56:57], v[56:57], v[58:59]
	s_nop 0
	v_cvt_pk_bf16_f32 v58, v56, v57
	s_nop 1
	v_mov_b32_dpp v59, v58 quad_perm:[1,0,3,2] row_mask:0xf bank_mask:0xf
	v_perm_b32 v56, v59, v58, v250
	v_add_u32_e32 v57, 0x104020, v163
	global_store_dword v57, v56, s[2:3]
	v_pk_mul_f32 v[56:57], v[52:53], v[52:53]
	s_nop 0
	v_pk_fma_f32 v[56:57], v[56:57], s[88:89], v[124:125] op_sel_hi:[1,0,0] neg_lo:[1,0,0] neg_hi:[1,0,0]
	s_nop 0
	v_pk_mul_f32 v[56:57], v[52:53], v[56:57]
	s_nop 0
	v_exp_f32_e32 v56, v56
	v_exp_f32_e32 v57, v57
	s_nop 0
	v_pk_add_f32 v[56:57], v[56:57], 1.0 op_sel_hi:[1,0]
	s_nop 0
	v_rcp_f32_e32 v56, v56
	v_rcp_f32_e32 v57, v57
	s_nop 0
	v_pk_mul_f32 v[52:53], v[52:53], v[56:57]
	s_nop 0
	v_cvt_pk_bf16_f32 v56, v52, v53
	s_nop 1
	v_mov_b32_dpp v57, v56 quad_perm:[1,0,3,2] row_mask:0xf bank_mask:0xf
	v_perm_b32 v52, v57, v56, v250
	v_add_u32_e32 v53, 0x100100, v163
	global_store_dword v53, v52, s[2:3]
	v_pk_add_f32 v[52:53], v[54:55], v[136:137] op_sel_hi:[1,0]
	s_nop 0
	v_pk_mul_f32 v[54:55], v[52:53], v[52:53]
	s_nop 0
	v_pk_fma_f32 v[54:55], v[54:55], s[88:89], v[124:125] op_sel_hi:[1,0,0] neg_lo:[1,0,0] neg_hi:[1,0,0]
	s_nop 0
	v_pk_mul_f32 v[54:55], v[52:53], v[54:55]
	s_nop 0
	v_exp_f32_e32 v54, v54
	v_exp_f32_e32 v55, v55
	s_nop 0
	v_pk_add_f32 v[54:55], v[54:55], 1.0 op_sel_hi:[1,0]
	s_nop 0
	v_rcp_f32_e32 v54, v54
	v_rcp_f32_e32 v55, v55
	s_nop 0
	v_pk_mul_f32 v[52:53], v[52:53], v[54:55]
	s_nop 0
	v_cvt_pk_bf16_f32 v54, v52, v53
	s_nop 1
	v_mov_b32_dpp v55, v54 quad_perm:[1,0,3,2] row_mask:0xf bank_mask:0xf
	v_perm_b32 v52, v55, v54, v250
	v_add_u32_e32 v53, 0x104100, v163
	global_store_dword v53, v52, s[2:3]
	v_pk_mul_f32 v[52:53], v[48:49], v[48:49]
	s_nop 0
	v_pk_fma_f32 v[52:53], v[52:53], s[88:89], v[124:125] op_sel_hi:[1,0,0] neg_lo:[1,0,0] neg_hi:[1,0,0]
	s_nop 0
	v_pk_mul_f32 v[52:53], v[48:49], v[52:53]
	s_nop 0
	v_exp_f32_e32 v52, v52
	v_exp_f32_e32 v53, v53
	s_nop 0
	v_pk_add_f32 v[52:53], v[52:53], 1.0 op_sel_hi:[1,0]
	s_nop 0
	v_rcp_f32_e32 v52, v52
	v_rcp_f32_e32 v53, v53
	s_nop 0
	v_pk_mul_f32 v[48:49], v[48:49], v[52:53]
	s_nop 0
	v_cvt_pk_bf16_f32 v52, v48, v49
	s_nop 1
	v_mov_b32_dpp v53, v52 quad_perm:[1,0,3,2] row_mask:0xf bank_mask:0xf
	v_perm_b32 v48, v53, v52, v250
	v_add_u32_e32 v49, 0x100120, v163
	global_store_dword v49, v48, s[2:3]
	v_pk_add_f32 v[48:49], v[50:51], v[134:135] op_sel_hi:[1,0]
	s_nop 0
	v_pk_mul_f32 v[50:51], v[48:49], v[48:49]
	s_nop 0
	v_pk_fma_f32 v[50:51], v[50:51], s[88:89], v[124:125] op_sel_hi:[1,0,0] neg_lo:[1,0,0] neg_hi:[1,0,0]
	s_nop 0
	v_pk_mul_f32 v[50:51], v[48:49], v[50:51]
	s_nop 0
	v_exp_f32_e32 v50, v50
	v_exp_f32_e32 v51, v51
	s_nop 0
	v_pk_add_f32 v[50:51], v[50:51], 1.0 op_sel_hi:[1,0]
	s_nop 0
	v_rcp_f32_e32 v50, v50
	v_rcp_f32_e32 v51, v51
	s_nop 0
	v_pk_mul_f32 v[48:49], v[48:49], v[50:51]
	s_nop 0
	v_cvt_pk_bf16_f32 v50, v48, v49
	s_nop 1
	v_mov_b32_dpp v51, v50 quad_perm:[1,0,3,2] row_mask:0xf bank_mask:0xf
	v_perm_b32 v48, v51, v50, v250
	v_add_u32_e32 v49, 0x104120, v163
	global_store_dword v49, v48, s[2:3]
	v_pk_add_f32 v[44:45], v[44:45], v[140:141] op_sel_hi:[1,0]
	v_pk_add_f32 v[40:41], v[40:41], v[138:139] op_sel_hi:[1,0]
	v_pk_mul_f32 v[48:49], v[44:45], v[44:45]
	v_pk_add_f32 v[36:37], v[36:37], v[136:137] op_sel_hi:[1,0]
	v_pk_fma_f32 v[48:49], v[48:49], s[88:89], v[124:125] op_sel_hi:[1,0,0] neg_lo:[1,0,0] neg_hi:[1,0,0]
	v_pk_add_f32 v[32:33], v[32:33], v[134:135] op_sel_hi:[1,0]
	v_pk_mul_f32 v[48:49], v[44:45], v[48:49]
	s_nop 0
	v_exp_f32_e32 v48, v48
	v_exp_f32_e32 v49, v49
	s_nop 0
	v_pk_add_f32 v[48:49], v[48:49], 1.0 op_sel_hi:[1,0]
	s_nop 0
	v_rcp_f32_e32 v48, v48
	v_rcp_f32_e32 v49, v49
	s_nop 0
	v_pk_mul_f32 v[44:45], v[44:45], v[48:49]
	s_nop 0
	v_cvt_pk_bf16_f32 v48, v44, v45
	s_nop 1
	v_mov_b32_dpp v49, v48 quad_perm:[1,0,3,2] row_mask:0xf bank_mask:0xf
	v_perm_b32 v44, v49, v48, v250
	v_add_u32_e32 v45, 0x120000, v163
	global_store_dword v45, v44, s[2:3]
	v_pk_add_f32 v[44:45], v[46:47], v[140:141] op_sel_hi:[1,0]
	s_nop 0
	v_pk_mul_f32 v[46:47], v[44:45], v[44:45]
	s_nop 0
	v_pk_fma_f32 v[46:47], v[46:47], s[88:89], v[124:125] op_sel_hi:[1,0,0] neg_lo:[1,0,0] neg_hi:[1,0,0]
	s_nop 0
	v_pk_mul_f32 v[46:47], v[44:45], v[46:47]
	s_nop 0
	v_exp_f32_e32 v46, v46
	v_exp_f32_e32 v47, v47
	s_nop 0
	v_pk_add_f32 v[46:47], v[46:47], 1.0 op_sel_hi:[1,0]
	s_nop 0
	v_rcp_f32_e32 v46, v46
	v_rcp_f32_e32 v47, v47
	s_nop 0
	v_pk_mul_f32 v[44:45], v[44:45], v[46:47]
	s_nop 0
	v_cvt_pk_bf16_f32 v46, v44, v45
	s_nop 1
	v_mov_b32_dpp v47, v46 quad_perm:[1,0,3,2] row_mask:0xf bank_mask:0xf
	v_perm_b32 v44, v47, v46, v250
	v_add_u32_e32 v45, 0x124000, v163
	global_store_dword v45, v44, s[2:3]
	v_pk_mul_f32 v[44:45], v[40:41], v[40:41]
	s_nop 0
	v_pk_fma_f32 v[44:45], v[44:45], s[88:89], v[124:125] op_sel_hi:[1,0,0] neg_lo:[1,0,0] neg_hi:[1,0,0]
	s_nop 0
	v_pk_mul_f32 v[44:45], v[40:41], v[44:45]
	s_nop 0
	v_exp_f32_e32 v44, v44
	v_exp_f32_e32 v45, v45
	s_nop 0
	v_pk_add_f32 v[44:45], v[44:45], 1.0 op_sel_hi:[1,0]
	s_nop 0
	v_rcp_f32_e32 v44, v44
	v_rcp_f32_e32 v45, v45
	s_nop 0
	v_pk_mul_f32 v[40:41], v[40:41], v[44:45]
	s_nop 0
	v_cvt_pk_bf16_f32 v44, v40, v41
	s_nop 1
	v_mov_b32_dpp v45, v44 quad_perm:[1,0,3,2] row_mask:0xf bank_mask:0xf
	v_perm_b32 v40, v45, v44, v250
	v_add_u32_e32 v41, 0x120020, v163
	global_store_dword v41, v40, s[2:3]
	v_pk_add_f32 v[40:41], v[42:43], v[138:139] op_sel_hi:[1,0]
	s_nop 0
	v_pk_mul_f32 v[42:43], v[40:41], v[40:41]
	s_nop 0
	v_pk_fma_f32 v[42:43], v[42:43], s[88:89], v[124:125] op_sel_hi:[1,0,0] neg_lo:[1,0,0] neg_hi:[1,0,0]
	s_nop 0
	v_pk_mul_f32 v[42:43], v[40:41], v[42:43]
	s_nop 0
	v_exp_f32_e32 v42, v42
	v_exp_f32_e32 v43, v43
	s_nop 0
	v_pk_add_f32 v[42:43], v[42:43], 1.0 op_sel_hi:[1,0]
	s_nop 0
	v_rcp_f32_e32 v42, v42
	v_rcp_f32_e32 v43, v43
	s_nop 0
	v_pk_mul_f32 v[40:41], v[40:41], v[42:43]
	s_nop 0
	v_cvt_pk_bf16_f32 v42, v40, v41
	s_nop 1
	v_mov_b32_dpp v43, v42 quad_perm:[1,0,3,2] row_mask:0xf bank_mask:0xf
	v_perm_b32 v40, v43, v42, v250
	v_add_u32_e32 v41, 0x124020, v163
	global_store_dword v41, v40, s[2:3]
	v_pk_mul_f32 v[40:41], v[36:37], v[36:37]
	s_nop 0
	v_pk_fma_f32 v[40:41], v[40:41], s[88:89], v[124:125] op_sel_hi:[1,0,0] neg_lo:[1,0,0] neg_hi:[1,0,0]
	s_nop 0
	v_pk_mul_f32 v[40:41], v[36:37], v[40:41]
	s_nop 0
	v_exp_f32_e32 v40, v40
	v_exp_f32_e32 v41, v41
	s_nop 0
	v_pk_add_f32 v[40:41], v[40:41], 1.0 op_sel_hi:[1,0]
	s_nop 0
	v_rcp_f32_e32 v40, v40
	v_rcp_f32_e32 v41, v41
	s_nop 0
	v_pk_mul_f32 v[36:37], v[36:37], v[40:41]
	s_nop 0
	v_cvt_pk_bf16_f32 v40, v36, v37
	s_nop 1
	v_mov_b32_dpp v41, v40 quad_perm:[1,0,3,2] row_mask:0xf bank_mask:0xf
	v_perm_b32 v36, v41, v40, v250
	v_add_u32_e32 v37, 0x120100, v163
	global_store_dword v37, v36, s[2:3]
	v_pk_add_f32 v[36:37], v[38:39], v[136:137] op_sel_hi:[1,0]
	s_nop 0
	v_pk_mul_f32 v[38:39], v[36:37], v[36:37]
	s_nop 0
	v_pk_fma_f32 v[38:39], v[38:39], s[88:89], v[124:125] op_sel_hi:[1,0,0] neg_lo:[1,0,0] neg_hi:[1,0,0]
	s_nop 0
	v_pk_mul_f32 v[38:39], v[36:37], v[38:39]
	s_nop 0
	v_exp_f32_e32 v38, v38
	v_exp_f32_e32 v39, v39
	s_nop 0
	v_pk_add_f32 v[38:39], v[38:39], 1.0 op_sel_hi:[1,0]
	s_nop 0
	v_rcp_f32_e32 v38, v38
	v_rcp_f32_e32 v39, v39
	s_nop 0
	v_pk_mul_f32 v[36:37], v[36:37], v[38:39]
	s_nop 0
	v_cvt_pk_bf16_f32 v38, v36, v37
	s_nop 1
	v_mov_b32_dpp v39, v38 quad_perm:[1,0,3,2] row_mask:0xf bank_mask:0xf
	v_perm_b32 v36, v39, v38, v250
	v_add_u32_e32 v37, 0x124100, v163
	global_store_dword v37, v36, s[2:3]
	v_pk_mul_f32 v[36:37], v[32:33], v[32:33]
	s_nop 0
	v_pk_fma_f32 v[36:37], v[36:37], s[88:89], v[124:125] op_sel_hi:[1,0,0] neg_lo:[1,0,0] neg_hi:[1,0,0]
	s_nop 0
	v_pk_mul_f32 v[36:37], v[32:33], v[36:37]
	s_nop 0
	v_exp_f32_e32 v36, v36
	v_exp_f32_e32 v37, v37
	s_nop 0
	v_pk_add_f32 v[36:37], v[36:37], 1.0 op_sel_hi:[1,0]
	s_nop 0
	v_rcp_f32_e32 v36, v36
	v_rcp_f32_e32 v37, v37
	s_nop 0
	v_pk_mul_f32 v[32:33], v[32:33], v[36:37]
	s_nop 0
	v_cvt_pk_bf16_f32 v36, v32, v33
	s_nop 1
	v_mov_b32_dpp v37, v36 quad_perm:[1,0,3,2] row_mask:0xf bank_mask:0xf
	v_perm_b32 v32, v37, v36, v250
	v_add_u32_e32 v33, 0x120120, v163
	global_store_dword v33, v32, s[2:3]
	v_pk_add_f32 v[32:33], v[34:35], v[134:135] op_sel_hi:[1,0]
	s_nop 0
	v_pk_mul_f32 v[34:35], v[32:33], v[32:33]
	s_nop 0
	v_pk_fma_f32 v[34:35], v[34:35], s[88:89], v[124:125] op_sel_hi:[1,0,0] neg_lo:[1,0,0] neg_hi:[1,0,0]
	s_nop 0
	v_pk_mul_f32 v[34:35], v[32:33], v[34:35]
	s_nop 0
	v_exp_f32_e32 v34, v34
	v_exp_f32_e32 v35, v35
	s_nop 0
	v_pk_add_f32 v[34:35], v[34:35], 1.0 op_sel_hi:[1,0]
	s_nop 0
	v_rcp_f32_e32 v34, v34
	v_rcp_f32_e32 v35, v35
	s_nop 0
	v_pk_mul_f32 v[32:33], v[32:33], v[34:35]
	s_nop 0
	v_cvt_pk_bf16_f32 v34, v32, v33
	s_nop 1
	v_mov_b32_dpp v35, v34 quad_perm:[1,0,3,2] row_mask:0xf bank_mask:0xf
	v_perm_b32 v32, v35, v34, v250
	v_add_u32_e32 v33, 0x124120, v163
	global_store_dword v33, v32, s[2:3]
	v_pk_add_f32 v[28:29], v[28:29], v[140:141] op_sel_hi:[1,0]
	v_pk_add_f32 v[24:25], v[24:25], v[138:139] op_sel_hi:[1,0]
	v_pk_mul_f32 v[32:33], v[28:29], v[28:29]
	v_pk_add_f32 v[20:21], v[20:21], v[136:137] op_sel_hi:[1,0]
	v_pk_fma_f32 v[32:33], v[32:33], s[88:89], v[124:125] op_sel_hi:[1,0,0] neg_lo:[1,0,0] neg_hi:[1,0,0]
	v_pk_add_f32 v[16:17], v[16:17], v[134:135] op_sel_hi:[1,0]
	v_pk_mul_f32 v[32:33], v[28:29], v[32:33]
	s_nop 0
	v_exp_f32_e32 v32, v32
	v_exp_f32_e32 v33, v33
	s_nop 0
	v_pk_add_f32 v[32:33], v[32:33], 1.0 op_sel_hi:[1,0]
	s_nop 0
	v_rcp_f32_e32 v32, v32
	v_rcp_f32_e32 v33, v33
	s_nop 0
	v_pk_mul_f32 v[28:29], v[28:29], v[32:33]
	s_nop 0
	v_cvt_pk_bf16_f32 v32, v28, v29
	s_nop 1
	v_mov_b32_dpp v33, v32 quad_perm:[1,0,3,2] row_mask:0xf bank_mask:0xf
	v_perm_b32 v28, v33, v32, v250
	v_add_u32_e32 v29, 0x140000, v163
	global_store_dword v29, v28, s[2:3]
	v_pk_add_f32 v[28:29], v[30:31], v[140:141] op_sel_hi:[1,0]
	s_nop 0
	v_pk_mul_f32 v[30:31], v[28:29], v[28:29]
	s_nop 0
	v_pk_fma_f32 v[30:31], v[30:31], s[88:89], v[124:125] op_sel_hi:[1,0,0] neg_lo:[1,0,0] neg_hi:[1,0,0]
	s_nop 0
	v_pk_mul_f32 v[30:31], v[28:29], v[30:31]
	s_nop 0
	v_exp_f32_e32 v30, v30
	v_exp_f32_e32 v31, v31
	s_nop 0
	v_pk_add_f32 v[30:31], v[30:31], 1.0 op_sel_hi:[1,0]
	s_nop 0
	v_rcp_f32_e32 v30, v30
	v_rcp_f32_e32 v31, v31
	s_nop 0
	v_pk_mul_f32 v[28:29], v[28:29], v[30:31]
	s_nop 0
	v_cvt_pk_bf16_f32 v30, v28, v29
	s_nop 1
	v_mov_b32_dpp v31, v30 quad_perm:[1,0,3,2] row_mask:0xf bank_mask:0xf
	v_perm_b32 v28, v31, v30, v250
	v_add_u32_e32 v29, 0x144000, v163
	global_store_dword v29, v28, s[2:3]
	v_pk_mul_f32 v[28:29], v[24:25], v[24:25]
	s_nop 0
	v_pk_fma_f32 v[28:29], v[28:29], s[88:89], v[124:125] op_sel_hi:[1,0,0] neg_lo:[1,0,0] neg_hi:[1,0,0]
	s_nop 0
	v_pk_mul_f32 v[28:29], v[24:25], v[28:29]
	s_nop 0
	v_exp_f32_e32 v28, v28
	v_exp_f32_e32 v29, v29
	s_nop 0
	v_pk_add_f32 v[28:29], v[28:29], 1.0 op_sel_hi:[1,0]
	s_nop 0
	v_rcp_f32_e32 v28, v28
	v_rcp_f32_e32 v29, v29
	s_nop 0
	v_pk_mul_f32 v[24:25], v[24:25], v[28:29]
	s_nop 0
	v_cvt_pk_bf16_f32 v28, v24, v25
	s_nop 1
	v_mov_b32_dpp v29, v28 quad_perm:[1,0,3,2] row_mask:0xf bank_mask:0xf
	v_perm_b32 v24, v29, v28, v250
	v_add_u32_e32 v25, 0x140020, v163
	global_store_dword v25, v24, s[2:3]
	v_pk_add_f32 v[24:25], v[26:27], v[138:139] op_sel_hi:[1,0]
	s_nop 0
	v_pk_mul_f32 v[26:27], v[24:25], v[24:25]
	s_nop 0
	v_pk_fma_f32 v[26:27], v[26:27], s[88:89], v[124:125] op_sel_hi:[1,0,0] neg_lo:[1,0,0] neg_hi:[1,0,0]
	s_nop 0
	v_pk_mul_f32 v[26:27], v[24:25], v[26:27]
	s_nop 0
	v_exp_f32_e32 v26, v26
	v_exp_f32_e32 v27, v27
	s_nop 0
	v_pk_add_f32 v[26:27], v[26:27], 1.0 op_sel_hi:[1,0]
	s_nop 0
	v_rcp_f32_e32 v26, v26
	v_rcp_f32_e32 v27, v27
	s_nop 0
	v_pk_mul_f32 v[24:25], v[24:25], v[26:27]
	s_nop 0
	v_cvt_pk_bf16_f32 v26, v24, v25
	s_nop 1
	v_mov_b32_dpp v27, v26 quad_perm:[1,0,3,2] row_mask:0xf bank_mask:0xf
	v_perm_b32 v24, v27, v26, v250
	v_add_u32_e32 v25, 0x144020, v163
	global_store_dword v25, v24, s[2:3]
	v_pk_mul_f32 v[24:25], v[20:21], v[20:21]
	s_nop 0
	v_pk_fma_f32 v[24:25], v[24:25], s[88:89], v[124:125] op_sel_hi:[1,0,0] neg_lo:[1,0,0] neg_hi:[1,0,0]
	s_nop 0
	v_pk_mul_f32 v[24:25], v[20:21], v[24:25]
	s_nop 0
	v_exp_f32_e32 v24, v24
	v_exp_f32_e32 v25, v25
	s_nop 0
	v_pk_add_f32 v[24:25], v[24:25], 1.0 op_sel_hi:[1,0]
	s_nop 0
	v_rcp_f32_e32 v24, v24
	v_rcp_f32_e32 v25, v25
	s_nop 0
	v_pk_mul_f32 v[20:21], v[20:21], v[24:25]
	s_nop 0
	v_cvt_pk_bf16_f32 v24, v20, v21
	s_nop 1
	v_mov_b32_dpp v25, v24 quad_perm:[1,0,3,2] row_mask:0xf bank_mask:0xf
	v_perm_b32 v20, v25, v24, v250
	v_add_u32_e32 v21, 0x140100, v163
	global_store_dword v21, v20, s[2:3]
	v_pk_add_f32 v[20:21], v[22:23], v[136:137] op_sel_hi:[1,0]
	s_nop 0
	v_pk_mul_f32 v[22:23], v[20:21], v[20:21]
	s_nop 0
	v_pk_fma_f32 v[22:23], v[22:23], s[88:89], v[124:125] op_sel_hi:[1,0,0] neg_lo:[1,0,0] neg_hi:[1,0,0]
	s_nop 0
	v_pk_mul_f32 v[22:23], v[20:21], v[22:23]
	s_nop 0
	v_exp_f32_e32 v22, v22
	v_exp_f32_e32 v23, v23
	s_nop 0
	v_pk_add_f32 v[22:23], v[22:23], 1.0 op_sel_hi:[1,0]
	s_nop 0
	v_rcp_f32_e32 v22, v22
	v_rcp_f32_e32 v23, v23
	s_nop 0
	v_pk_mul_f32 v[20:21], v[20:21], v[22:23]
	s_nop 0
	v_cvt_pk_bf16_f32 v22, v20, v21
	s_nop 1
	v_mov_b32_dpp v23, v22 quad_perm:[1,0,3,2] row_mask:0xf bank_mask:0xf
	v_perm_b32 v20, v23, v22, v250
	v_add_u32_e32 v21, 0x144100, v163
	global_store_dword v21, v20, s[2:3]
	v_pk_mul_f32 v[20:21], v[16:17], v[16:17]
	s_nop 0
	v_pk_fma_f32 v[20:21], v[20:21], s[88:89], v[124:125] op_sel_hi:[1,0,0] neg_lo:[1,0,0] neg_hi:[1,0,0]
	s_nop 0
	v_pk_mul_f32 v[20:21], v[16:17], v[20:21]
	s_nop 0
	v_exp_f32_e32 v20, v20
	v_exp_f32_e32 v21, v21
	s_nop 0
	v_pk_add_f32 v[20:21], v[20:21], 1.0 op_sel_hi:[1,0]
	s_nop 0
	v_rcp_f32_e32 v20, v20
	v_rcp_f32_e32 v21, v21
	s_nop 0
	v_pk_mul_f32 v[16:17], v[16:17], v[20:21]
	s_nop 0
	v_cvt_pk_bf16_f32 v20, v16, v17
	s_nop 1
	v_mov_b32_dpp v21, v20 quad_perm:[1,0,3,2] row_mask:0xf bank_mask:0xf
	v_perm_b32 v16, v21, v20, v250
	v_add_u32_e32 v17, 0x140120, v163
	global_store_dword v17, v16, s[2:3]
	v_pk_add_f32 v[16:17], v[18:19], v[134:135] op_sel_hi:[1,0]
	s_nop 0
	v_pk_mul_f32 v[18:19], v[16:17], v[16:17]
	s_nop 0
	v_pk_fma_f32 v[18:19], v[18:19], s[88:89], v[124:125] op_sel_hi:[1,0,0] neg_lo:[1,0,0] neg_hi:[1,0,0]
	s_nop 0
	v_pk_mul_f32 v[18:19], v[16:17], v[18:19]
	s_nop 0
	v_exp_f32_e32 v18, v18
	v_exp_f32_e32 v19, v19
	s_nop 0
	v_pk_add_f32 v[18:19], v[18:19], 1.0 op_sel_hi:[1,0]
	s_nop 0
	v_rcp_f32_e32 v18, v18
	v_rcp_f32_e32 v19, v19
	s_nop 0
	v_pk_mul_f32 v[16:17], v[16:17], v[18:19]
	s_nop 0
	v_cvt_pk_bf16_f32 v18, v16, v17
	s_nop 1
	v_mov_b32_dpp v19, v18 quad_perm:[1,0,3,2] row_mask:0xf bank_mask:0xf
	v_perm_b32 v16, v19, v18, v250
	v_add_u32_e32 v17, 0x144120, v163
	global_store_dword v17, v16, s[2:3]
	v_pk_add_f32 v[12:13], v[12:13], v[140:141] op_sel_hi:[1,0]
	v_pk_add_f32 v[8:9], v[8:9], v[138:139] op_sel_hi:[1,0]
	v_pk_mul_f32 v[16:17], v[12:13], v[12:13]
	v_pk_add_f32 v[4:5], v[4:5], v[136:137] op_sel_hi:[1,0]
	v_pk_fma_f32 v[16:17], v[16:17], s[88:89], v[124:125] op_sel_hi:[1,0,0] neg_lo:[1,0,0] neg_hi:[1,0,0]
	v_pk_add_f32 v[0:1], v[0:1], v[134:135] op_sel_hi:[1,0]
	v_pk_mul_f32 v[16:17], v[12:13], v[16:17]
	s_nop 0
	v_exp_f32_e32 v16, v16
	v_exp_f32_e32 v17, v17
	s_nop 0
	v_pk_add_f32 v[16:17], v[16:17], 1.0 op_sel_hi:[1,0]
	s_nop 0
	v_rcp_f32_e32 v16, v16
	v_rcp_f32_e32 v17, v17
	s_nop 0
	v_pk_mul_f32 v[12:13], v[12:13], v[16:17]
	s_nop 0
	v_cvt_pk_bf16_f32 v16, v12, v13
	s_nop 1
	v_mov_b32_dpp v17, v16 quad_perm:[1,0,3,2] row_mask:0xf bank_mask:0xf
	v_perm_b32 v12, v17, v16, v250
	v_add_u32_e32 v13, 0x160000, v163
	global_store_dword v13, v12, s[2:3]
	v_pk_add_f32 v[12:13], v[14:15], v[140:141] op_sel_hi:[1,0]
	s_nop 0
	v_pk_mul_f32 v[14:15], v[12:13], v[12:13]
	s_nop 0
	v_pk_fma_f32 v[14:15], v[14:15], s[88:89], v[124:125] op_sel_hi:[1,0,0] neg_lo:[1,0,0] neg_hi:[1,0,0]
	s_nop 0
	v_pk_mul_f32 v[14:15], v[12:13], v[14:15]
	s_nop 0
	v_exp_f32_e32 v14, v14
	v_exp_f32_e32 v15, v15
	s_nop 0
	v_pk_add_f32 v[14:15], v[14:15], 1.0 op_sel_hi:[1,0]
	s_nop 0
	v_rcp_f32_e32 v14, v14
	v_rcp_f32_e32 v15, v15
	s_nop 0
	v_pk_mul_f32 v[12:13], v[12:13], v[14:15]
	s_nop 0
	v_cvt_pk_bf16_f32 v14, v12, v13
	s_nop 1
	v_mov_b32_dpp v15, v14 quad_perm:[1,0,3,2] row_mask:0xf bank_mask:0xf
	v_perm_b32 v12, v15, v14, v250
	v_add_u32_e32 v13, 0x164000, v163
	global_store_dword v13, v12, s[2:3]
	v_pk_mul_f32 v[12:13], v[8:9], v[8:9]
	s_nop 0
	v_pk_fma_f32 v[12:13], v[12:13], s[88:89], v[124:125] op_sel_hi:[1,0,0] neg_lo:[1,0,0] neg_hi:[1,0,0]
	s_nop 0
	v_pk_mul_f32 v[12:13], v[8:9], v[12:13]
	s_nop 0
	v_exp_f32_e32 v12, v12
	v_exp_f32_e32 v13, v13
	s_nop 0
	v_pk_add_f32 v[12:13], v[12:13], 1.0 op_sel_hi:[1,0]
	s_nop 0
	v_rcp_f32_e32 v12, v12
	v_rcp_f32_e32 v13, v13
	s_nop 0
	v_pk_mul_f32 v[8:9], v[8:9], v[12:13]
	s_nop 0
	v_cvt_pk_bf16_f32 v12, v8, v9
	s_nop 1
	v_mov_b32_dpp v13, v12 quad_perm:[1,0,3,2] row_mask:0xf bank_mask:0xf
	v_perm_b32 v8, v13, v12, v250
	v_add_u32_e32 v9, 0x160020, v163
	global_store_dword v9, v8, s[2:3]
	v_pk_add_f32 v[8:9], v[10:11], v[138:139] op_sel_hi:[1,0]
	s_nop 0
	v_pk_mul_f32 v[10:11], v[8:9], v[8:9]
	s_nop 0
	v_pk_fma_f32 v[10:11], v[10:11], s[88:89], v[124:125] op_sel_hi:[1,0,0] neg_lo:[1,0,0] neg_hi:[1,0,0]
	s_nop 0
	v_pk_mul_f32 v[10:11], v[8:9], v[10:11]
	s_nop 0
	v_exp_f32_e32 v10, v10
	v_exp_f32_e32 v11, v11
	s_nop 0
	v_pk_add_f32 v[10:11], v[10:11], 1.0 op_sel_hi:[1,0]
	s_nop 0
	v_rcp_f32_e32 v10, v10
	v_rcp_f32_e32 v11, v11
	s_nop 0
	v_pk_mul_f32 v[8:9], v[8:9], v[10:11]
	s_nop 0
	v_cvt_pk_bf16_f32 v10, v8, v9
	s_nop 1
	v_mov_b32_dpp v11, v10 quad_perm:[1,0,3,2] row_mask:0xf bank_mask:0xf
	v_perm_b32 v8, v11, v10, v250
	v_add_u32_e32 v9, 0x164020, v163
	global_store_dword v9, v8, s[2:3]
	v_pk_mul_f32 v[8:9], v[4:5], v[4:5]
	s_nop 0
	v_pk_fma_f32 v[8:9], v[8:9], s[88:89], v[124:125] op_sel_hi:[1,0,0] neg_lo:[1,0,0] neg_hi:[1,0,0]
	s_nop 0
	v_pk_mul_f32 v[8:9], v[4:5], v[8:9]
	s_nop 0
	v_exp_f32_e32 v8, v8
	v_exp_f32_e32 v9, v9
	s_nop 0
	v_pk_add_f32 v[8:9], v[8:9], 1.0 op_sel_hi:[1,0]
	s_nop 0
	v_rcp_f32_e32 v8, v8
	v_rcp_f32_e32 v9, v9
	s_nop 0
	v_pk_mul_f32 v[4:5], v[4:5], v[8:9]
	s_nop 0
	v_cvt_pk_bf16_f32 v8, v4, v5
	s_nop 1
	v_mov_b32_dpp v9, v8 quad_perm:[1,0,3,2] row_mask:0xf bank_mask:0xf
	v_perm_b32 v4, v9, v8, v250
	v_add_u32_e32 v5, 0x160100, v163
	global_store_dword v5, v4, s[2:3]
	v_pk_add_f32 v[4:5], v[6:7], v[136:137] op_sel_hi:[1,0]
	s_nop 0
	v_pk_mul_f32 v[6:7], v[4:5], v[4:5]
	s_nop 0
	v_pk_fma_f32 v[6:7], v[6:7], s[88:89], v[124:125] op_sel_hi:[1,0,0] neg_lo:[1,0,0] neg_hi:[1,0,0]
	s_nop 0
	v_pk_mul_f32 v[6:7], v[4:5], v[6:7]
	s_nop 0
	v_exp_f32_e32 v6, v6
	v_exp_f32_e32 v7, v7
	s_nop 0
	v_pk_add_f32 v[6:7], v[6:7], 1.0 op_sel_hi:[1,0]
	s_nop 0
	v_rcp_f32_e32 v6, v6
	v_rcp_f32_e32 v7, v7
	s_nop 0
	v_pk_mul_f32 v[4:5], v[4:5], v[6:7]
	s_nop 0
	v_cvt_pk_bf16_f32 v6, v4, v5
	s_nop 1
	v_mov_b32_dpp v7, v6 quad_perm:[1,0,3,2] row_mask:0xf bank_mask:0xf
	v_perm_b32 v4, v7, v6, v250
	v_add_u32_e32 v5, 0x164100, v163
	global_store_dword v5, v4, s[2:3]
	v_pk_mul_f32 v[4:5], v[0:1], v[0:1]
	s_nop 0
	v_pk_fma_f32 v[4:5], v[4:5], s[88:89], v[124:125] op_sel_hi:[1,0,0] neg_lo:[1,0,0] neg_hi:[1,0,0]
	s_nop 0
	v_pk_mul_f32 v[4:5], v[0:1], v[4:5]
	s_nop 0
	v_exp_f32_e32 v4, v4
	v_exp_f32_e32 v5, v5
	s_nop 0
	v_pk_add_f32 v[4:5], v[4:5], 1.0 op_sel_hi:[1,0]
	s_nop 0
	v_rcp_f32_e32 v4, v4
	v_rcp_f32_e32 v5, v5
	s_nop 0
	v_pk_mul_f32 v[0:1], v[0:1], v[4:5]
	s_nop 0
	v_cvt_pk_bf16_f32 v4, v0, v1
	s_nop 1
	v_mov_b32_dpp v5, v4 quad_perm:[1,0,3,2] row_mask:0xf bank_mask:0xf
	v_perm_b32 v0, v5, v4, v250
	v_add_u32_e32 v1, 0x160120, v163
	global_store_dword v1, v0, s[2:3]
	v_pk_add_f32 v[0:1], v[2:3], v[134:135] op_sel_hi:[1,0]
	s_nop 0
	v_pk_mul_f32 v[2:3], v[0:1], v[0:1]
	s_nop 0
	v_pk_fma_f32 v[2:3], v[2:3], s[88:89], v[124:125] op_sel_hi:[1,0,0] neg_lo:[1,0,0] neg_hi:[1,0,0]
	s_nop 0
	v_pk_mul_f32 v[2:3], v[0:1], v[2:3]
	s_nop 0
	v_exp_f32_e32 v2, v2
	v_exp_f32_e32 v3, v3
	s_nop 0
	v_pk_add_f32 v[2:3], v[2:3], 1.0 op_sel_hi:[1,0]
	s_nop 0
	v_rcp_f32_e32 v2, v2
	v_rcp_f32_e32 v3, v3
	s_nop 0
	v_pk_mul_f32 v[0:1], v[0:1], v[2:3]
	s_nop 0
	v_cvt_pk_bf16_f32 v2, v0, v1
	s_nop 1
	v_mov_b32_dpp v3, v2 quad_perm:[1,0,3,2] row_mask:0xf bank_mask:0xf
	v_perm_b32 v0, v3, v2, v250
	v_add_u32_e32 v1, 0x164120, v163
	global_store_dword v1, v0, s[2:3]
	s_and_b64 vcc, exec, s[24:25]
	s_mov_b32 s38, s68
	s_mov_b32 s40, s70
	s_cbranch_vccnz .LBB0_1548

.LBB0_1555:
	v_readlane_b32 s2, v255, 20
	v_readlane_b32 s3, v255, 21
	s_add_i32 s34, s2, -2
	s_lshl_b64 s[2:3], s[34:35], 22
	s_add_u32 s2, s26, s2
	s_addc_u32 s3, s27, s3
	s_add_u32 s34, s2, 0x2100000
	s_addc_u32 s46, s3, 0
	s_add_u32 s2, s26, 0x3c00000
	s_addc_u32 s3, s27, 0
	s_add_u32 s12, s26, 0x7c00000
	s_addc_u32 s13, s27, 0
	s_add_i32 s6, s6, s7
	s_ashr_i32 s7, s6, 31
	s_lshr_b32 s7, s7, 26
	s_add_i32 s7, s6, s7
	s_and_b32 s8, s7, 0xffc0
	s_sub_i32 s6, s6, s8
	s_bfe_i32 s8, s6, 0x80000
	s_bfe_u32 s8, s8, 0x3000c
	s_add_i32 s8, s6, s8
	s_bfe_i32 s9, s8, 0x80000
	s_and_b32 s8, s8, 0xf8
	s_sub_i32 s6, s6, s8
	s_sext_i32_i8 s6, s6
	s_lshl_b32 s7, s7, 5
	s_sext_i32_i16 s9, s9
	s_and_b32 s7, s7, 0xfffff800
	s_lshl_b32 s6, s6, 8
	v_ashrrev_i32_e32 v1, 6, v0
	v_lshlrev_b32_e32 v2, 4, v0
	v_lshrrev_b32_e32 v3, 31, v0
	s_add_i32 s40, s6, s7
	s_lshl_b32 s6, s9, 5
	v_add_u32_e32 v3, v1, v3
	v_and_b32_e32 v10, 48, v2
	v_lshlrev_b32_e32 v2, 9, v0
	s_and_b32 s42, s6, 0xffffff00
	v_ashrrev_i32_e32 v9, 1, v3
	v_and_b32_e32 v3, 0x3fffffe, v3
	v_and_b32_e32 v11, 0x7800, v2
	s_ashr_i32 s41, s40, 31
	s_ashr_i32 s43, s42, 31
	v_lshlrev_b32_e32 v134, 10, v1
	v_sub_u32_e32 v3, v1, v3
	v_lshl_or_b32 v2, v9, 15, v11
	s_lshl_b64 s[6:7], s[40:41], 11
	s_lshl_b64 s[8:9], s[42:43], 11
	v_and_b32_e32 v8, 32, v0
	v_lshl_add_u32 v2, v3, 6, v2
	s_waitcnt lgkmcnt(0)
	s_add_u32 s14, s34, s8
	v_add_u32_e32 v135, 0x10000, v134
	v_bitop3_b32 v128, v2, v10, v8 bitop3:0xf6
	s_addc_u32 s15, s46, s9
	v_readfirstlane_b32 s8, v135
	v_add_u32_e32 v136, 0x12000, v134
	v_lshl_add_u64 v[2:3], s[14:15], 0, v[128:129]
	s_mov_b32 m0, s8
	s_mov_b64 s[10:11], 0x20000
	v_readfirstlane_b32 s8, v136
	s_add_u32 s18, s16, s6
	global_load_lds_dwordx4 v128, s[14:15]
	v_lshl_add_u64 v[4:5], v[2:3], 0, s[10:11]
	s_mov_b32 m0, s8
	s_addc_u32 s19, s17, s7
	v_readfirstlane_b32 s6, v134
	v_add_u32_e32 v137, 0x2000, v134
	global_load_lds_dwordx4 v[4:5], off
	v_lshl_add_u64 v[4:5], s[18:19], 0, v[128:129]
	s_mov_b32 m0, s6
	v_readfirstlane_b32 s6, v137
	v_add_u32_e32 v138, 0x14000, v134
	global_load_lds_dwordx4 v128, s[18:19]
	v_lshl_add_u64 v[6:7], v[4:5], 0, s[10:11]
	s_mov_b32 m0, s6
	s_mov_b64 s[8:9], 0x40000
	v_readfirstlane_b32 s6, v138
	v_add_u32_e32 v139, 0x16000, v134
	global_load_lds_dwordx4 v[6:7], off
	v_lshl_add_u64 v[6:7], v[2:3], 0, s[8:9]
	s_mov_b32 m0, s6
	s_mov_b64 s[10:11], 0x60000
	v_readfirstlane_b32 s6, v139
	v_add_u32_e32 v140, 0x4000, v134
	global_load_lds_dwordx4 v[6:7], off
	v_lshl_add_u64 v[6:7], v[2:3], 0, s[10:11]
	s_mov_b32 m0, s6
	v_readfirstlane_b32 s6, v140
	v_add_u32_e32 v141, 0x6000, v134
	global_load_lds_dwordx4 v[6:7], off
	v_lshl_add_u64 v[6:7], v[4:5], 0, s[8:9]
	s_mov_b32 m0, s6
	v_readfirstlane_b32 s6, v141
	v_add_u32_e32 v142, 0x18000, v134
	global_load_lds_dwordx4 v[6:7], off
	v_lshl_add_u64 v[6:7], v[4:5], 0, s[10:11]
	s_mov_b32 m0, s6
	v_readfirstlane_b32 s6, v142
	v_add_u32_e32 v143, 0x1a000, v134
	global_load_lds_dwordx4 v[6:7], off
	v_lshl_add_u64 v[6:7], v[2:3], 0, s[44:45]
	s_mov_b32 m0, s6
	s_mov_b64 s[8:9], 0x20080
	v_readfirstlane_b32 s6, v143
	v_add_u32_e32 v144, 0x8000, v134
	global_load_lds_dwordx4 v[6:7], off
	v_lshl_add_u64 v[6:7], v[2:3], 0, s[8:9]
	s_mov_b32 m0, s6
	v_readfirstlane_b32 s6, v144
	v_add_u32_e32 v145, 0xa000, v134
	global_load_lds_dwordx4 v[6:7], off
	v_lshl_add_u64 v[6:7], v[4:5], 0, s[44:45]
	s_mov_b32 m0, s6
	v_readfirstlane_b32 s6, v145
	v_add_u32_e32 v146, 0x1c000, v134
	global_load_lds_dwordx4 v[6:7], off
	v_lshl_add_u64 v[4:5], v[4:5], 0, s[8:9]
	s_mov_b32 m0, s6
	v_readfirstlane_b32 s6, v146
	v_add_u32_e32 v147, 0x1e000, v134
	global_load_lds_dwordx4 v[4:5], off
	v_lshl_add_u64 v[4:5], v[2:3], 0, s[48:49]
	s_mov_b32 m0, s6
	v_readfirstlane_b32 s6, v147
	global_load_lds_dwordx4 v[4:5], off
	v_lshl_add_u64 v[2:3], v[2:3], 0, s[50:51]
	s_mov_b32 m0, s6
	v_and_b32_e32 v5, 48, v0
	global_load_lds_dwordx4 v[2:3], off
	v_and_b32_e32 v3, 15, v0
	v_lshlrev_b32_e32 v3, 6, v3
	v_lshlrev_b32_e32 v7, 2, v0
	v_ashrrev_i32_e32 v2, 8, v0
	v_or_b32_e32 v6, v3, v5
	v_and_b32_e32 v7, 32, v7
	s_mov_b32 s8, 0x10000
	v_lshrrev_b32_e32 v17, 2, v0
	v_bitop3_b32 v12, v6, s8, v7 bitop3:0xde
	v_lshlrev_b32_e32 v13, 6, v2
	s_mov_b32 s8, 0x14000
	v_and_b32_e32 v16, 1, v0
	v_and_b32_e32 v17, 12, v17
	v_and_b32_e32 v1, 3, v1
	v_bitop3_b32 v14, v6, s8, v7 bitop3:0xde
	s_mov_b32 s8, 0x18000
	v_or3_b32 v148, v13, v17, v16
	v_and_b32_e32 v13, 14, v0
	v_cmp_eq_u32_e64 s[6:7], 1, v2
	v_lshlrev_b32_e32 v4, 12, v1
	v_bitop3_b32 v15, v6, s8, v7 bitop3:0xde
	s_mov_b32 s8, 0x1c000
	v_lshl_or_b32 v149, v1, 5, v13
	v_lshlrev_b32_e32 v1, 13, v2
	v_lshlrev_b32_e32 v2, 6, v0
	s_movk_i32 s22, 0x7f80
	v_bitop3_b32 v6, v6, s8, v7 bitop3:0xde
	s_movk_i32 s8, 0x100
	v_and_b32_e32 v2, 0x3c0, v2
	v_mul_lo_u32 v9, v9, s22
	v_bitop3_b32 v3, v3, v7, v5 bitop3:0x36
	v_cmp_gt_u32_e64 s[8:9], s8, v0
	v_bitop3_b32 v2, v2, v7, v5 bitop3:0x36
	v_or_b32_e32 v5, 0x800, v1
	v_or_b32_e32 v7, 0x1000, v1
	v_or_b32_e32 v13, 0x1800, v1
	v_bitop3_b32 v8, v10, v9, v8 bitop3:0xde
	v_and_b32_e32 v0, 0xffffffc0, v0
	v_cmp_eq_u32_e64 s[10:11], 0, v16
	v_add3_u32 v132, v8, v11, v0
	v_mov_b32_e32 v133, v129
	v_add_u32_e32 v150, v12, v4
	v_add_u32_e32 v151, v3, v1
	v_add_u32_e32 v152, v2, v5
	v_add_u32_e32 v153, v2, v7
	v_add_u32_e32 v154, v2, v13
	v_add_u32_e32 v155, v14, v4
	v_add_u32_e32 v156, v15, v4
	v_add_u32_e32 v157, v6, v4
	s_waitcnt vmcnt(0)
	v_mov_b32_e32 v250, 0x3020706
	v_mov_b32_e32 v251, 0x5040100
	v_cndmask_b32_e64 v250, v250, v251, s[10:11]
	s_branch .LBB0_1557

.LBB0_1569:
	s_and_b32 s25, s42, 0x300
	v_or_b32_e32 v158, s25, v149
	v_add_lshl_u32 v159, v148, s40, 11
	v_lshl_or_b32 v227, v158, 1, v159
	s_cmpk_gt_i32 s42, 0x3ff
	s_mov_b64 s[40:41], -1
	v_add_u32_e32 v226, 0x1000, v227
	v_or_b32_e32 v225, 32, v227
	v_add_u32_e32 v224, 0x1020, v227
	v_or_b32_e32 v223, 0x100, v227
	v_add_u32_e32 v222, 0x1100, v227
	v_or_b32_e32 v221, 0x120, v227
	v_add_u32_e32 v220, 0x1120, v227
	v_add_u32_e32 v219, 0x8000, v227
	v_add_u32_e32 v218, 0x9000, v227
	v_add_u32_e32 v217, 0x8020, v227
	v_add_u32_e32 v216, 0x9020, v227
	v_add_u32_e32 v215, 0x8100, v227
	v_add_u32_e32 v214, 0x9100, v227
	v_add_u32_e32 v213, 0x8120, v227
	v_add_u32_e32 v212, 0x9120, v227
	v_add_u32_e32 v211, 0x10000, v227
	v_add_u32_e32 v210, 0x11000, v227
	v_add_u32_e32 v209, 0x10020, v227
	v_add_u32_e32 v208, 0x11020, v227
	v_add_u32_e32 v207, 0x10100, v227
	v_add_u32_e32 v206, 0x11100, v227
	v_add_u32_e32 v205, 0x10120, v227
	v_add_u32_e32 v204, 0x11120, v227
	v_add_u32_e32 v203, 0x18000, v227
	v_add_u32_e32 v202, 0x19000, v227
	v_add_u32_e32 v201, 0x18020, v227
	v_add_u32_e32 v200, 0x19020, v227
	v_add_u32_e32 v199, 0x18100, v227
	v_add_u32_e32 v198, 0x19100, v227
	v_add_u32_e32 v197, 0x18120, v227
	v_add_u32_e32 v196, 0x19120, v227
	v_add_u32_e32 v195, 0x40000, v227
	v_add_u32_e32 v194, 0x41000, v227
	v_add_u32_e32 v193, 0x40020, v227
	v_add_u32_e32 v192, 0x41020, v227
	v_add_u32_e32 v191, 0x40100, v227
	v_add_u32_e32 v190, 0x41100, v227
	v_add_u32_e32 v189, 0x40120, v227
	v_add_u32_e32 v188, 0x41120, v227
	v_add_u32_e32 v187, 0x48000, v227
	v_add_u32_e32 v186, 0x49000, v227
	v_add_u32_e32 v185, 0x48020, v227
	v_add_u32_e32 v184, 0x49020, v227
	v_add_u32_e32 v183, 0x48100, v227
	v_add_u32_e32 v182, 0x49100, v227
	v_add_u32_e32 v181, 0x48120, v227
	v_add_u32_e32 v180, 0x49120, v227
	v_add_u32_e32 v173, 0x50000, v227
	v_add_u32_e32 v172, 0x51000, v227
	v_add_u32_e32 v171, 0x50020, v227
	v_add_u32_e32 v170, 0x51020, v227
	v_add_u32_e32 v169, 0x50100, v227
	v_add_u32_e32 v168, 0x51100, v227
	v_add_u32_e32 v167, 0x50120, v227
	v_add_u32_e32 v166, 0x51120, v227
	v_add_u32_e32 v165, 0x58000, v227
	v_add_u32_e32 v164, 0x59000, v227
	v_add_u32_e32 v163, 0x58020, v227
	v_add_u32_e32 v162, 0x59020, v227
	v_add_u32_e32 v161, 0x58100, v227
	v_add_u32_e32 v160, 0x59100, v227
	v_add_u32_e32 v159, 0x58120, v227
	v_add_u32_e32 v158, 0x59120, v227
	s_cbranch_scc1 .LBB0_1571
	v_cvt_pk_bf16_f32 v178, v124, v125
	s_nop 1
	v_mov_b32_dpp v179, v178 quad_perm:[1,0,3,2] row_mask:0xf bank_mask:0xf
	v_perm_b32 v178, v179, v178, v250
	global_store_dword v227, v178, s[2:3]
	v_cvt_pk_bf16_f32 v178, v126, v127
	s_nop 1
	v_mov_b32_dpp v179, v178 quad_perm:[1,0,3,2] row_mask:0xf bank_mask:0xf
	v_perm_b32 v178, v179, v178, v250
	global_store_dword v226, v178, s[2:3]
	v_cvt_pk_bf16_f32 v178, v120, v121
	s_nop 1
	v_mov_b32_dpp v179, v178 quad_perm:[1,0,3,2] row_mask:0xf bank_mask:0xf
	v_perm_b32 v178, v179, v178, v250
	global_store_dword v225, v178, s[2:3]
	v_cvt_pk_bf16_f32 v178, v122, v123
	s_nop 1
	v_mov_b32_dpp v179, v178 quad_perm:[1,0,3,2] row_mask:0xf bank_mask:0xf
	v_perm_b32 v178, v179, v178, v250
	global_store_dword v224, v178, s[2:3]
	v_cvt_pk_bf16_f32 v178, v116, v117
	s_nop 1
	v_mov_b32_dpp v179, v178 quad_perm:[1,0,3,2] row_mask:0xf bank_mask:0xf
	v_perm_b32 v178, v179, v178, v250
	global_store_dword v223, v178, s[2:3]
	v_cvt_pk_bf16_f32 v178, v118, v119
	s_nop 1
	v_mov_b32_dpp v179, v178 quad_perm:[1,0,3,2] row_mask:0xf bank_mask:0xf
	v_perm_b32 v178, v179, v178, v250
	global_store_dword v222, v178, s[2:3]
	v_cvt_pk_bf16_f32 v178, v112, v113
	s_nop 1
	v_mov_b32_dpp v179, v178 quad_perm:[1,0,3,2] row_mask:0xf bank_mask:0xf
	v_perm_b32 v178, v179, v178, v250
	global_store_dword v221, v178, s[2:3]
	v_cvt_pk_bf16_f32 v178, v114, v115
	s_nop 1
	v_mov_b32_dpp v179, v178 quad_perm:[1,0,3,2] row_mask:0xf bank_mask:0xf
	v_perm_b32 v178, v179, v178, v250
	global_store_dword v220, v178, s[2:3]
	v_cvt_pk_bf16_f32 v178, v108, v109
	s_nop 1
	v_mov_b32_dpp v179, v178 quad_perm:[1,0,3,2] row_mask:0xf bank_mask:0xf
	v_perm_b32 v178, v179, v178, v250
	global_store_dword v219, v178, s[2:3]
	v_cvt_pk_bf16_f32 v178, v110, v111
	s_nop 1
	v_mov_b32_dpp v179, v178 quad_perm:[1,0,3,2] row_mask:0xf bank_mask:0xf
	v_perm_b32 v178, v179, v178, v250
	global_store_dword v218, v178, s[2:3]
	v_cvt_pk_bf16_f32 v178, v104, v105
	s_nop 1
	v_mov_b32_dpp v179, v178 quad_perm:[1,0,3,2] row_mask:0xf bank_mask:0xf
	v_perm_b32 v178, v179, v178, v250
	global_store_dword v217, v178, s[2:3]
	v_cvt_pk_bf16_f32 v178, v106, v107
	s_nop 1
	v_mov_b32_dpp v179, v178 quad_perm:[1,0,3,2] row_mask:0xf bank_mask:0xf
	v_perm_b32 v178, v179, v178, v250
	global_store_dword v216, v178, s[2:3]
	v_cvt_pk_bf16_f32 v178, v100, v101
	s_nop 1
	v_mov_b32_dpp v179, v178 quad_perm:[1,0,3,2] row_mask:0xf bank_mask:0xf
	v_perm_b32 v178, v179, v178, v250
	global_store_dword v215, v178, s[2:3]
	v_cvt_pk_bf16_f32 v178, v102, v103
	s_nop 1
	v_mov_b32_dpp v179, v178 quad_perm:[1,0,3,2] row_mask:0xf bank_mask:0xf
	v_perm_b32 v178, v179, v178, v250
	global_store_dword v214, v178, s[2:3]
	v_cvt_pk_bf16_f32 v178, v96, v97
	s_nop 1
	v_mov_b32_dpp v179, v178 quad_perm:[1,0,3,2] row_mask:0xf bank_mask:0xf
	v_perm_b32 v178, v179, v178, v250
	global_store_dword v213, v178, s[2:3]
	v_cvt_pk_bf16_f32 v178, v98, v99
	s_nop 1
	v_mov_b32_dpp v179, v178 quad_perm:[1,0,3,2] row_mask:0xf bank_mask:0xf
	v_perm_b32 v178, v179, v178, v250
	global_store_dword v212, v178, s[2:3]
	v_cvt_pk_bf16_f32 v178, v92, v93
	s_nop 1
	v_mov_b32_dpp v179, v178 quad_perm:[1,0,3,2] row_mask:0xf bank_mask:0xf
	v_perm_b32 v178, v179, v178, v250
	global_store_dword v211, v178, s[2:3]
	v_cvt_pk_bf16_f32 v178, v94, v95
	s_nop 1
	v_mov_b32_dpp v179, v178 quad_perm:[1,0,3,2] row_mask:0xf bank_mask:0xf
	v_perm_b32 v178, v179, v178, v250
	global_store_dword v210, v178, s[2:3]
	v_cvt_pk_bf16_f32 v178, v88, v89
	s_nop 1
	v_mov_b32_dpp v179, v178 quad_perm:[1,0,3,2] row_mask:0xf bank_mask:0xf
	v_perm_b32 v178, v179, v178, v250
	global_store_dword v209, v178, s[2:3]
	v_cvt_pk_bf16_f32 v178, v90, v91
	s_nop 1
	v_mov_b32_dpp v179, v178 quad_perm:[1,0,3,2] row_mask:0xf bank_mask:0xf
	v_perm_b32 v178, v179, v178, v250
	global_store_dword v208, v178, s[2:3]
	v_cvt_pk_bf16_f32 v178, v84, v85
	s_nop 1
	v_mov_b32_dpp v179, v178 quad_perm:[1,0,3,2] row_mask:0xf bank_mask:0xf
	v_perm_b32 v178, v179, v178, v250
	global_store_dword v207, v178, s[2:3]
	v_cvt_pk_bf16_f32 v178, v86, v87
	s_nop 1
	v_mov_b32_dpp v179, v178 quad_perm:[1,0,3,2] row_mask:0xf bank_mask:0xf
	v_perm_b32 v178, v179, v178, v250
	global_store_dword v206, v178, s[2:3]
	v_cvt_pk_bf16_f32 v178, v80, v81
	s_nop 1
	v_mov_b32_dpp v179, v178 quad_perm:[1,0,3,2] row_mask:0xf bank_mask:0xf
	v_perm_b32 v178, v179, v178, v250
	global_store_dword v205, v178, s[2:3]
	v_cvt_pk_bf16_f32 v178, v82, v83
	s_nop 1
	v_mov_b32_dpp v179, v178 quad_perm:[1,0,3,2] row_mask:0xf bank_mask:0xf
	v_perm_b32 v178, v179, v178, v250
	global_store_dword v204, v178, s[2:3]
	v_cvt_pk_bf16_f32 v178, v76, v77
	s_nop 1
	v_mov_b32_dpp v179, v178 quad_perm:[1,0,3,2] row_mask:0xf bank_mask:0xf
	v_perm_b32 v178, v179, v178, v250
	global_store_dword v203, v178, s[2:3]
	v_cvt_pk_bf16_f32 v178, v78, v79
	s_nop 1
	v_mov_b32_dpp v179, v178 quad_perm:[1,0,3,2] row_mask:0xf bank_mask:0xf
	v_perm_b32 v178, v179, v178, v250
	global_store_dword v202, v178, s[2:3]
	v_cvt_pk_bf16_f32 v178, v72, v73
	s_nop 1
	v_mov_b32_dpp v179, v178 quad_perm:[1,0,3,2] row_mask:0xf bank_mask:0xf
	v_perm_b32 v178, v179, v178, v250
	global_store_dword v201, v178, s[2:3]
	v_cvt_pk_bf16_f32 v178, v74, v75
	s_nop 1
	v_mov_b32_dpp v179, v178 quad_perm:[1,0,3,2] row_mask:0xf bank_mask:0xf
	v_perm_b32 v178, v179, v178, v250
	global_store_dword v200, v178, s[2:3]
	v_cvt_pk_bf16_f32 v178, v68, v69
	s_nop 1
	v_mov_b32_dpp v179, v178 quad_perm:[1,0,3,2] row_mask:0xf bank_mask:0xf
	v_perm_b32 v178, v179, v178, v250
	global_store_dword v199, v178, s[2:3]
	v_cvt_pk_bf16_f32 v178, v70, v71
	s_nop 1
	v_mov_b32_dpp v179, v178 quad_perm:[1,0,3,2] row_mask:0xf bank_mask:0xf
	v_perm_b32 v178, v179, v178, v250
	global_store_dword v198, v178, s[2:3]
	v_cvt_pk_bf16_f32 v178, v64, v65
	s_nop 1
	v_mov_b32_dpp v179, v178 quad_perm:[1,0,3,2] row_mask:0xf bank_mask:0xf
	v_perm_b32 v178, v179, v178, v250
	global_store_dword v197, v178, s[2:3]
	v_cvt_pk_bf16_f32 v178, v66, v67
	s_nop 1
	v_mov_b32_dpp v179, v178 quad_perm:[1,0,3,2] row_mask:0xf bank_mask:0xf
	v_perm_b32 v178, v179, v178, v250
	global_store_dword v196, v178, s[2:3]
	v_cvt_pk_bf16_f32 v178, v60, v61
	s_nop 1
	v_mov_b32_dpp v179, v178 quad_perm:[1,0,3,2] row_mask:0xf bank_mask:0xf
	v_perm_b32 v178, v179, v178, v250
	global_store_dword v195, v178, s[2:3]
	v_cvt_pk_bf16_f32 v178, v62, v63
	s_nop 1
	v_mov_b32_dpp v179, v178 quad_perm:[1,0,3,2] row_mask:0xf bank_mask:0xf
	v_perm_b32 v178, v179, v178, v250
	global_store_dword v194, v178, s[2:3]
	v_cvt_pk_bf16_f32 v178, v56, v57
	s_nop 1
	v_mov_b32_dpp v179, v178 quad_perm:[1,0,3,2] row_mask:0xf bank_mask:0xf
	v_perm_b32 v178, v179, v178, v250
	global_store_dword v193, v178, s[2:3]
	v_cvt_pk_bf16_f32 v178, v58, v59
	s_nop 1
	v_mov_b32_dpp v179, v178 quad_perm:[1,0,3,2] row_mask:0xf bank_mask:0xf
	v_perm_b32 v178, v179, v178, v250
	global_store_dword v192, v178, s[2:3]
	v_cvt_pk_bf16_f32 v178, v52, v53
	s_nop 1
	v_mov_b32_dpp v179, v178 quad_perm:[1,0,3,2] row_mask:0xf bank_mask:0xf
	v_perm_b32 v178, v179, v178, v250
	global_store_dword v191, v178, s[2:3]
	v_cvt_pk_bf16_f32 v178, v54, v55
	s_nop 1
	v_mov_b32_dpp v179, v178 quad_perm:[1,0,3,2] row_mask:0xf bank_mask:0xf
	v_perm_b32 v178, v179, v178, v250
	global_store_dword v190, v178, s[2:3]
	v_cvt_pk_bf16_f32 v178, v48, v49
	s_nop 1
	v_mov_b32_dpp v179, v178 quad_perm:[1,0,3,2] row_mask:0xf bank_mask:0xf
	v_perm_b32 v178, v179, v178, v250
	global_store_dword v189, v178, s[2:3]
	v_cvt_pk_bf16_f32 v178, v50, v51
	s_nop 1
	v_mov_b32_dpp v179, v178 quad_perm:[1,0,3,2] row_mask:0xf bank_mask:0xf
	v_perm_b32 v178, v179, v178, v250
	global_store_dword v188, v178, s[2:3]
	v_cvt_pk_bf16_f32 v178, v44, v45
	s_nop 1
	v_mov_b32_dpp v179, v178 quad_perm:[1,0,3,2] row_mask:0xf bank_mask:0xf
	v_perm_b32 v178, v179, v178, v250
	global_store_dword v187, v178, s[2:3]
	v_cvt_pk_bf16_f32 v178, v46, v47
	s_nop 1
	v_mov_b32_dpp v179, v178 quad_perm:[1,0,3,2] row_mask:0xf bank_mask:0xf
	v_perm_b32 v178, v179, v178, v250
	global_store_dword v186, v178, s[2:3]
	v_cvt_pk_bf16_f32 v178, v40, v41
	s_nop 1
	v_mov_b32_dpp v179, v178 quad_perm:[1,0,3,2] row_mask:0xf bank_mask:0xf
	v_perm_b32 v178, v179, v178, v250
	global_store_dword v185, v178, s[2:3]
	v_cvt_pk_bf16_f32 v178, v42, v43
	s_nop 1
	v_mov_b32_dpp v179, v178 quad_perm:[1,0,3,2] row_mask:0xf bank_mask:0xf
	v_perm_b32 v178, v179, v178, v250
	global_store_dword v184, v178, s[2:3]
	v_cvt_pk_bf16_f32 v178, v36, v37
	s_nop 1
	v_mov_b32_dpp v179, v178 quad_perm:[1,0,3,2] row_mask:0xf bank_mask:0xf
	v_perm_b32 v178, v179, v178, v250
	global_store_dword v183, v178, s[2:3]
	v_cvt_pk_bf16_f32 v178, v38, v39
	s_nop 1
	v_mov_b32_dpp v179, v178 quad_perm:[1,0,3,2] row_mask:0xf bank_mask:0xf
	v_perm_b32 v178, v179, v178, v250
	global_store_dword v182, v178, s[2:3]
	v_cvt_pk_bf16_f32 v178, v32, v33
	s_nop 1
	v_mov_b32_dpp v179, v178 quad_perm:[1,0,3,2] row_mask:0xf bank_mask:0xf
	v_perm_b32 v178, v179, v178, v250
	global_store_dword v181, v178, s[2:3]
	v_cvt_pk_bf16_f32 v178, v34, v35
	s_nop 1
	v_mov_b32_dpp v179, v178 quad_perm:[1,0,3,2] row_mask:0xf bank_mask:0xf
	v_perm_b32 v178, v179, v178, v250
	global_store_dword v180, v178, s[2:3]
	v_cvt_pk_bf16_f32 v178, v28, v29
	s_nop 1
	v_mov_b32_dpp v179, v178 quad_perm:[1,0,3,2] row_mask:0xf bank_mask:0xf
	v_perm_b32 v178, v179, v178, v250
	global_store_dword v173, v178, s[2:3]
	v_cvt_pk_bf16_f32 v178, v30, v31
	s_nop 1
	v_mov_b32_dpp v179, v178 quad_perm:[1,0,3,2] row_mask:0xf bank_mask:0xf
	v_perm_b32 v178, v179, v178, v250
	global_store_dword v172, v178, s[2:3]
	v_cvt_pk_bf16_f32 v178, v24, v25
	s_nop 1
	v_mov_b32_dpp v179, v178 quad_perm:[1,0,3,2] row_mask:0xf bank_mask:0xf
	v_perm_b32 v178, v179, v178, v250
	global_store_dword v171, v178, s[2:3]
	v_cvt_pk_bf16_f32 v178, v26, v27
	s_nop 1
	v_mov_b32_dpp v179, v178 quad_perm:[1,0,3,2] row_mask:0xf bank_mask:0xf
	v_perm_b32 v178, v179, v178, v250
	global_store_dword v170, v178, s[2:3]
	v_cvt_pk_bf16_f32 v178, v20, v21
	s_nop 1
	v_mov_b32_dpp v179, v178 quad_perm:[1,0,3,2] row_mask:0xf bank_mask:0xf
	v_perm_b32 v178, v179, v178, v250
	global_store_dword v169, v178, s[2:3]
	v_cvt_pk_bf16_f32 v178, v22, v23
	s_nop 1
	v_mov_b32_dpp v179, v178 quad_perm:[1,0,3,2] row_mask:0xf bank_mask:0xf
	v_perm_b32 v178, v179, v178, v250
	global_store_dword v168, v178, s[2:3]
	v_cvt_pk_bf16_f32 v178, v16, v17
	s_nop 1
	v_mov_b32_dpp v179, v178 quad_perm:[1,0,3,2] row_mask:0xf bank_mask:0xf
	v_perm_b32 v178, v179, v178, v250
	global_store_dword v167, v178, s[2:3]
	v_cvt_pk_bf16_f32 v178, v18, v19
	s_nop 1
	v_mov_b32_dpp v179, v178 quad_perm:[1,0,3,2] row_mask:0xf bank_mask:0xf
	v_perm_b32 v178, v179, v178, v250
	global_store_dword v166, v178, s[2:3]
	v_cvt_pk_bf16_f32 v178, v12, v13
	s_nop 1
	v_mov_b32_dpp v179, v178 quad_perm:[1,0,3,2] row_mask:0xf bank_mask:0xf
	v_perm_b32 v178, v179, v178, v250
	global_store_dword v165, v178, s[2:3]
	v_cvt_pk_bf16_f32 v178, v14, v15
	s_nop 1
	v_mov_b32_dpp v179, v178 quad_perm:[1,0,3,2] row_mask:0xf bank_mask:0xf
	v_perm_b32 v178, v179, v178, v250
	global_store_dword v164, v178, s[2:3]
	v_cvt_pk_bf16_f32 v178, v8, v9
	s_nop 1
	v_mov_b32_dpp v179, v178 quad_perm:[1,0,3,2] row_mask:0xf bank_mask:0xf
	v_perm_b32 v178, v179, v178, v250
	global_store_dword v163, v178, s[2:3]
	v_cvt_pk_bf16_f32 v178, v10, v11
	s_nop 1
	v_mov_b32_dpp v179, v178 quad_perm:[1,0,3,2] row_mask:0xf bank_mask:0xf
	v_perm_b32 v178, v179, v178, v250
	global_store_dword v162, v178, s[2:3]
	v_cvt_pk_bf16_f32 v178, v4, v5
	s_nop 1
	v_mov_b32_dpp v179, v178 quad_perm:[1,0,3,2] row_mask:0xf bank_mask:0xf
	v_perm_b32 v178, v179, v178, v250
	global_store_dword v161, v178, s[2:3]
	v_cvt_pk_bf16_f32 v178, v6, v7
	s_nop 1
	v_mov_b32_dpp v179, v178 quad_perm:[1,0,3,2] row_mask:0xf bank_mask:0xf
	v_perm_b32 v178, v179, v178, v250
	global_store_dword v160, v178, s[2:3]
	v_cvt_pk_bf16_f32 v178, v0, v1
	s_nop 1
	v_mov_b32_dpp v179, v178 quad_perm:[1,0,3,2] row_mask:0xf bank_mask:0xf
	v_perm_b32 v178, v179, v178, v250
	global_store_dword v159, v178, s[2:3]
	v_cvt_pk_bf16_f32 v178, v2, v3
	s_nop 1
	v_mov_b32_dpp v179, v178 quad_perm:[1,0,3,2] row_mask:0xf bank_mask:0xf
	v_perm_b32 v178, v179, v178, v250
	global_store_dword v158, v178, s[2:3]
	s_cbranch_execnz .LBB0_1556
	s_branch .LBB0_1572

.LBB0_1572:
	v_mul_f32_e32 v124, 0xbfb8aa3b, v124
	v_mul_f32_e32 v125, 0xbfb8aa3b, v125
	v_exp_f32_e32 v124, v124
	v_exp_f32_e32 v125, v125
	v_mul_f32_e32 v126, 0xbfb8aa3b, v126
	v_mul_f32_e32 v127, 0xbfb8aa3b, v127
	v_add_f32_e32 v124, 1.0, v124
	v_add_f32_e32 v125, 1.0, v125
	v_exp_f32_e32 v126, v126
	v_exp_f32_e32 v127, v127
	v_rcp_f32_e32 v124, v124
	v_rcp_f32_e32 v125, v125
	v_mul_f32_e32 v120, 0xbfb8aa3b, v120
	v_mul_f32_e32 v121, 0xbfb8aa3b, v121
	v_add_f32_e32 v126, 1.0, v126
	v_add_f32_e32 v127, 1.0, v127
	v_exp_f32_e32 v120, v120
	v_exp_f32_e32 v121, v121
	v_mov_b32_e32 v178, v129
	v_cndmask_b32_e64 v179, v124, v125, s[10:11]
	v_rcp_f32_e32 v126, v126
	v_rcp_f32_e32 v127, v127
	v_mov_b32_dpp v178, v179 quad_perm:[1,0,3,2] row_mask:0xf bank_mask:0xf
	v_cndmask_b32_e64 v124, v178, v124, s[10:11]
	v_mul_f32_e32 v122, 0xbfb8aa3b, v122
	v_mul_f32_e32 v123, 0xbfb8aa3b, v123
	v_cndmask_b32_e64 v125, v125, v178, s[10:11]
	v_cvt_pk_bf16_f32 v124, v124, v125
	v_add_f32_e32 v120, 1.0, v120
	v_add_f32_e32 v121, 1.0, v121
	v_exp_f32_e32 v122, v122
	v_exp_f32_e32 v123, v123
	global_store_dword v227, v124, s[12:13]
	v_cndmask_b32_e64 v124, v126, v127, s[10:11]
	v_mov_b32_e32 v125, v129
	v_rcp_f32_e32 v120, v120
	v_rcp_f32_e32 v121, v121
	v_mov_b32_dpp v125, v124 quad_perm:[1,0,3,2] row_mask:0xf bank_mask:0xf
	v_cndmask_b32_e64 v124, v125, v126, s[10:11]
	v_mul_f32_e32 v116, 0xbfb8aa3b, v116
	v_mul_f32_e32 v117, 0xbfb8aa3b, v117
	v_cndmask_b32_e64 v125, v127, v125, s[10:11]
	v_cvt_pk_bf16_f32 v124, v124, v125
	v_add_f32_e32 v122, 1.0, v122
	v_add_f32_e32 v123, 1.0, v123
	v_exp_f32_e32 v116, v116
	v_exp_f32_e32 v117, v117
	global_store_dword v226, v124, s[12:13]
	v_cndmask_b32_e64 v124, v120, v121, s[10:11]
	v_mov_b32_e32 v125, v129
	v_rcp_f32_e32 v122, v122
	v_rcp_f32_e32 v123, v123
	v_mov_b32_dpp v125, v124 quad_perm:[1,0,3,2] row_mask:0xf bank_mask:0xf
	v_cndmask_b32_e64 v120, v125, v120, s[10:11]
	v_mul_f32_e32 v118, 0xbfb8aa3b, v118
	v_mul_f32_e32 v119, 0xbfb8aa3b, v119
	v_cndmask_b32_e64 v121, v121, v125, s[10:11]
	v_cvt_pk_bf16_f32 v120, v120, v121
	v_add_f32_e32 v116, 1.0, v116
	v_add_f32_e32 v117, 1.0, v117
	v_exp_f32_e32 v118, v118
	v_exp_f32_e32 v119, v119
	global_store_dword v225, v120, s[12:13]
	v_cndmask_b32_e64 v120, v122, v123, s[10:11]
	v_mov_b32_e32 v121, v129
	v_rcp_f32_e32 v116, v116
	v_rcp_f32_e32 v117, v117
	v_mov_b32_dpp v121, v120 quad_perm:[1,0,3,2] row_mask:0xf bank_mask:0xf
	v_cndmask_b32_e64 v120, v121, v122, s[10:11]
	v_mul_f32_e32 v112, 0xbfb8aa3b, v112
	v_mul_f32_e32 v113, 0xbfb8aa3b, v113
	v_cndmask_b32_e64 v121, v123, v121, s[10:11]
	v_cvt_pk_bf16_f32 v120, v120, v121
	v_add_f32_e32 v118, 1.0, v118
	v_add_f32_e32 v119, 1.0, v119
	v_exp_f32_e32 v112, v112
	v_exp_f32_e32 v113, v113
	global_store_dword v224, v120, s[12:13]
	v_cndmask_b32_e64 v120, v116, v117, s[10:11]
	v_mov_b32_e32 v121, v129
	v_rcp_f32_e32 v118, v118
	v_rcp_f32_e32 v119, v119
	v_mov_b32_dpp v121, v120 quad_perm:[1,0,3,2] row_mask:0xf bank_mask:0xf
	v_cndmask_b32_e64 v116, v121, v116, s[10:11]
	v_mul_f32_e32 v114, 0xbfb8aa3b, v114
	v_mul_f32_e32 v115, 0xbfb8aa3b, v115
	v_cndmask_b32_e64 v117, v117, v121, s[10:11]
	v_cvt_pk_bf16_f32 v116, v116, v117
	v_add_f32_e32 v112, 1.0, v112
	v_add_f32_e32 v113, 1.0, v113
	v_exp_f32_e32 v114, v114
	v_exp_f32_e32 v115, v115
	global_store_dword v223, v116, s[12:13]
	v_cndmask_b32_e64 v116, v118, v119, s[10:11]
	v_mov_b32_e32 v117, v129
	v_rcp_f32_e32 v112, v112
	v_rcp_f32_e32 v113, v113
	v_mov_b32_dpp v117, v116 quad_perm:[1,0,3,2] row_mask:0xf bank_mask:0xf
	v_cndmask_b32_e64 v116, v117, v118, s[10:11]
	v_cndmask_b32_e64 v117, v119, v117, s[10:11]
	v_cvt_pk_bf16_f32 v116, v116, v117
	v_add_f32_e32 v114, 1.0, v114
	v_add_f32_e32 v115, 1.0, v115
	global_store_dword v222, v116, s[12:13]
	v_cndmask_b32_e64 v116, v112, v113, s[10:11]
	v_mov_b32_e32 v117, v129
	v_rcp_f32_e32 v114, v114
	v_rcp_f32_e32 v115, v115
	v_mov_b32_dpp v117, v116 quad_perm:[1,0,3,2] row_mask:0xf bank_mask:0xf
	v_cndmask_b32_e64 v112, v117, v112, s[10:11]
	v_cndmask_b32_e64 v113, v113, v117, s[10:11]
	v_cvt_pk_bf16_f32 v112, v112, v113
	global_store_dword v221, v112, s[12:13]
	v_cvt_pk_bf16_f32 v112, v114, v115
	s_nop 1
	v_mov_b32_dpp v113, v112 quad_perm:[1,0,3,2] row_mask:0xf bank_mask:0xf
	v_perm_b32 v112, v113, v112, v250
	global_store_dword v220, v112, s[12:13]
	v_mul_f32_e32 v108, 0xbfb8aa3b, v108
	v_mul_f32_e32 v109, 0xbfb8aa3b, v109
	v_exp_f32_e32 v108, v108
	v_exp_f32_e32 v109, v109
	v_mul_f32_e32 v110, 0xbfb8aa3b, v110
	v_mul_f32_e32 v111, 0xbfb8aa3b, v111
	v_add_f32_e32 v108, 1.0, v108
	v_add_f32_e32 v109, 1.0, v109
	v_exp_f32_e32 v110, v110
	v_exp_f32_e32 v111, v111
	v_rcp_f32_e32 v108, v108
	v_rcp_f32_e32 v109, v109
	v_mul_f32_e32 v104, 0xbfb8aa3b, v104
	v_mul_f32_e32 v105, 0xbfb8aa3b, v105
	v_add_f32_e32 v110, 1.0, v110
	v_add_f32_e32 v111, 1.0, v111
	v_exp_f32_e32 v104, v104
	v_exp_f32_e32 v105, v105
	v_mov_b32_e32 v112, v129
	v_cndmask_b32_e64 v113, v108, v109, s[10:11]
	v_rcp_f32_e32 v110, v110
	v_rcp_f32_e32 v111, v111
	v_mov_b32_dpp v112, v113 quad_perm:[1,0,3,2] row_mask:0xf bank_mask:0xf
	v_cndmask_b32_e64 v108, v112, v108, s[10:11]
	v_mul_f32_e32 v106, 0xbfb8aa3b, v106
	v_mul_f32_e32 v107, 0xbfb8aa3b, v107
	v_cndmask_b32_e64 v109, v109, v112, s[10:11]
	v_cvt_pk_bf16_f32 v108, v108, v109
	v_add_f32_e32 v104, 1.0, v104
	v_add_f32_e32 v105, 1.0, v105
	v_exp_f32_e32 v106, v106
	v_exp_f32_e32 v107, v107
	global_store_dword v219, v108, s[12:13]
	v_cndmask_b32_e64 v108, v110, v111, s[10:11]
	v_mov_b32_e32 v109, v129
	v_rcp_f32_e32 v104, v104
	v_rcp_f32_e32 v105, v105
	v_mov_b32_dpp v109, v108 quad_perm:[1,0,3,2] row_mask:0xf bank_mask:0xf
	v_cndmask_b32_e64 v108, v109, v110, s[10:11]
	v_mul_f32_e32 v100, 0xbfb8aa3b, v100
	v_mul_f32_e32 v101, 0xbfb8aa3b, v101
	v_cndmask_b32_e64 v109, v111, v109, s[10:11]
	v_cvt_pk_bf16_f32 v108, v108, v109
	v_add_f32_e32 v106, 1.0, v106
	v_add_f32_e32 v107, 1.0, v107
	v_exp_f32_e32 v100, v100
	v_exp_f32_e32 v101, v101
	global_store_dword v218, v108, s[12:13]
	v_cndmask_b32_e64 v108, v104, v105, s[10:11]
	v_mov_b32_e32 v109, v129
	v_rcp_f32_e32 v106, v106
	v_rcp_f32_e32 v107, v107
	v_mov_b32_dpp v109, v108 quad_perm:[1,0,3,2] row_mask:0xf bank_mask:0xf
	v_cndmask_b32_e64 v104, v109, v104, s[10:11]
	v_mul_f32_e32 v102, 0xbfb8aa3b, v102
	v_mul_f32_e32 v103, 0xbfb8aa3b, v103
	v_cndmask_b32_e64 v105, v105, v109, s[10:11]
	v_cvt_pk_bf16_f32 v104, v104, v105
	v_add_f32_e32 v100, 1.0, v100
	v_add_f32_e32 v101, 1.0, v101
	v_exp_f32_e32 v102, v102
	v_exp_f32_e32 v103, v103
	global_store_dword v217, v104, s[12:13]
	v_cndmask_b32_e64 v104, v106, v107, s[10:11]
	v_mov_b32_e32 v105, v129
	v_rcp_f32_e32 v100, v100
	v_rcp_f32_e32 v101, v101
	v_mov_b32_dpp v105, v104 quad_perm:[1,0,3,2] row_mask:0xf bank_mask:0xf
	v_cndmask_b32_e64 v104, v105, v106, s[10:11]
	v_mul_f32_e32 v96, 0xbfb8aa3b, v96
	v_mul_f32_e32 v97, 0xbfb8aa3b, v97
	v_cndmask_b32_e64 v105, v107, v105, s[10:11]
	v_cvt_pk_bf16_f32 v104, v104, v105
	v_add_f32_e32 v102, 1.0, v102
	v_add_f32_e32 v103, 1.0, v103
	v_exp_f32_e32 v96, v96
	v_exp_f32_e32 v97, v97
	global_store_dword v216, v104, s[12:13]
	v_cndmask_b32_e64 v104, v100, v101, s[10:11]
	v_mov_b32_e32 v105, v129
	v_rcp_f32_e32 v102, v102
	v_rcp_f32_e32 v103, v103
	v_mov_b32_dpp v105, v104 quad_perm:[1,0,3,2] row_mask:0xf bank_mask:0xf
	v_cndmask_b32_e64 v100, v105, v100, s[10:11]
	v_mul_f32_e32 v98, 0xbfb8aa3b, v98
	v_mul_f32_e32 v99, 0xbfb8aa3b, v99
	v_cndmask_b32_e64 v101, v101, v105, s[10:11]
	v_cvt_pk_bf16_f32 v100, v100, v101
	v_add_f32_e32 v96, 1.0, v96
	v_add_f32_e32 v97, 1.0, v97
	v_exp_f32_e32 v98, v98
	v_exp_f32_e32 v99, v99
	global_store_dword v215, v100, s[12:13]
	v_cndmask_b32_e64 v100, v102, v103, s[10:11]
	v_mov_b32_e32 v101, v129
	v_rcp_f32_e32 v96, v96
	v_rcp_f32_e32 v97, v97
	v_mov_b32_dpp v101, v100 quad_perm:[1,0,3,2] row_mask:0xf bank_mask:0xf
	v_cndmask_b32_e64 v100, v101, v102, s[10:11]
	v_cndmask_b32_e64 v101, v103, v101, s[10:11]
	v_cvt_pk_bf16_f32 v100, v100, v101
	v_add_f32_e32 v98, 1.0, v98
	v_add_f32_e32 v99, 1.0, v99
	global_store_dword v214, v100, s[12:13]
	v_cndmask_b32_e64 v100, v96, v97, s[10:11]
	v_mov_b32_e32 v101, v129
	v_rcp_f32_e32 v98, v98
	v_rcp_f32_e32 v99, v99
	v_mov_b32_dpp v101, v100 quad_perm:[1,0,3,2] row_mask:0xf bank_mask:0xf
	v_cndmask_b32_e64 v96, v101, v96, s[10:11]
	v_cndmask_b32_e64 v97, v97, v101, s[10:11]
	v_cvt_pk_bf16_f32 v96, v96, v97
	global_store_dword v213, v96, s[12:13]
	v_cvt_pk_bf16_f32 v96, v98, v99
	s_nop 1
	v_mov_b32_dpp v97, v96 quad_perm:[1,0,3,2] row_mask:0xf bank_mask:0xf
	v_perm_b32 v96, v97, v96, v250
	global_store_dword v212, v96, s[12:13]
	v_mul_f32_e32 v92, 0xbfb8aa3b, v92
	v_mul_f32_e32 v93, 0xbfb8aa3b, v93
	v_exp_f32_e32 v92, v92
	v_exp_f32_e32 v93, v93
	v_mul_f32_e32 v94, 0xbfb8aa3b, v94
	v_mul_f32_e32 v95, 0xbfb8aa3b, v95
	v_add_f32_e32 v92, 1.0, v92
	v_add_f32_e32 v93, 1.0, v93
	v_exp_f32_e32 v94, v94
	v_exp_f32_e32 v95, v95
	v_rcp_f32_e32 v92, v92
	v_rcp_f32_e32 v93, v93
	v_mul_f32_e32 v88, 0xbfb8aa3b, v88
	v_mul_f32_e32 v89, 0xbfb8aa3b, v89
	v_add_f32_e32 v94, 1.0, v94
	v_add_f32_e32 v95, 1.0, v95
	v_exp_f32_e32 v88, v88
	v_exp_f32_e32 v89, v89
	v_mov_b32_e32 v96, v129
	v_cndmask_b32_e64 v97, v92, v93, s[10:11]
	v_rcp_f32_e32 v94, v94
	v_rcp_f32_e32 v95, v95
	v_mov_b32_dpp v96, v97 quad_perm:[1,0,3,2] row_mask:0xf bank_mask:0xf
	v_cndmask_b32_e64 v92, v96, v92, s[10:11]
	v_mul_f32_e32 v90, 0xbfb8aa3b, v90
	v_mul_f32_e32 v91, 0xbfb8aa3b, v91
	v_cndmask_b32_e64 v93, v93, v96, s[10:11]
	v_cvt_pk_bf16_f32 v92, v92, v93
	v_add_f32_e32 v88, 1.0, v88
	v_add_f32_e32 v89, 1.0, v89
	v_exp_f32_e32 v90, v90
	v_exp_f32_e32 v91, v91
	global_store_dword v211, v92, s[12:13]
	v_cndmask_b32_e64 v92, v94, v95, s[10:11]
	v_mov_b32_e32 v93, v129
	v_rcp_f32_e32 v88, v88
	v_rcp_f32_e32 v89, v89
	v_mov_b32_dpp v93, v92 quad_perm:[1,0,3,2] row_mask:0xf bank_mask:0xf
	v_cndmask_b32_e64 v92, v93, v94, s[10:11]
	v_mul_f32_e32 v84, 0xbfb8aa3b, v84
	v_mul_f32_e32 v85, 0xbfb8aa3b, v85
	v_cndmask_b32_e64 v93, v95, v93, s[10:11]
	v_cvt_pk_bf16_f32 v92, v92, v93
	v_add_f32_e32 v90, 1.0, v90
	v_add_f32_e32 v91, 1.0, v91
	v_exp_f32_e32 v84, v84
	v_exp_f32_e32 v85, v85
	global_store_dword v210, v92, s[12:13]
	v_cndmask_b32_e64 v92, v88, v89, s[10:11]
	v_mov_b32_e32 v93, v129
	v_rcp_f32_e32 v90, v90
	v_rcp_f32_e32 v91, v91
	v_mov_b32_dpp v93, v92 quad_perm:[1,0,3,2] row_mask:0xf bank_mask:0xf
	v_cndmask_b32_e64 v88, v93, v88, s[10:11]
	v_mul_f32_e32 v86, 0xbfb8aa3b, v86
	v_mul_f32_e32 v87, 0xbfb8aa3b, v87
	v_cndmask_b32_e64 v89, v89, v93, s[10:11]
	v_cvt_pk_bf16_f32 v88, v88, v89
	v_add_f32_e32 v84, 1.0, v84
	v_add_f32_e32 v85, 1.0, v85
	v_exp_f32_e32 v86, v86
	v_exp_f32_e32 v87, v87
	global_store_dword v209, v88, s[12:13]
	v_cndmask_b32_e64 v88, v90, v91, s[10:11]
	v_mov_b32_e32 v89, v129
	v_rcp_f32_e32 v84, v84
	v_rcp_f32_e32 v85, v85
	v_mov_b32_dpp v89, v88 quad_perm:[1,0,3,2] row_mask:0xf bank_mask:0xf
	v_cndmask_b32_e64 v88, v89, v90, s[10:11]
	v_mul_f32_e32 v80, 0xbfb8aa3b, v80
	v_mul_f32_e32 v81, 0xbfb8aa3b, v81
	v_cndmask_b32_e64 v89, v91, v89, s[10:11]
	v_cvt_pk_bf16_f32 v88, v88, v89
	v_add_f32_e32 v86, 1.0, v86
	v_add_f32_e32 v87, 1.0, v87
	v_exp_f32_e32 v80, v80
	v_exp_f32_e32 v81, v81
	global_store_dword v208, v88, s[12:13]
	v_cndmask_b32_e64 v88, v84, v85, s[10:11]
	v_mov_b32_e32 v89, v129
	v_rcp_f32_e32 v86, v86
	v_rcp_f32_e32 v87, v87
	v_mov_b32_dpp v89, v88 quad_perm:[1,0,3,2] row_mask:0xf bank_mask:0xf
	v_cndmask_b32_e64 v84, v89, v84, s[10:11]
	v_mul_f32_e32 v82, 0xbfb8aa3b, v82
	v_mul_f32_e32 v83, 0xbfb8aa3b, v83
	v_cndmask_b32_e64 v85, v85, v89, s[10:11]
	v_cvt_pk_bf16_f32 v84, v84, v85
	v_add_f32_e32 v80, 1.0, v80
	v_add_f32_e32 v81, 1.0, v81
	v_exp_f32_e32 v82, v82
	v_exp_f32_e32 v83, v83
	global_store_dword v207, v84, s[12:13]
	v_cndmask_b32_e64 v84, v86, v87, s[10:11]
	v_mov_b32_e32 v85, v129
	v_rcp_f32_e32 v80, v80
	v_rcp_f32_e32 v81, v81
	v_mov_b32_dpp v85, v84 quad_perm:[1,0,3,2] row_mask:0xf bank_mask:0xf
	v_cndmask_b32_e64 v84, v85, v86, s[10:11]
	v_cndmask_b32_e64 v85, v87, v85, s[10:11]
	v_cvt_pk_bf16_f32 v84, v84, v85
	v_add_f32_e32 v82, 1.0, v82
	v_add_f32_e32 v83, 1.0, v83
	global_store_dword v206, v84, s[12:13]
	v_cndmask_b32_e64 v84, v80, v81, s[10:11]
	v_mov_b32_e32 v85, v129
	v_rcp_f32_e32 v82, v82
	v_rcp_f32_e32 v83, v83
	v_mov_b32_dpp v85, v84 quad_perm:[1,0,3,2] row_mask:0xf bank_mask:0xf
	v_cndmask_b32_e64 v80, v85, v80, s[10:11]
	v_cndmask_b32_e64 v81, v81, v85, s[10:11]
	v_cvt_pk_bf16_f32 v80, v80, v81
	global_store_dword v205, v80, s[12:13]
	v_cvt_pk_bf16_f32 v80, v82, v83
	s_nop 1
	v_mov_b32_dpp v81, v80 quad_perm:[1,0,3,2] row_mask:0xf bank_mask:0xf
	v_perm_b32 v80, v81, v80, v250
	global_store_dword v204, v80, s[12:13]
	v_mul_f32_e32 v76, 0xbfb8aa3b, v76
	v_mul_f32_e32 v77, 0xbfb8aa3b, v77
	v_exp_f32_e32 v76, v76
	v_exp_f32_e32 v77, v77
	v_mul_f32_e32 v78, 0xbfb8aa3b, v78
	v_mul_f32_e32 v79, 0xbfb8aa3b, v79
	v_add_f32_e32 v76, 1.0, v76
	v_add_f32_e32 v77, 1.0, v77
	v_exp_f32_e32 v78, v78
	v_exp_f32_e32 v79, v79
	v_rcp_f32_e32 v76, v76
	v_rcp_f32_e32 v77, v77
	v_mul_f32_e32 v72, 0xbfb8aa3b, v72
	v_mul_f32_e32 v73, 0xbfb8aa3b, v73
	v_add_f32_e32 v78, 1.0, v78
	v_add_f32_e32 v79, 1.0, v79
	v_exp_f32_e32 v72, v72
	v_exp_f32_e32 v73, v73
	v_mov_b32_e32 v80, v129
	v_cndmask_b32_e64 v81, v76, v77, s[10:11]
	v_rcp_f32_e32 v78, v78
	v_rcp_f32_e32 v79, v79
	v_mov_b32_dpp v80, v81 quad_perm:[1,0,3,2] row_mask:0xf bank_mask:0xf
	v_cndmask_b32_e64 v76, v80, v76, s[10:11]
	v_mul_f32_e32 v74, 0xbfb8aa3b, v74
	v_mul_f32_e32 v75, 0xbfb8aa3b, v75
	v_cndmask_b32_e64 v77, v77, v80, s[10:11]
	v_cvt_pk_bf16_f32 v76, v76, v77
	v_add_f32_e32 v72, 1.0, v72
	v_add_f32_e32 v73, 1.0, v73
	v_exp_f32_e32 v74, v74
	v_exp_f32_e32 v75, v75
	global_store_dword v203, v76, s[12:13]
	v_cndmask_b32_e64 v76, v78, v79, s[10:11]
	v_mov_b32_e32 v77, v129
	v_rcp_f32_e32 v72, v72
	v_rcp_f32_e32 v73, v73
	v_mov_b32_dpp v77, v76 quad_perm:[1,0,3,2] row_mask:0xf bank_mask:0xf
	v_cndmask_b32_e64 v76, v77, v78, s[10:11]
	v_mul_f32_e32 v68, 0xbfb8aa3b, v68
	v_mul_f32_e32 v69, 0xbfb8aa3b, v69
	v_cndmask_b32_e64 v77, v79, v77, s[10:11]
	v_cvt_pk_bf16_f32 v76, v76, v77
	v_add_f32_e32 v74, 1.0, v74
	v_add_f32_e32 v75, 1.0, v75
	v_exp_f32_e32 v68, v68
	v_exp_f32_e32 v69, v69
	global_store_dword v202, v76, s[12:13]
	v_cndmask_b32_e64 v76, v72, v73, s[10:11]
	v_mov_b32_e32 v77, v129
	v_rcp_f32_e32 v74, v74
	v_rcp_f32_e32 v75, v75
	v_mov_b32_dpp v77, v76 quad_perm:[1,0,3,2] row_mask:0xf bank_mask:0xf
	v_cndmask_b32_e64 v72, v77, v72, s[10:11]
	v_mul_f32_e32 v70, 0xbfb8aa3b, v70
	v_mul_f32_e32 v71, 0xbfb8aa3b, v71
	v_cndmask_b32_e64 v73, v73, v77, s[10:11]
	v_cvt_pk_bf16_f32 v72, v72, v73
	v_add_f32_e32 v68, 1.0, v68
	v_add_f32_e32 v69, 1.0, v69
	v_exp_f32_e32 v70, v70
	v_exp_f32_e32 v71, v71
	global_store_dword v201, v72, s[12:13]
	v_cndmask_b32_e64 v72, v74, v75, s[10:11]
	v_mov_b32_e32 v73, v129
	v_rcp_f32_e32 v68, v68
	v_rcp_f32_e32 v69, v69
	v_mov_b32_dpp v73, v72 quad_perm:[1,0,3,2] row_mask:0xf bank_mask:0xf
	v_cndmask_b32_e64 v72, v73, v74, s[10:11]
	v_mul_f32_e32 v64, 0xbfb8aa3b, v64
	v_mul_f32_e32 v65, 0xbfb8aa3b, v65
	v_cndmask_b32_e64 v73, v75, v73, s[10:11]
	v_cvt_pk_bf16_f32 v72, v72, v73
	v_add_f32_e32 v70, 1.0, v70
	v_add_f32_e32 v71, 1.0, v71
	v_exp_f32_e32 v64, v64
	v_exp_f32_e32 v65, v65
	global_store_dword v200, v72, s[12:13]
	v_cndmask_b32_e64 v72, v68, v69, s[10:11]
	v_mov_b32_e32 v73, v129
	v_rcp_f32_e32 v70, v70
	v_rcp_f32_e32 v71, v71
	v_mov_b32_dpp v73, v72 quad_perm:[1,0,3,2] row_mask:0xf bank_mask:0xf
	v_cndmask_b32_e64 v68, v73, v68, s[10:11]
	v_mul_f32_e32 v66, 0xbfb8aa3b, v66
	v_mul_f32_e32 v67, 0xbfb8aa3b, v67
	v_cndmask_b32_e64 v69, v69, v73, s[10:11]
	v_cvt_pk_bf16_f32 v68, v68, v69
	v_add_f32_e32 v64, 1.0, v64
	v_add_f32_e32 v65, 1.0, v65
	v_exp_f32_e32 v66, v66
	v_exp_f32_e32 v67, v67
	global_store_dword v199, v68, s[12:13]
	v_cndmask_b32_e64 v68, v70, v71, s[10:11]
	v_mov_b32_e32 v69, v129
	v_rcp_f32_e32 v64, v64
	v_rcp_f32_e32 v65, v65
	v_mov_b32_dpp v69, v68 quad_perm:[1,0,3,2] row_mask:0xf bank_mask:0xf
	v_cndmask_b32_e64 v68, v69, v70, s[10:11]
	v_cndmask_b32_e64 v69, v71, v69, s[10:11]
	v_cvt_pk_bf16_f32 v68, v68, v69
	v_add_f32_e32 v66, 1.0, v66
	v_add_f32_e32 v67, 1.0, v67
	global_store_dword v198, v68, s[12:13]
	v_cndmask_b32_e64 v68, v64, v65, s[10:11]
	v_mov_b32_e32 v69, v129
	v_rcp_f32_e32 v66, v66
	v_rcp_f32_e32 v67, v67
	v_mov_b32_dpp v69, v68 quad_perm:[1,0,3,2] row_mask:0xf bank_mask:0xf
	v_cndmask_b32_e64 v64, v69, v64, s[10:11]
	v_cndmask_b32_e64 v65, v65, v69, s[10:11]
	v_cvt_pk_bf16_f32 v64, v64, v65
	global_store_dword v197, v64, s[12:13]
	v_cvt_pk_bf16_f32 v64, v66, v67
	s_nop 1
	v_mov_b32_dpp v65, v64 quad_perm:[1,0,3,2] row_mask:0xf bank_mask:0xf
	v_perm_b32 v64, v65, v64, v250
	global_store_dword v196, v64, s[12:13]
	v_mul_f32_e32 v60, 0xbfb8aa3b, v60
	v_mul_f32_e32 v61, 0xbfb8aa3b, v61
	v_exp_f32_e32 v60, v60
	v_exp_f32_e32 v61, v61
	v_mul_f32_e32 v62, 0xbfb8aa3b, v62
	v_mul_f32_e32 v63, 0xbfb8aa3b, v63
	v_add_f32_e32 v60, 1.0, v60
	v_add_f32_e32 v61, 1.0, v61
	v_exp_f32_e32 v62, v62
	v_exp_f32_e32 v63, v63
	v_rcp_f32_e32 v60, v60
	v_rcp_f32_e32 v61, v61
	v_mul_f32_e32 v56, 0xbfb8aa3b, v56
	v_mul_f32_e32 v57, 0xbfb8aa3b, v57
	v_add_f32_e32 v62, 1.0, v62
	v_add_f32_e32 v63, 1.0, v63
	v_exp_f32_e32 v56, v56
	v_exp_f32_e32 v57, v57
	v_mov_b32_e32 v64, v129
	v_cndmask_b32_e64 v65, v60, v61, s[10:11]
	v_rcp_f32_e32 v62, v62
	v_rcp_f32_e32 v63, v63
	v_mov_b32_dpp v64, v65 quad_perm:[1,0,3,2] row_mask:0xf bank_mask:0xf
	v_cndmask_b32_e64 v60, v64, v60, s[10:11]
	v_mul_f32_e32 v58, 0xbfb8aa3b, v58
	v_mul_f32_e32 v59, 0xbfb8aa3b, v59
	v_cndmask_b32_e64 v61, v61, v64, s[10:11]
	v_cvt_pk_bf16_f32 v60, v60, v61
	v_add_f32_e32 v56, 1.0, v56
	v_add_f32_e32 v57, 1.0, v57
	v_exp_f32_e32 v58, v58
	v_exp_f32_e32 v59, v59
	global_store_dword v195, v60, s[12:13]
	v_cndmask_b32_e64 v60, v62, v63, s[10:11]
	v_mov_b32_e32 v61, v129
	v_rcp_f32_e32 v56, v56
	v_rcp_f32_e32 v57, v57
	v_mov_b32_dpp v61, v60 quad_perm:[1,0,3,2] row_mask:0xf bank_mask:0xf
	v_cndmask_b32_e64 v60, v61, v62, s[10:11]
	v_mul_f32_e32 v52, 0xbfb8aa3b, v52
	v_mul_f32_e32 v53, 0xbfb8aa3b, v53
	v_cndmask_b32_e64 v61, v63, v61, s[10:11]
	v_cvt_pk_bf16_f32 v60, v60, v61
	v_add_f32_e32 v58, 1.0, v58
	v_add_f32_e32 v59, 1.0, v59
	v_exp_f32_e32 v52, v52
	v_exp_f32_e32 v53, v53
	global_store_dword v194, v60, s[12:13]
	v_cndmask_b32_e64 v60, v56, v57, s[10:11]
	v_mov_b32_e32 v61, v129
	v_rcp_f32_e32 v58, v58
	v_rcp_f32_e32 v59, v59
	v_mov_b32_dpp v61, v60 quad_perm:[1,0,3,2] row_mask:0xf bank_mask:0xf
	v_cndmask_b32_e64 v56, v61, v56, s[10:11]
	v_mul_f32_e32 v54, 0xbfb8aa3b, v54
	v_mul_f32_e32 v55, 0xbfb8aa3b, v55
	v_cndmask_b32_e64 v57, v57, v61, s[10:11]
	v_cvt_pk_bf16_f32 v56, v56, v57
	v_add_f32_e32 v52, 1.0, v52
	v_add_f32_e32 v53, 1.0, v53
	v_exp_f32_e32 v54, v54
	v_exp_f32_e32 v55, v55
	global_store_dword v193, v56, s[12:13]
	v_cndmask_b32_e64 v56, v58, v59, s[10:11]
	v_mov_b32_e32 v57, v129
	v_rcp_f32_e32 v52, v52
	v_rcp_f32_e32 v53, v53
	v_mov_b32_dpp v57, v56 quad_perm:[1,0,3,2] row_mask:0xf bank_mask:0xf
	v_cndmask_b32_e64 v56, v57, v58, s[10:11]
	v_mul_f32_e32 v48, 0xbfb8aa3b, v48
	v_mul_f32_e32 v49, 0xbfb8aa3b, v49
	v_cndmask_b32_e64 v57, v59, v57, s[10:11]
	v_cvt_pk_bf16_f32 v56, v56, v57
	v_add_f32_e32 v54, 1.0, v54
	v_add_f32_e32 v55, 1.0, v55
	v_exp_f32_e32 v48, v48
	v_exp_f32_e32 v49, v49
	global_store_dword v192, v56, s[12:13]
	v_cndmask_b32_e64 v56, v52, v53, s[10:11]
	v_mov_b32_e32 v57, v129
	v_rcp_f32_e32 v54, v54
	v_rcp_f32_e32 v55, v55
	v_mov_b32_dpp v57, v56 quad_perm:[1,0,3,2] row_mask:0xf bank_mask:0xf
	v_cndmask_b32_e64 v52, v57, v52, s[10:11]
	v_mul_f32_e32 v50, 0xbfb8aa3b, v50
	v_mul_f32_e32 v51, 0xbfb8aa3b, v51
	v_cndmask_b32_e64 v53, v53, v57, s[10:11]
	v_cvt_pk_bf16_f32 v52, v52, v53
	v_add_f32_e32 v48, 1.0, v48
	v_add_f32_e32 v49, 1.0, v49
	v_exp_f32_e32 v50, v50
	v_exp_f32_e32 v51, v51
	global_store_dword v191, v52, s[12:13]
	v_cndmask_b32_e64 v52, v54, v55, s[10:11]
	v_mov_b32_e32 v53, v129
	v_rcp_f32_e32 v48, v48
	v_rcp_f32_e32 v49, v49
	v_mov_b32_dpp v53, v52 quad_perm:[1,0,3,2] row_mask:0xf bank_mask:0xf
	v_cndmask_b32_e64 v52, v53, v54, s[10:11]
	v_cndmask_b32_e64 v53, v55, v53, s[10:11]
	v_cvt_pk_bf16_f32 v52, v52, v53
	v_add_f32_e32 v50, 1.0, v50
	v_add_f32_e32 v51, 1.0, v51
	global_store_dword v190, v52, s[12:13]
	v_cndmask_b32_e64 v52, v48, v49, s[10:11]
	v_mov_b32_e32 v53, v129
	v_rcp_f32_e32 v50, v50
	v_rcp_f32_e32 v51, v51
	v_mov_b32_dpp v53, v52 quad_perm:[1,0,3,2] row_mask:0xf bank_mask:0xf
	v_cndmask_b32_e64 v48, v53, v48, s[10:11]
	v_cndmask_b32_e64 v49, v49, v53, s[10:11]
	v_cvt_pk_bf16_f32 v48, v48, v49
	global_store_dword v189, v48, s[12:13]
	v_cvt_pk_bf16_f32 v48, v50, v51
	s_nop 1
	v_mov_b32_dpp v49, v48 quad_perm:[1,0,3,2] row_mask:0xf bank_mask:0xf
	v_perm_b32 v48, v49, v48, v250
	global_store_dword v188, v48, s[12:13]
	v_mul_f32_e32 v44, 0xbfb8aa3b, v44
	v_mul_f32_e32 v45, 0xbfb8aa3b, v45
	v_exp_f32_e32 v44, v44
	v_exp_f32_e32 v45, v45
	v_mul_f32_e32 v46, 0xbfb8aa3b, v46
	v_mul_f32_e32 v47, 0xbfb8aa3b, v47
	v_add_f32_e32 v44, 1.0, v44
	v_add_f32_e32 v45, 1.0, v45
	v_exp_f32_e32 v46, v46
	v_exp_f32_e32 v47, v47
	v_rcp_f32_e32 v44, v44
	v_rcp_f32_e32 v45, v45
	v_mul_f32_e32 v40, 0xbfb8aa3b, v40
	v_mul_f32_e32 v41, 0xbfb8aa3b, v41
	v_add_f32_e32 v46, 1.0, v46
	v_add_f32_e32 v47, 1.0, v47
	v_exp_f32_e32 v40, v40
	v_exp_f32_e32 v41, v41
	v_mov_b32_e32 v48, v129
	v_cndmask_b32_e64 v49, v44, v45, s[10:11]
	v_rcp_f32_e32 v46, v46
	v_rcp_f32_e32 v47, v47
	v_mov_b32_dpp v48, v49 quad_perm:[1,0,3,2] row_mask:0xf bank_mask:0xf
	v_cndmask_b32_e64 v44, v48, v44, s[10:11]
	v_mul_f32_e32 v42, 0xbfb8aa3b, v42
	v_mul_f32_e32 v43, 0xbfb8aa3b, v43
	v_cndmask_b32_e64 v45, v45, v48, s[10:11]
	v_cvt_pk_bf16_f32 v44, v44, v45
	v_add_f32_e32 v40, 1.0, v40
	v_add_f32_e32 v41, 1.0, v41
	v_exp_f32_e32 v42, v42
	v_exp_f32_e32 v43, v43
	global_store_dword v187, v44, s[12:13]
	v_cndmask_b32_e64 v44, v46, v47, s[10:11]
	v_mov_b32_e32 v45, v129
	v_rcp_f32_e32 v40, v40
	v_rcp_f32_e32 v41, v41
	v_mov_b32_dpp v45, v44 quad_perm:[1,0,3,2] row_mask:0xf bank_mask:0xf
	v_cndmask_b32_e64 v44, v45, v46, s[10:11]
	v_mul_f32_e32 v36, 0xbfb8aa3b, v36
	v_mul_f32_e32 v37, 0xbfb8aa3b, v37
	v_cndmask_b32_e64 v45, v47, v45, s[10:11]
	v_cvt_pk_bf16_f32 v44, v44, v45
	v_add_f32_e32 v42, 1.0, v42
	v_add_f32_e32 v43, 1.0, v43
	v_exp_f32_e32 v36, v36
	v_exp_f32_e32 v37, v37
	global_store_dword v186, v44, s[12:13]
	v_cndmask_b32_e64 v44, v40, v41, s[10:11]
	v_mov_b32_e32 v45, v129
	v_rcp_f32_e32 v42, v42
	v_rcp_f32_e32 v43, v43
	v_mov_b32_dpp v45, v44 quad_perm:[1,0,3,2] row_mask:0xf bank_mask:0xf
	v_cndmask_b32_e64 v40, v45, v40, s[10:11]
	v_mul_f32_e32 v38, 0xbfb8aa3b, v38
	v_mul_f32_e32 v39, 0xbfb8aa3b, v39
	v_cndmask_b32_e64 v41, v41, v45, s[10:11]
	v_cvt_pk_bf16_f32 v40, v40, v41
	v_add_f32_e32 v36, 1.0, v36
	v_add_f32_e32 v37, 1.0, v37
	v_exp_f32_e32 v38, v38
	v_exp_f32_e32 v39, v39
	global_store_dword v185, v40, s[12:13]
	v_cndmask_b32_e64 v40, v42, v43, s[10:11]
	v_mov_b32_e32 v41, v129
	v_rcp_f32_e32 v36, v36
	v_rcp_f32_e32 v37, v37
	v_mov_b32_dpp v41, v40 quad_perm:[1,0,3,2] row_mask:0xf bank_mask:0xf
	v_cndmask_b32_e64 v40, v41, v42, s[10:11]
	v_mul_f32_e32 v32, 0xbfb8aa3b, v32
	v_mul_f32_e32 v33, 0xbfb8aa3b, v33
	v_cndmask_b32_e64 v41, v43, v41, s[10:11]
	v_cvt_pk_bf16_f32 v40, v40, v41
	v_add_f32_e32 v38, 1.0, v38
	v_add_f32_e32 v39, 1.0, v39
	v_exp_f32_e32 v32, v32
	v_exp_f32_e32 v33, v33
	global_store_dword v184, v40, s[12:13]
	v_cndmask_b32_e64 v40, v36, v37, s[10:11]
	v_mov_b32_e32 v41, v129
	v_rcp_f32_e32 v38, v38
	v_rcp_f32_e32 v39, v39
	v_mov_b32_dpp v41, v40 quad_perm:[1,0,3,2] row_mask:0xf bank_mask:0xf
	v_cndmask_b32_e64 v36, v41, v36, s[10:11]
	v_mul_f32_e32 v34, 0xbfb8aa3b, v34
	v_mul_f32_e32 v35, 0xbfb8aa3b, v35
	v_cndmask_b32_e64 v37, v37, v41, s[10:11]
	v_cvt_pk_bf16_f32 v36, v36, v37
	v_add_f32_e32 v32, 1.0, v32
	v_add_f32_e32 v33, 1.0, v33
	v_exp_f32_e32 v34, v34
	v_exp_f32_e32 v35, v35
	global_store_dword v183, v36, s[12:13]
	v_cndmask_b32_e64 v36, v38, v39, s[10:11]
	v_mov_b32_e32 v37, v129
	v_rcp_f32_e32 v32, v32
	v_rcp_f32_e32 v33, v33
	v_mov_b32_dpp v37, v36 quad_perm:[1,0,3,2] row_mask:0xf bank_mask:0xf
	v_cndmask_b32_e64 v36, v37, v38, s[10:11]
	v_cndmask_b32_e64 v37, v39, v37, s[10:11]
	v_cvt_pk_bf16_f32 v36, v36, v37
	v_add_f32_e32 v34, 1.0, v34
	v_add_f32_e32 v35, 1.0, v35
	global_store_dword v182, v36, s[12:13]
	v_cndmask_b32_e64 v36, v32, v33, s[10:11]
	v_mov_b32_e32 v37, v129
	v_rcp_f32_e32 v34, v34
	v_rcp_f32_e32 v35, v35
	v_mov_b32_dpp v37, v36 quad_perm:[1,0,3,2] row_mask:0xf bank_mask:0xf
	v_cndmask_b32_e64 v32, v37, v32, s[10:11]
	v_cndmask_b32_e64 v33, v33, v37, s[10:11]
	v_cvt_pk_bf16_f32 v32, v32, v33
	global_store_dword v181, v32, s[12:13]
	v_cvt_pk_bf16_f32 v32, v34, v35
	s_nop 1
	v_mov_b32_dpp v33, v32 quad_perm:[1,0,3,2] row_mask:0xf bank_mask:0xf
	v_perm_b32 v32, v33, v32, v250
	global_store_dword v180, v32, s[12:13]
	v_mul_f32_e32 v28, 0xbfb8aa3b, v28
	v_mul_f32_e32 v29, 0xbfb8aa3b, v29
	v_exp_f32_e32 v28, v28
	v_exp_f32_e32 v29, v29
	v_mul_f32_e32 v30, 0xbfb8aa3b, v30
	v_mul_f32_e32 v31, 0xbfb8aa3b, v31
	v_add_f32_e32 v28, 1.0, v28
	v_add_f32_e32 v29, 1.0, v29
	v_exp_f32_e32 v30, v30
	v_exp_f32_e32 v31, v31
	v_rcp_f32_e32 v28, v28
	v_rcp_f32_e32 v29, v29
	v_mul_f32_e32 v24, 0xbfb8aa3b, v24
	v_mul_f32_e32 v25, 0xbfb8aa3b, v25
	v_add_f32_e32 v30, 1.0, v30
	v_add_f32_e32 v31, 1.0, v31
	v_exp_f32_e32 v24, v24
	v_exp_f32_e32 v25, v25
	v_mov_b32_e32 v32, v129
	v_cndmask_b32_e64 v33, v28, v29, s[10:11]
	v_rcp_f32_e32 v30, v30
	v_rcp_f32_e32 v31, v31
	v_mov_b32_dpp v32, v33 quad_perm:[1,0,3,2] row_mask:0xf bank_mask:0xf
	v_cndmask_b32_e64 v28, v32, v28, s[10:11]
	v_mul_f32_e32 v26, 0xbfb8aa3b, v26
	v_mul_f32_e32 v27, 0xbfb8aa3b, v27
	v_cndmask_b32_e64 v29, v29, v32, s[10:11]
	v_cvt_pk_bf16_f32 v28, v28, v29
	v_add_f32_e32 v24, 1.0, v24
	v_add_f32_e32 v25, 1.0, v25
	v_exp_f32_e32 v26, v26
	v_exp_f32_e32 v27, v27
	global_store_dword v173, v28, s[12:13]
	v_cndmask_b32_e64 v28, v30, v31, s[10:11]
	v_mov_b32_e32 v29, v129
	v_rcp_f32_e32 v24, v24
	v_rcp_f32_e32 v25, v25
	v_mov_b32_dpp v29, v28 quad_perm:[1,0,3,2] row_mask:0xf bank_mask:0xf
	v_cndmask_b32_e64 v28, v29, v30, s[10:11]
	v_mul_f32_e32 v20, 0xbfb8aa3b, v20
	v_mul_f32_e32 v21, 0xbfb8aa3b, v21
	v_cndmask_b32_e64 v29, v31, v29, s[10:11]
	v_cvt_pk_bf16_f32 v28, v28, v29
	v_add_f32_e32 v26, 1.0, v26
	v_add_f32_e32 v27, 1.0, v27
	v_exp_f32_e32 v20, v20
	v_exp_f32_e32 v21, v21
	global_store_dword v172, v28, s[12:13]
	v_cndmask_b32_e64 v28, v24, v25, s[10:11]
	v_mov_b32_e32 v29, v129
	v_rcp_f32_e32 v26, v26
	v_rcp_f32_e32 v27, v27
	v_mov_b32_dpp v29, v28 quad_perm:[1,0,3,2] row_mask:0xf bank_mask:0xf
	v_cndmask_b32_e64 v24, v29, v24, s[10:11]
	v_mul_f32_e32 v22, 0xbfb8aa3b, v22
	v_mul_f32_e32 v23, 0xbfb8aa3b, v23
	v_cndmask_b32_e64 v25, v25, v29, s[10:11]
	v_cvt_pk_bf16_f32 v24, v24, v25
	v_add_f32_e32 v20, 1.0, v20
	v_add_f32_e32 v21, 1.0, v21
	v_exp_f32_e32 v22, v22
	v_exp_f32_e32 v23, v23
	global_store_dword v171, v24, s[12:13]
	v_cndmask_b32_e64 v24, v26, v27, s[10:11]
	v_mov_b32_e32 v25, v129
	v_rcp_f32_e32 v20, v20
	v_rcp_f32_e32 v21, v21
	v_mov_b32_dpp v25, v24 quad_perm:[1,0,3,2] row_mask:0xf bank_mask:0xf
	v_cndmask_b32_e64 v24, v25, v26, s[10:11]
	v_mul_f32_e32 v16, 0xbfb8aa3b, v16
	v_mul_f32_e32 v17, 0xbfb8aa3b, v17
	v_cndmask_b32_e64 v25, v27, v25, s[10:11]
	v_cvt_pk_bf16_f32 v24, v24, v25
	v_add_f32_e32 v22, 1.0, v22
	v_add_f32_e32 v23, 1.0, v23
	v_exp_f32_e32 v16, v16
	v_exp_f32_e32 v17, v17
	global_store_dword v170, v24, s[12:13]
	v_cndmask_b32_e64 v24, v20, v21, s[10:11]
	v_mov_b32_e32 v25, v129
	v_rcp_f32_e32 v22, v22
	v_rcp_f32_e32 v23, v23
	v_mov_b32_dpp v25, v24 quad_perm:[1,0,3,2] row_mask:0xf bank_mask:0xf
	v_cndmask_b32_e64 v20, v25, v20, s[10:11]
	v_mul_f32_e32 v18, 0xbfb8aa3b, v18
	v_mul_f32_e32 v19, 0xbfb8aa3b, v19
	v_cndmask_b32_e64 v21, v21, v25, s[10:11]
	v_cvt_pk_bf16_f32 v20, v20, v21
	v_add_f32_e32 v16, 1.0, v16
	v_add_f32_e32 v17, 1.0, v17
	v_exp_f32_e32 v18, v18
	v_exp_f32_e32 v19, v19
	global_store_dword v169, v20, s[12:13]
	v_cndmask_b32_e64 v20, v22, v23, s[10:11]
	v_mov_b32_e32 v21, v129
	v_rcp_f32_e32 v16, v16
	v_rcp_f32_e32 v17, v17
	v_mov_b32_dpp v21, v20 quad_perm:[1,0,3,2] row_mask:0xf bank_mask:0xf
	v_cndmask_b32_e64 v20, v21, v22, s[10:11]
	v_cndmask_b32_e64 v21, v23, v21, s[10:11]
	v_cvt_pk_bf16_f32 v20, v20, v21
	v_add_f32_e32 v18, 1.0, v18
	v_add_f32_e32 v19, 1.0, v19
	global_store_dword v168, v20, s[12:13]
	v_cndmask_b32_e64 v20, v16, v17, s[10:11]
	v_mov_b32_e32 v21, v129
	v_rcp_f32_e32 v18, v18
	v_rcp_f32_e32 v19, v19
	v_mov_b32_dpp v21, v20 quad_perm:[1,0,3,2] row_mask:0xf bank_mask:0xf
	v_cndmask_b32_e64 v16, v21, v16, s[10:11]
	v_cndmask_b32_e64 v17, v17, v21, s[10:11]
	v_cvt_pk_bf16_f32 v16, v16, v17
	global_store_dword v167, v16, s[12:13]
	v_cvt_pk_bf16_f32 v16, v18, v19
	s_nop 1
	v_mov_b32_dpp v17, v16 quad_perm:[1,0,3,2] row_mask:0xf bank_mask:0xf
	v_perm_b32 v16, v17, v16, v250
	global_store_dword v166, v16, s[12:13]
	v_mul_f32_e32 v12, 0xbfb8aa3b, v12
	v_mul_f32_e32 v13, 0xbfb8aa3b, v13
	v_exp_f32_e32 v12, v12
	v_exp_f32_e32 v13, v13
	v_mul_f32_e32 v14, 0xbfb8aa3b, v14
	v_mul_f32_e32 v15, 0xbfb8aa3b, v15
	v_add_f32_e32 v12, 1.0, v12
	v_add_f32_e32 v13, 1.0, v13
	v_exp_f32_e32 v14, v14
	v_exp_f32_e32 v15, v15
	v_rcp_f32_e32 v12, v12
	v_rcp_f32_e32 v13, v13
	v_mul_f32_e32 v8, 0xbfb8aa3b, v8
	v_mul_f32_e32 v9, 0xbfb8aa3b, v9
	v_add_f32_e32 v14, 1.0, v14
	v_add_f32_e32 v15, 1.0, v15
	v_exp_f32_e32 v8, v8
	v_exp_f32_e32 v9, v9
	v_mov_b32_e32 v16, v129
	v_cndmask_b32_e64 v17, v12, v13, s[10:11]
	v_rcp_f32_e32 v14, v14
	v_rcp_f32_e32 v15, v15
	v_mov_b32_dpp v16, v17 quad_perm:[1,0,3,2] row_mask:0xf bank_mask:0xf
	v_cndmask_b32_e64 v12, v16, v12, s[10:11]
	v_mul_f32_e32 v10, 0xbfb8aa3b, v10
	v_mul_f32_e32 v11, 0xbfb8aa3b, v11
	v_cndmask_b32_e64 v13, v13, v16, s[10:11]
	v_cvt_pk_bf16_f32 v12, v12, v13
	v_add_f32_e32 v8, 1.0, v8
	v_add_f32_e32 v9, 1.0, v9
	v_exp_f32_e32 v10, v10
	v_exp_f32_e32 v11, v11
	global_store_dword v165, v12, s[12:13]
	v_cndmask_b32_e64 v12, v14, v15, s[10:11]
	v_mov_b32_e32 v13, v129
	v_rcp_f32_e32 v8, v8
	v_rcp_f32_e32 v9, v9
	v_mov_b32_dpp v13, v12 quad_perm:[1,0,3,2] row_mask:0xf bank_mask:0xf
	v_cndmask_b32_e64 v12, v13, v14, s[10:11]
	v_mul_f32_e32 v4, 0xbfb8aa3b, v4
	v_mul_f32_e32 v5, 0xbfb8aa3b, v5
	v_cndmask_b32_e64 v13, v15, v13, s[10:11]
	v_cvt_pk_bf16_f32 v12, v12, v13
	v_add_f32_e32 v10, 1.0, v10
	v_add_f32_e32 v11, 1.0, v11
	v_exp_f32_e32 v4, v4
	v_exp_f32_e32 v5, v5
	global_store_dword v164, v12, s[12:13]
	v_cndmask_b32_e64 v12, v8, v9, s[10:11]
	v_mov_b32_e32 v13, v129
	v_rcp_f32_e32 v10, v10
	v_rcp_f32_e32 v11, v11
	v_mov_b32_dpp v13, v12 quad_perm:[1,0,3,2] row_mask:0xf bank_mask:0xf
	v_cndmask_b32_e64 v8, v13, v8, s[10:11]
	v_mul_f32_e32 v6, 0xbfb8aa3b, v6
	v_mul_f32_e32 v7, 0xbfb8aa3b, v7
	v_cndmask_b32_e64 v9, v9, v13, s[10:11]
	v_cvt_pk_bf16_f32 v8, v8, v9
	v_add_f32_e32 v4, 1.0, v4
	v_add_f32_e32 v5, 1.0, v5
	v_exp_f32_e32 v6, v6
	v_exp_f32_e32 v7, v7
	global_store_dword v163, v8, s[12:13]
	v_cndmask_b32_e64 v8, v10, v11, s[10:11]
	v_mov_b32_e32 v9, v129
	v_rcp_f32_e32 v4, v4
	v_rcp_f32_e32 v5, v5
	v_mov_b32_dpp v9, v8 quad_perm:[1,0,3,2] row_mask:0xf bank_mask:0xf
	v_cndmask_b32_e64 v8, v9, v10, s[10:11]
	v_mul_f32_e32 v0, 0xbfb8aa3b, v0
	v_mul_f32_e32 v1, 0xbfb8aa3b, v1
	v_cndmask_b32_e64 v9, v11, v9, s[10:11]
	v_cvt_pk_bf16_f32 v8, v8, v9
	v_add_f32_e32 v6, 1.0, v6
	v_add_f32_e32 v7, 1.0, v7
	v_exp_f32_e32 v0, v0
	v_exp_f32_e32 v1, v1
	global_store_dword v162, v8, s[12:13]
	v_cndmask_b32_e64 v8, v4, v5, s[10:11]
	v_mov_b32_e32 v9, v129
	v_rcp_f32_e32 v6, v6
	v_rcp_f32_e32 v7, v7
	v_mov_b32_dpp v9, v8 quad_perm:[1,0,3,2] row_mask:0xf bank_mask:0xf
	v_cndmask_b32_e64 v4, v9, v4, s[10:11]
	v_mul_f32_e32 v2, 0xbfb8aa3b, v2
	v_mul_f32_e32 v3, 0xbfb8aa3b, v3
	v_cndmask_b32_e64 v5, v5, v9, s[10:11]
	v_cvt_pk_bf16_f32 v4, v4, v5
	v_add_f32_e32 v0, 1.0, v0
	v_add_f32_e32 v1, 1.0, v1
	v_exp_f32_e32 v2, v2
	v_exp_f32_e32 v3, v3
	global_store_dword v161, v4, s[12:13]
	v_cndmask_b32_e64 v4, v6, v7, s[10:11]
	v_mov_b32_e32 v5, v129
	v_rcp_f32_e32 v0, v0
	v_rcp_f32_e32 v1, v1
	v_mov_b32_dpp v5, v4 quad_perm:[1,0,3,2] row_mask:0xf bank_mask:0xf
	v_cndmask_b32_e64 v4, v5, v6, s[10:11]
	v_cndmask_b32_e64 v5, v7, v5, s[10:11]
	v_cvt_pk_bf16_f32 v4, v4, v5
	v_add_f32_e32 v2, 1.0, v2
	v_add_f32_e32 v3, 1.0, v3
	global_store_dword v160, v4, s[12:13]
	v_cndmask_b32_e64 v4, v0, v1, s[10:11]
	v_mov_b32_e32 v5, v129
	v_rcp_f32_e32 v2, v2
	v_rcp_f32_e32 v3, v3
	v_mov_b32_dpp v5, v4 quad_perm:[1,0,3,2] row_mask:0xf bank_mask:0xf
	v_cndmask_b32_e64 v0, v5, v0, s[10:11]
	v_cndmask_b32_e64 v1, v1, v5, s[10:11]
	v_cvt_pk_bf16_f32 v0, v0, v1
	global_store_dword v159, v0, s[12:13]
	v_cvt_pk_bf16_f32 v0, v2, v3
	s_nop 1
	v_mov_b32_dpp v1, v0 quad_perm:[1,0,3,2] row_mask:0xf bank_mask:0xf
	v_perm_b32 v0, v1, v0, v250
	global_store_dword v158, v0, s[12:13]
	s_branch .LBB0_1556
